# alt_q3 + s_setprio removed around MFMA segments (both wave groups equal issue priority)
# speedup vs baseline: 1.0042x; 1.0042x over previous
; #define PG8_STAGE(bufoff, gbase, voff) do { _Pragma("unroll") for (int _i = 0; _i < 2; ++_i) \
;         __builtin_amdgcn_global_load_lds((const unsigned*)((const char*)(gbase) + (voff)[_i]), (PG8_LAS unsigned*)(lds + (bufoff) + ldsw + _i * 8192), 16, 0, 0); } while (0)
; #define PG8_LDA(dst, b, h) do { _Pragma("unroll") for (int m = 0; m < 4; ++m) _Pragma("unroll") for (int k = 0; k < 2; ++k) dst[m][k] = *(const PG8_LAS bf16x8*)(lds + PG8_SA(b, h) + aoff + m * 2048 + k * 1024); } while (0)
; #define PG8_LDB(dst, b, h) do { _Pragma("unroll") for (int n = 0; n < 2; ++n) _Pragma("unroll") for (int k = 0; k < 2; ++k) dst[n][k] = *(const PG8_LAS bf16x8*)(lds + PG8_SB(b, h) + boff + n * 2048 + k * 1024); } while (0)
; #define PG8_MMA(ai, bj, At, Bt) do { __builtin_amdgcn_s_setprio(1); _Pragma("unroll") for (int m = 0; m < 4; ++m) _Pragma("unroll") for (int n = 0; n < 2; ++n) _Pragma("unroll") for (int k = 0; k < 2; ++k) \
;         acc[ai][bj][m][n] = __builtin_amdgcn_mfma_f32_16x16x32_bf16(Bt[n][k], At[m][k], acc[ai][bj][m][n], 0, 0, 0); __builtin_amdgcn_s_setprio(0); } while (0)
; #define PG8_WAIT_V(n) asm volatile("s_waitcnt vmcnt(" #n ")" ::: "memory")
; #define PG8_WAIT_L(n) do { asm volatile("s_waitcnt lgkmcnt(" #n ")" ::: "memory"); __builtin_amdgcn_s_waitcnt(0xC07F); } while (0)
; #define PG8_BAR __builtin_amdgcn_s_barrier()
; #define PG8_SCHED __builtin_amdgcn_sched_barrier(0)
; template <class Epi, class Sched, bool SEG3 = false>
; __device__ __forceinline__ void gemm_phase(PG8_LAS unsigned char* lds, const Gemm g, const Sched& S, const Epi& E) {
;     ...
;             PG8_LDB(B0, 0, 0); PG8_LDB(B1, 0, 1); PG8_SCHED; PG8_LDA(At, 0, 0); PG8_STAGE(PG8_SA(1, 1), a1 + hsA, voffA);
;             PG8_WAIT_V(8); PG8_WAIT_L(0); PG8_BAR; if (cur.half != 1) { PG8_MMA(0, 0, At, B0); PG8_MMA(0, 1, At, B1); } PG8_BAR; PG8_SCHED;
;             PG8_LDA(At, 0, 1); PG8_STAGE(PG8_SB(0, 0), b2, voffB); PG8_STAGE(PG8_SB(0, 1), b2 + hsB, voffB); PG8_STAGE(PG8_SA(0, 0), a2, voffA);
;             PG8_WAIT_V(8); PG8_WAIT_L(0); PG8_BAR; if (cur.half != 0) { PG8_MMA(1, 0, At, B0); PG8_MMA(1, 1, At, B1); } PG8_BAR; PG8_SCHED;
.LBB0_225:
	v_add_u32_e32 v142, s54, v146
	ds_read_b128 v[152:155], v142
	ds_read_b128 v[156:159], v142 offset:1024
	ds_read_b128 v[160:163], v142 offset:2048
	ds_read_b128 v[164:167], v142 offset:3072
	v_add_u32_e32 v142, s55, v146
	ds_read_b128 v[168:171], v142
	ds_read_b128 v[172:175], v142 offset:1024
	ds_read_b128 v[176:179], v142 offset:2048
	ds_read_b128 v[180:183], v142 offset:3072
	s_add_i32 s95, s40, 2
	s_add_u32 s0, s38, 0xfffc0080
	s_addc_u32 s1, s39, -1
	s_cmp_eq_u32 s89, s40
	s_cselect_b32 s40, s92, s93
	s_cselect_b32 s43, s17, s1
	s_cselect_b32 s42, s29, s0
	s_cselect_b32 s41, s31, s94
	v_lshl_add_u64 v[142:143], s[38:39], 0, v[138:139]
	s_add_i32 m0, s78, 0xc000
	ds_read_b128 v[184:187], v151
	ds_read_b128 v[188:191], v151 offset:1024
	ds_read_b128 v[192:195], v151 offset:2048
	ds_read_b128 v[196:199], v151 offset:3072
	ds_read_b128 v[200:203], v151 offset:4096
	ds_read_b128 v[204:207], v151 offset:5120
	ds_read_b128 v[208:211], v151 offset:6144
	ds_read_b128 v[212:215], v151 offset:7168
	global_load_lds_dwordx4 v[142:143], off
	v_lshl_add_u64 v[142:143], s[38:39], 0, v[140:141]
	s_add_i32 m0, s78, 0xe000
	s_nop 0
	global_load_lds_dwordx4 v[142:143], off
	s_waitcnt vmcnt(8)
	s_waitcnt lgkmcnt(0)
	s_waitcnt lgkmcnt(0)
	s_barrier
	v_mfma_f32_16x16x32_bf16 v[126:129], v[152:155], v[184:187], v[126:129]
	v_mfma_f32_16x16x32_bf16 v[122:125], v[160:163], v[184:187], v[122:125]
	v_mfma_f32_16x16x32_bf16 v[110:113], v[152:155], v[192:195], v[110:113]
	v_mfma_f32_16x16x32_bf16 v[106:109], v[160:163], v[192:195], v[106:109]
	v_mfma_f32_16x16x32_bf16 v[94:97], v[152:155], v[200:203], v[94:97]
	v_mfma_f32_16x16x32_bf16 v[90:93], v[160:163], v[200:203], v[90:93]
	v_mfma_f32_16x16x32_bf16 v[78:81], v[152:155], v[208:211], v[78:81]
	v_mfma_f32_16x16x32_bf16 v[74:77], v[160:163], v[208:211], v[74:77]
	v_mfma_f32_16x16x32_bf16 v[126:129], v[156:159], v[188:191], v[126:129]
	v_mfma_f32_16x16x32_bf16 v[122:125], v[164:167], v[188:191], v[122:125]
	v_mfma_f32_16x16x32_bf16 v[110:113], v[156:159], v[196:199], v[110:113]
	v_mfma_f32_16x16x32_bf16 v[106:109], v[164:167], v[196:199], v[106:109]
	v_mfma_f32_16x16x32_bf16 v[94:97], v[156:159], v[204:207], v[94:97]
	v_mfma_f32_16x16x32_bf16 v[90:93], v[164:167], v[204:207], v[90:93]
	v_mfma_f32_16x16x32_bf16 v[78:81], v[156:159], v[212:215], v[78:81]
	v_mfma_f32_16x16x32_bf16 v[74:77], v[164:167], v[212:215], v[74:77]
	v_mfma_f32_16x16x32_bf16 v[118:121], v[168:171], v[184:187], v[118:121]
	v_mfma_f32_16x16x32_bf16 v[114:117], v[176:179], v[184:187], v[114:117]
	v_mfma_f32_16x16x32_bf16 v[102:105], v[168:171], v[192:195], v[102:105]
	v_mfma_f32_16x16x32_bf16 v[98:101], v[176:179], v[192:195], v[98:101]
	v_mfma_f32_16x16x32_bf16 v[86:89], v[168:171], v[200:203], v[86:89]
	v_mfma_f32_16x16x32_bf16 v[82:85], v[176:179], v[200:203], v[82:85]
	v_mfma_f32_16x16x32_bf16 v[70:73], v[168:171], v[208:211], v[70:73]
	v_mfma_f32_16x16x32_bf16 v[66:69], v[176:179], v[208:211], v[66:69]
	v_mfma_f32_16x16x32_bf16 v[118:121], v[172:175], v[188:191], v[118:121]
	v_mfma_f32_16x16x32_bf16 v[114:117], v[180:183], v[188:191], v[114:117]
	v_mfma_f32_16x16x32_bf16 v[102:105], v[172:175], v[196:199], v[102:105]
	v_mfma_f32_16x16x32_bf16 v[98:101], v[180:183], v[196:199], v[98:101]
	v_mfma_f32_16x16x32_bf16 v[86:89], v[172:175], v[204:207], v[86:89]
	v_mfma_f32_16x16x32_bf16 v[82:85], v[180:183], v[204:207], v[82:85]
	v_mfma_f32_16x16x32_bf16 v[70:73], v[172:175], v[212:215], v[70:73]
	v_mfma_f32_16x16x32_bf16 v[66:69], v[180:183], v[212:215], v[66:69]
	s_barrier
	s_mov_b32 m0, s19
	v_lshl_add_u64 v[142:143], s[40:41], 0, v[130:131]
	s_add_u32 s96, s40, 0x40000
	ds_read_b128 v[184:187], v151 offset:16384
	ds_read_b128 v[188:191], v151 offset:17408
	ds_read_b128 v[192:195], v151 offset:18432
	ds_read_b128 v[196:199], v151 offset:19456
	ds_read_b128 v[200:203], v151 offset:20480
	ds_read_b128 v[204:207], v151 offset:21504
	ds_read_b128 v[208:211], v151 offset:22528
	ds_read_b128 v[212:215], v151 offset:23552
	global_load_lds_dwordx4 v[142:143], off
	v_lshl_add_u64 v[216:217], s[40:41], 0, v[136:137]
	s_mov_b32 m0, s75
	s_addc_u32 s97, s41, 0
	global_load_lds_dwordx4 v[216:217], off
	v_lshl_add_u64 v[218:219], s[96:97], 0, v[130:131]
	s_mov_b32 m0, s76
	v_lshl_add_u64 v[220:221], s[42:43], 0, v[134:135]
	global_load_lds_dwordx4 v[218:219], off
	v_lshl_add_u64 v[218:219], s[96:97], 0, v[136:137]
	s_mov_b32 m0, s77
	s_nop 0
	global_load_lds_dwordx4 v[218:219], off
	v_lshl_add_u64 v[218:219], s[42:43], 0, v[132:133]
	s_mov_b32 m0, s78
	s_nop 0
	global_load_lds_dwordx4 v[218:219], off
	s_mov_b32 m0, s79
	s_nop 0
	global_load_lds_dwordx4 v[220:221], off
	s_waitcnt vmcnt(8)
	s_waitcnt lgkmcnt(0)
	s_waitcnt lgkmcnt(0)
	s_barrier
; #define PG8_STAGE(bufoff, gbase, voff) do { _Pragma("unroll") for (int _i = 0; _i < 2; ++_i) \
;         __builtin_amdgcn_global_load_lds((const unsigned*)((const char*)(gbase) + (voff)[_i]), (PG8_LAS unsigned*)(lds + (bufoff) + ldsw + _i * 8192), 16, 0, 0); } while (0)
; #define PG8_LDA(dst, b, h) do { _Pragma("unroll") for (int m = 0; m < 4; ++m) _Pragma("unroll") for (int k = 0; k < 2; ++k) dst[m][k] = *(const PG8_LAS bf16x8*)(lds + PG8_SA(b, h) + aoff + m * 2048 + k * 1024); } while (0)
; #define PG8_LDB(dst, b, h) do { _Pragma("unroll") for (int n = 0; n < 2; ++n) _Pragma("unroll") for (int k = 0; k < 2; ++k) dst[n][k] = *(const PG8_LAS bf16x8*)(lds + PG8_SB(b, h) + boff + n * 2048 + k * 1024); } while (0)
; #define PG8_MMA(ai, bj, At, Bt) do { __builtin_amdgcn_s_setprio(1); _Pragma("unroll") for (int m = 0; m < 4; ++m) _Pragma("unroll") for (int n = 0; n < 2; ++n) _Pragma("unroll") for (int k = 0; k < 2; ++k) \
;         acc[ai][bj][m][n] = __builtin_amdgcn_mfma_f32_16x16x32_bf16(Bt[n][k], At[m][k], acc[ai][bj][m][n], 0, 0, 0); __builtin_amdgcn_s_setprio(0); } while (0)
; #define PG8_WAIT_V(n) asm volatile("s_waitcnt vmcnt(" #n ")" ::: "memory")
; #define PG8_WAIT_L(n) do { asm volatile("s_waitcnt lgkmcnt(" #n ")" ::: "memory"); __builtin_amdgcn_s_waitcnt(0xC07F); } while (0)
; #define PG8_BAR __builtin_amdgcn_s_barrier()
; #define PG8_SCHED __builtin_amdgcn_sched_barrier(0)
; template <class Epi, class Sched, bool SEG3 = false>
; __device__ __forceinline__ void gemm_phase(PG8_LAS unsigned char* lds, const Gemm g, const Sched& S, const Epi& E) {
;     ...
;             PG8_WAIT_V(8); PG8_WAIT_L(0); PG8_BAR; if (cur.half != 0) { PG8_MMA(1, 0, At, B0); PG8_MMA(1, 1, At, B1); } PG8_BAR; PG8_SCHED;
;             PG8_LDB(B0, 1, 0); PG8_LDB(B1, 1, 1); PG8_SCHED; PG8_LDA(At, 1, 0); PG8_STAGE(PG8_SA(0, 1), a2 + hsA, voffA);
;             PG8_WAIT_V(8); PG8_WAIT_L(0); PG8_BAR; if (cur.half != 1) { PG8_MMA(0, 0, At, B0); PG8_MMA(0, 1, At, B1); } PG8_BAR; PG8_SCHED;
	v_mfma_f32_16x16x32_bf16 v[62:65], v[152:155], v[184:187], v[62:65]
	v_mfma_f32_16x16x32_bf16 v[58:61], v[160:163], v[184:187], v[58:61]
	v_mfma_f32_16x16x32_bf16 v[46:49], v[152:155], v[192:195], v[46:49]
	v_mfma_f32_16x16x32_bf16 v[42:45], v[160:163], v[192:195], v[42:45]
	v_mfma_f32_16x16x32_bf16 v[30:33], v[152:155], v[200:203], v[30:33]
	v_mfma_f32_16x16x32_bf16 v[26:29], v[160:163], v[200:203], v[26:29]
	v_mfma_f32_16x16x32_bf16 v[14:17], v[152:155], v[208:211], v[14:17]
	v_mfma_f32_16x16x32_bf16 v[10:13], v[160:163], v[208:211], v[10:13]
	v_mfma_f32_16x16x32_bf16 v[62:65], v[156:159], v[188:191], v[62:65]
	v_mfma_f32_16x16x32_bf16 v[58:61], v[164:167], v[188:191], v[58:61]
	v_mfma_f32_16x16x32_bf16 v[46:49], v[156:159], v[196:199], v[46:49]
	v_mfma_f32_16x16x32_bf16 v[42:45], v[164:167], v[196:199], v[42:45]
	v_mfma_f32_16x16x32_bf16 v[30:33], v[156:159], v[204:207], v[30:33]
	v_mfma_f32_16x16x32_bf16 v[26:29], v[164:167], v[204:207], v[26:29]
	v_mfma_f32_16x16x32_bf16 v[14:17], v[156:159], v[212:215], v[14:17]
	v_mfma_f32_16x16x32_bf16 v[10:13], v[164:167], v[212:215], v[10:13]
	v_mfma_f32_16x16x32_bf16 v[54:57], v[168:171], v[184:187], v[54:57]
	v_mfma_f32_16x16x32_bf16 v[50:53], v[176:179], v[184:187], v[50:53]
	v_mfma_f32_16x16x32_bf16 v[38:41], v[168:171], v[192:195], v[38:41]
	v_mfma_f32_16x16x32_bf16 v[34:37], v[176:179], v[192:195], v[34:37]
	v_mfma_f32_16x16x32_bf16 v[22:25], v[168:171], v[200:203], v[22:25]
	v_mfma_f32_16x16x32_bf16 v[18:21], v[176:179], v[200:203], v[18:21]
	v_mfma_f32_16x16x32_bf16 v[6:9], v[168:171], v[208:211], v[6:9]
	v_mfma_f32_16x16x32_bf16 v[2:5], v[176:179], v[208:211], v[2:5]
	v_mfma_f32_16x16x32_bf16 v[54:57], v[172:175], v[188:191], v[54:57]
	v_mfma_f32_16x16x32_bf16 v[50:53], v[180:183], v[188:191], v[50:53]
	v_mfma_f32_16x16x32_bf16 v[38:41], v[172:175], v[196:199], v[38:41]
	v_mfma_f32_16x16x32_bf16 v[34:37], v[180:183], v[196:199], v[34:37]
	v_mfma_f32_16x16x32_bf16 v[22:25], v[172:175], v[204:207], v[22:25]
	v_mfma_f32_16x16x32_bf16 v[18:21], v[180:183], v[204:207], v[18:21]
	v_mfma_f32_16x16x32_bf16 v[6:9], v[172:175], v[212:215], v[6:9]
	v_mfma_f32_16x16x32_bf16 v[2:5], v[180:183], v[212:215], v[2:5]
	s_barrier
	v_add_u32_e32 v164, s56, v146
	v_add_u32_e32 v180, s57, v146
	ds_read_b128 v[152:155], v164
	ds_read_b128 v[156:159], v164 offset:1024
	ds_read_b128 v[160:163], v164 offset:2048
	ds_read_b128 v[164:167], v164 offset:3072
	ds_read_b128 v[168:171], v180
	ds_read_b128 v[172:175], v180 offset:1024
	ds_read_b128 v[176:179], v180 offset:2048
	ds_read_b128 v[180:183], v180 offset:3072
	s_add_u32 s42, s42, 0x40000
	s_addc_u32 s43, s43, 0
	s_mov_b32 m0, s80
	v_lshl_add_u64 v[222:223], s[42:43], 0, v[132:133]
	ds_read_b128 v[184:187], v151 offset:32768
	ds_read_b128 v[188:191], v151 offset:33792
	ds_read_b128 v[192:195], v151 offset:34816
	ds_read_b128 v[196:199], v151 offset:35840
	ds_read_b128 v[200:203], v151 offset:36864
	ds_read_b128 v[204:207], v151 offset:37888
	ds_read_b128 v[208:211], v151 offset:38912
	ds_read_b128 v[212:215], v151 offset:39936
	global_load_lds_dwordx4 v[222:223], off
	v_lshl_add_u64 v[222:223], s[42:43], 0, v[134:135]
	s_mov_b32 m0, s81
	s_nop 0
	global_load_lds_dwordx4 v[222:223], off
	s_waitcnt vmcnt(8)
	s_waitcnt lgkmcnt(0)
	s_waitcnt lgkmcnt(0)
	s_barrier
	v_mfma_f32_16x16x32_bf16 v[126:129], v[152:155], v[184:187], v[126:129]
	v_mfma_f32_16x16x32_bf16 v[122:125], v[160:163], v[184:187], v[122:125]
	v_mfma_f32_16x16x32_bf16 v[110:113], v[152:155], v[192:195], v[110:113]
	v_mfma_f32_16x16x32_bf16 v[106:109], v[160:163], v[192:195], v[106:109]
	v_mfma_f32_16x16x32_bf16 v[94:97], v[152:155], v[200:203], v[94:97]
	v_mfma_f32_16x16x32_bf16 v[90:93], v[160:163], v[200:203], v[90:93]
	v_mfma_f32_16x16x32_bf16 v[78:81], v[152:155], v[208:211], v[78:81]
	v_mfma_f32_16x16x32_bf16 v[74:77], v[160:163], v[208:211], v[74:77]
	v_mfma_f32_16x16x32_bf16 v[126:129], v[156:159], v[188:191], v[126:129]
	v_mfma_f32_16x16x32_bf16 v[122:125], v[164:167], v[188:191], v[122:125]
	v_mfma_f32_16x16x32_bf16 v[110:113], v[156:159], v[196:199], v[110:113]
	v_mfma_f32_16x16x32_bf16 v[106:109], v[164:167], v[196:199], v[106:109]
	v_mfma_f32_16x16x32_bf16 v[94:97], v[156:159], v[204:207], v[94:97]
	v_mfma_f32_16x16x32_bf16 v[90:93], v[164:167], v[204:207], v[90:93]
	v_mfma_f32_16x16x32_bf16 v[78:81], v[156:159], v[212:215], v[78:81]
	v_mfma_f32_16x16x32_bf16 v[74:77], v[164:167], v[212:215], v[74:77]
	v_mfma_f32_16x16x32_bf16 v[118:121], v[168:171], v[184:187], v[118:121]
	v_mfma_f32_16x16x32_bf16 v[114:117], v[176:179], v[184:187], v[114:117]
	v_mfma_f32_16x16x32_bf16 v[102:105], v[168:171], v[192:195], v[102:105]
	v_mfma_f32_16x16x32_bf16 v[98:101], v[176:179], v[192:195], v[98:101]
	v_mfma_f32_16x16x32_bf16 v[86:89], v[168:171], v[200:203], v[86:89]
	v_mfma_f32_16x16x32_bf16 v[82:85], v[176:179], v[200:203], v[82:85]
	v_mfma_f32_16x16x32_bf16 v[70:73], v[168:171], v[208:211], v[70:73]
	v_mfma_f32_16x16x32_bf16 v[66:69], v[176:179], v[208:211], v[66:69]
	v_mfma_f32_16x16x32_bf16 v[118:121], v[172:175], v[188:191], v[118:121]
	v_mfma_f32_16x16x32_bf16 v[114:117], v[180:183], v[188:191], v[114:117]
	v_mfma_f32_16x16x32_bf16 v[102:105], v[172:175], v[196:199], v[102:105]
	v_mfma_f32_16x16x32_bf16 v[98:101], v[180:183], v[196:199], v[98:101]
	v_mfma_f32_16x16x32_bf16 v[86:89], v[172:175], v[204:207], v[86:89]
	v_mfma_f32_16x16x32_bf16 v[82:85], v[180:183], v[204:207], v[82:85]
	v_mfma_f32_16x16x32_bf16 v[70:73], v[172:175], v[212:215], v[70:73]
	v_mfma_f32_16x16x32_bf16 v[66:69], v[180:183], v[212:215], v[66:69]
	s_barrier
; #define PG8_STAGE(bufoff, gbase, voff) do { _Pragma("unroll") for (int _i = 0; _i < 2; ++_i) \
;         __builtin_amdgcn_global_load_lds((const unsigned*)((const char*)(gbase) + (voff)[_i]), (PG8_LAS unsigned*)(lds + (bufoff) + ldsw + _i * 8192), 16, 0, 0); } while (0)
; #define PG8_LDA(dst, b, h) do { _Pragma("unroll") for (int m = 0; m < 4; ++m) _Pragma("unroll") for (int k = 0; k < 2; ++k) dst[m][k] = *(const PG8_LAS bf16x8*)(lds + PG8_SA(b, h) + aoff + m * 2048 + k * 1024); } while (0)
; #define PG8_MMA(ai, bj, At, Bt) do { __builtin_amdgcn_s_setprio(1); _Pragma("unroll") for (int m = 0; m < 4; ++m) _Pragma("unroll") for (int n = 0; n < 2; ++n) _Pragma("unroll") for (int k = 0; k < 2; ++k) \
;         acc[ai][bj][m][n] = __builtin_amdgcn_mfma_f32_16x16x32_bf16(Bt[n][k], At[m][k], acc[ai][bj][m][n], 0, 0, 0); __builtin_amdgcn_s_setprio(0); } while (0)
; #define PG8_WAIT_V(n) asm volatile("s_waitcnt vmcnt(" #n ")" ::: "memory")
; #define PG8_WAIT_L(n) do { asm volatile("s_waitcnt lgkmcnt(" #n ")" ::: "memory"); __builtin_amdgcn_s_waitcnt(0xC07F); } while (0)
; #define PG8_BAR __builtin_amdgcn_s_barrier()
; #define PG8_SCHED __builtin_amdgcn_sched_barrier(0)
; template <class Epi, class Sched, bool SEG3 = false>
; __device__ __forceinline__ void gemm_phase(PG8_LAS unsigned char* lds, const Gemm g, const Sched& S, const Epi& E) {
;     ...
;             PG8_LDA(At, 1, 1); PG8_STAGE(PG8_SB(1, 0), b3, voffB); PG8_STAGE(PG8_SB(1, 1), b3 + hsB, voffB); PG8_STAGE(PG8_SA(1, 0), a3, voffA);
;             PG8_WAIT_V(8); PG8_WAIT_L(0); PG8_BAR; if (cur.half != 0) { PG8_MMA(1, 0, At, B0); PG8_MMA(1, 1, At, B1); } PG8_BAR; PG8_SCHED;
;         }
	s_mov_b32 m0, s83
	v_lshl_add_u64 v[142:143], v[142:143], 0, s[6:7]
	s_add_u32 s40, s40, 0x40080
	ds_read_b128 v[184:187], v151 offset:49152
	ds_read_b128 v[188:191], v151 offset:50176
	ds_read_b128 v[192:195], v151 offset:51200
	ds_read_b128 v[196:199], v151 offset:52224
	ds_read_b128 v[200:203], v151 offset:53248
	ds_read_b128 v[204:207], v151 offset:54272
	ds_read_b128 v[208:211], v151 offset:55296
	ds_read_b128 v[212:215], v151 offset:56320
	global_load_lds_dwordx4 v[142:143], off
	v_lshl_add_u64 v[142:143], v[216:217], 0, s[6:7]
	s_mov_b32 m0, s84
	s_addc_u32 s41, s41, 0
	global_load_lds_dwordx4 v[142:143], off
	v_lshl_add_u64 v[142:143], s[40:41], 0, v[130:131]
	s_mov_b32 m0, s87
	s_nop 0
	global_load_lds_dwordx4 v[142:143], off
	v_lshl_add_u64 v[142:143], s[40:41], 0, v[136:137]
	s_mov_b32 m0, s88
	s_nop 0
	global_load_lds_dwordx4 v[142:143], off
	v_lshl_add_u64 v[142:143], v[218:219], 0, s[6:7]
	s_mov_b32 m0, s85
	s_nop 0
	global_load_lds_dwordx4 v[142:143], off
	v_lshl_add_u64 v[142:143], v[220:221], 0, s[6:7]
	s_mov_b32 m0, s86
	s_nop 0
	global_load_lds_dwordx4 v[142:143], off
	s_waitcnt vmcnt(8)
	s_waitcnt lgkmcnt(0)
	s_waitcnt lgkmcnt(0)
	s_barrier
	v_mfma_f32_16x16x32_bf16 v[62:65], v[152:155], v[184:187], v[62:65]
	v_mfma_f32_16x16x32_bf16 v[58:61], v[160:163], v[184:187], v[58:61]
	v_mfma_f32_16x16x32_bf16 v[46:49], v[152:155], v[192:195], v[46:49]
	v_mfma_f32_16x16x32_bf16 v[42:45], v[160:163], v[192:195], v[42:45]
	v_mfma_f32_16x16x32_bf16 v[30:33], v[152:155], v[200:203], v[30:33]
	v_mfma_f32_16x16x32_bf16 v[26:29], v[160:163], v[200:203], v[26:29]
	v_mfma_f32_16x16x32_bf16 v[14:17], v[152:155], v[208:211], v[14:17]
	v_mfma_f32_16x16x32_bf16 v[10:13], v[160:163], v[208:211], v[10:13]
	v_mfma_f32_16x16x32_bf16 v[62:65], v[156:159], v[188:191], v[62:65]
	v_mfma_f32_16x16x32_bf16 v[58:61], v[164:167], v[188:191], v[58:61]
	v_mfma_f32_16x16x32_bf16 v[46:49], v[156:159], v[196:199], v[46:49]
	v_mfma_f32_16x16x32_bf16 v[42:45], v[164:167], v[196:199], v[42:45]
	v_mfma_f32_16x16x32_bf16 v[30:33], v[156:159], v[204:207], v[30:33]
	v_mfma_f32_16x16x32_bf16 v[26:29], v[164:167], v[204:207], v[26:29]
	v_mfma_f32_16x16x32_bf16 v[14:17], v[156:159], v[212:215], v[14:17]
	v_mfma_f32_16x16x32_bf16 v[10:13], v[164:167], v[212:215], v[10:13]
	v_mfma_f32_16x16x32_bf16 v[54:57], v[168:171], v[184:187], v[54:57]
	v_mfma_f32_16x16x32_bf16 v[50:53], v[176:179], v[184:187], v[50:53]
	v_mfma_f32_16x16x32_bf16 v[38:41], v[168:171], v[192:195], v[38:41]
	v_mfma_f32_16x16x32_bf16 v[34:37], v[176:179], v[192:195], v[34:37]
	v_mfma_f32_16x16x32_bf16 v[22:25], v[168:171], v[200:203], v[22:25]
	v_mfma_f32_16x16x32_bf16 v[18:21], v[176:179], v[200:203], v[18:21]
	v_mfma_f32_16x16x32_bf16 v[6:9], v[168:171], v[208:211], v[6:9]
	v_mfma_f32_16x16x32_bf16 v[2:5], v[176:179], v[208:211], v[2:5]
	v_mfma_f32_16x16x32_bf16 v[54:57], v[172:175], v[188:191], v[54:57]
	v_mfma_f32_16x16x32_bf16 v[50:53], v[180:183], v[188:191], v[50:53]
	v_mfma_f32_16x16x32_bf16 v[38:41], v[172:175], v[196:199], v[38:41]
	v_mfma_f32_16x16x32_bf16 v[34:37], v[180:183], v[196:199], v[34:37]
	v_mfma_f32_16x16x32_bf16 v[22:25], v[172:175], v[204:207], v[22:25]
	v_mfma_f32_16x16x32_bf16 v[18:21], v[180:183], v[204:207], v[18:21]
	v_mfma_f32_16x16x32_bf16 v[6:9], v[172:175], v[212:215], v[6:9]
	v_mfma_f32_16x16x32_bf16 v[2:5], v[180:183], v[212:215], v[2:5]
	s_barrier
	s_add_u32 s38, s38, 0x100
	s_addc_u32 s39, s39, 0
	s_add_u32 s93, s93, 0x100
	s_addc_u32 s94, s94, 0
	s_cmp_ge_i32 s95, s82
	s_mov_b32 s40, s95
	s_cbranch_scc0 .LBB0_225
	s_and_b64 vcc, exec, s[24:25]
	s_cbranch_vccz .LBB0_228

; #define PG8_STAGE(bufoff, gbase, voff) do { _Pragma("unroll") for (int _i = 0; _i < 2; ++_i) \
;         __builtin_amdgcn_global_load_lds((const unsigned*)((const char*)(gbase) + (voff)[_i]), (PG8_LAS unsigned*)(lds + (bufoff) + ldsw + _i * 8192), 16, 0, 0); } while (0)
; #define PG8_LDA(dst, b, h) do { _Pragma("unroll") for (int m = 0; m < 4; ++m) _Pragma("unroll") for (int k = 0; k < 2; ++k) dst[m][k] = *(const PG8_LAS bf16x8*)(lds + PG8_SA(b, h) + aoff + m * 2048 + k * 1024); } while (0)
; #define PG8_LDB(dst, b, h) do { _Pragma("unroll") for (int n = 0; n < 2; ++n) _Pragma("unroll") for (int k = 0; k < 2; ++k) dst[n][k] = *(const PG8_LAS bf16x8*)(lds + PG8_SB(b, h) + boff + n * 2048 + k * 1024); } while (0)
; #define PG8_MMA(ai, bj, At, Bt) do { __builtin_amdgcn_s_setprio(1); _Pragma("unroll") for (int m = 0; m < 4; ++m) _Pragma("unroll") for (int n = 0; n < 2; ++n) _Pragma("unroll") for (int k = 0; k < 2; ++k) \
;         acc[ai][bj][m][n] = __builtin_amdgcn_mfma_f32_16x16x32_bf16(Bt[n][k], At[m][k], acc[ai][bj][m][n], 0, 0, 0); __builtin_amdgcn_s_setprio(0); } while (0)
; #define PG8_WAIT_V(n) asm volatile("s_waitcnt vmcnt(" #n ")" ::: "memory")
; #define PG8_WAIT_L(n) do { asm volatile("s_waitcnt lgkmcnt(" #n ")" ::: "memory"); __builtin_amdgcn_s_waitcnt(0xC07F); } while (0)
; #define PG8_BAR __builtin_amdgcn_s_barrier()
; template <class Epi, class Sched, bool SEG3 = false>
; __device__ __forceinline__ void gemm_phase(PG8_LAS unsigned char* lds, const Gemm g, const Sched& S, const Epi& E) {
;     ...
;             const bool last = (t == ntc - 2);
;             const char* a1 = cA + (size_t)(t + 1) * kstep;
;             const char* a2 = last ? nA : cA + (size_t)(t + 2) * kstep; const char* b2 = last ? nB : cB + (size_t)(t + 2) * kstep;
;             const char* a3 = a2 + kstep; const char* b3 = b2 + kstep;
;             PG8_LDB(B0, 0, 0); PG8_LDB(B1, 0, 1); PG8_SCHED; PG8_LDA(At, 0, 0); PG8_STAGE(PG8_SA(1, 1), a1 + hsA, voffA);
;             PG8_WAIT_V(8); PG8_WAIT_L(0); PG8_BAR; if (cur.half != 1) { PG8_MMA(0, 0, At, B0); PG8_MMA(0, 1, At, B1); } PG8_BAR; PG8_SCHED;
;             PG8_LDA(At, 0, 1); PG8_STAGE(PG8_SB(0, 0), b2, voffB); PG8_STAGE(PG8_SB(0, 1), b2 + hsB, voffB); PG8_STAGE(PG8_SA(0, 0), a2, voffA);
;             PG8_WAIT_V(8); PG8_WAIT_L(0); PG8_BAR; if (cur.half != 0) { PG8_MMA(1, 0, At, B0); PG8_MMA(1, 1, At, B1); } PG8_BAR; PG8_SCHED;
.LBB0_269:
	v_add_u32_e32 v142, s54, v146
	ds_read_b128 v[152:155], v142
	ds_read_b128 v[156:159], v142 offset:1024
	ds_read_b128 v[160:163], v142 offset:2048
	ds_read_b128 v[164:167], v142 offset:3072
	v_add_u32_e32 v142, s55, v146
	ds_read_b128 v[168:171], v142
	ds_read_b128 v[172:175], v142 offset:1024
	ds_read_b128 v[176:179], v142 offset:2048
	ds_read_b128 v[180:183], v142 offset:3072
	s_add_i32 vcc_lo, s40, 2
	s_add_u32 s0, s38, 0xfffc0080
	s_addc_u32 s1, s39, -1
	s_cmp_eq_u32 s92, s40
	s_cselect_b32 s40, s95, s96
	s_cselect_b32 s43, s17, s1
	s_cselect_b32 s42, s29, s0
	s_cselect_b32 s41, s31, s97
	v_lshl_add_u64 v[142:143], s[38:39], 0, v[138:139]
	s_add_i32 m0, s82, 0xc000
	ds_read_b128 v[184:187], v151
	ds_read_b128 v[188:191], v151 offset:1024
	ds_read_b128 v[192:195], v151 offset:2048
	ds_read_b128 v[196:199], v151 offset:3072
	ds_read_b128 v[200:203], v151 offset:4096
	ds_read_b128 v[204:207], v151 offset:5120
	ds_read_b128 v[208:211], v151 offset:6144
	ds_read_b128 v[212:215], v151 offset:7168
	global_load_lds_dwordx4 v[142:143], off
	v_lshl_add_u64 v[142:143], s[38:39], 0, v[140:141]
	s_add_i32 m0, s82, 0xe000
	s_nop 0
	global_load_lds_dwordx4 v[142:143], off
	s_waitcnt vmcnt(8)
	s_waitcnt lgkmcnt(0)
	s_waitcnt lgkmcnt(0)
	s_barrier
	v_mfma_f32_16x16x32_bf16 v[126:129], v[152:155], v[184:187], v[126:129]
	v_mfma_f32_16x16x32_bf16 v[122:125], v[160:163], v[184:187], v[122:125]
	v_mfma_f32_16x16x32_bf16 v[110:113], v[152:155], v[192:195], v[110:113]
	v_mfma_f32_16x16x32_bf16 v[106:109], v[160:163], v[192:195], v[106:109]
	v_mfma_f32_16x16x32_bf16 v[94:97], v[152:155], v[200:203], v[94:97]
	v_mfma_f32_16x16x32_bf16 v[90:93], v[160:163], v[200:203], v[90:93]
	v_mfma_f32_16x16x32_bf16 v[78:81], v[152:155], v[208:211], v[78:81]
	v_mfma_f32_16x16x32_bf16 v[74:77], v[160:163], v[208:211], v[74:77]
	v_mfma_f32_16x16x32_bf16 v[126:129], v[156:159], v[188:191], v[126:129]
	v_mfma_f32_16x16x32_bf16 v[122:125], v[164:167], v[188:191], v[122:125]
	v_mfma_f32_16x16x32_bf16 v[110:113], v[156:159], v[196:199], v[110:113]
	v_mfma_f32_16x16x32_bf16 v[106:109], v[164:167], v[196:199], v[106:109]
	v_mfma_f32_16x16x32_bf16 v[94:97], v[156:159], v[204:207], v[94:97]
	v_mfma_f32_16x16x32_bf16 v[90:93], v[164:167], v[204:207], v[90:93]
	v_mfma_f32_16x16x32_bf16 v[78:81], v[156:159], v[212:215], v[78:81]
	v_mfma_f32_16x16x32_bf16 v[74:77], v[164:167], v[212:215], v[74:77]
	v_mfma_f32_16x16x32_bf16 v[118:121], v[168:171], v[184:187], v[118:121]
	v_mfma_f32_16x16x32_bf16 v[114:117], v[176:179], v[184:187], v[114:117]
	v_mfma_f32_16x16x32_bf16 v[102:105], v[168:171], v[192:195], v[102:105]
	v_mfma_f32_16x16x32_bf16 v[98:101], v[176:179], v[192:195], v[98:101]
	v_mfma_f32_16x16x32_bf16 v[86:89], v[168:171], v[200:203], v[86:89]
	v_mfma_f32_16x16x32_bf16 v[82:85], v[176:179], v[200:203], v[82:85]
	v_mfma_f32_16x16x32_bf16 v[70:73], v[168:171], v[208:211], v[70:73]
	v_mfma_f32_16x16x32_bf16 v[66:69], v[176:179], v[208:211], v[66:69]
	v_mfma_f32_16x16x32_bf16 v[118:121], v[172:175], v[188:191], v[118:121]
	v_mfma_f32_16x16x32_bf16 v[114:117], v[180:183], v[188:191], v[114:117]
	v_mfma_f32_16x16x32_bf16 v[102:105], v[172:175], v[196:199], v[102:105]
	v_mfma_f32_16x16x32_bf16 v[98:101], v[180:183], v[196:199], v[98:101]
	v_mfma_f32_16x16x32_bf16 v[86:89], v[172:175], v[204:207], v[86:89]
	v_mfma_f32_16x16x32_bf16 v[82:85], v[180:183], v[204:207], v[82:85]
	v_mfma_f32_16x16x32_bf16 v[70:73], v[172:175], v[212:215], v[70:73]
	v_mfma_f32_16x16x32_bf16 v[66:69], v[180:183], v[212:215], v[66:69]
	s_barrier
	s_mov_b32 m0, s19
	v_lshl_add_u64 v[142:143], s[40:41], 0, v[130:131]
	s_add_u32 s0, s40, 0x40000
	ds_read_b128 v[184:187], v151 offset:16384
	ds_read_b128 v[188:191], v151 offset:17408
	ds_read_b128 v[192:195], v151 offset:18432
	ds_read_b128 v[196:199], v151 offset:19456
	ds_read_b128 v[200:203], v151 offset:20480
	ds_read_b128 v[204:207], v151 offset:21504
	ds_read_b128 v[208:211], v151 offset:22528
	ds_read_b128 v[212:215], v151 offset:23552
	global_load_lds_dwordx4 v[142:143], off
	v_lshl_add_u64 v[216:217], s[40:41], 0, v[136:137]
	s_mov_b32 m0, s79
	s_addc_u32 s1, s41, 0
	global_load_lds_dwordx4 v[216:217], off
	v_lshl_add_u64 v[218:219], s[0:1], 0, v[130:131]
	s_mov_b32 m0, s80
	v_lshl_add_u64 v[220:221], s[42:43], 0, v[134:135]
	global_load_lds_dwordx4 v[218:219], off
	v_lshl_add_u64 v[218:219], s[0:1], 0, v[136:137]
	s_mov_b32 m0, s81
	s_nop 0
	global_load_lds_dwordx4 v[218:219], off
	v_lshl_add_u64 v[218:219], s[42:43], 0, v[132:133]
	s_mov_b32 m0, s82
	s_nop 0
	global_load_lds_dwordx4 v[218:219], off
	s_mov_b32 m0, s83
	s_nop 0
	global_load_lds_dwordx4 v[220:221], off
	s_waitcnt vmcnt(8)
	s_waitcnt lgkmcnt(0)
	s_waitcnt lgkmcnt(0)
	s_barrier
; #define PG8_STAGE(bufoff, gbase, voff) do { _Pragma("unroll") for (int _i = 0; _i < 2; ++_i) \
;         __builtin_amdgcn_global_load_lds((const unsigned*)((const char*)(gbase) + (voff)[_i]), (PG8_LAS unsigned*)(lds + (bufoff) + ldsw + _i * 8192), 16, 0, 0); } while (0)
; #define PG8_LDA(dst, b, h) do { _Pragma("unroll") for (int m = 0; m < 4; ++m) _Pragma("unroll") for (int k = 0; k < 2; ++k) dst[m][k] = *(const PG8_LAS bf16x8*)(lds + PG8_SA(b, h) + aoff + m * 2048 + k * 1024); } while (0)
; #define PG8_LDB(dst, b, h) do { _Pragma("unroll") for (int n = 0; n < 2; ++n) _Pragma("unroll") for (int k = 0; k < 2; ++k) dst[n][k] = *(const PG8_LAS bf16x8*)(lds + PG8_SB(b, h) + boff + n * 2048 + k * 1024); } while (0)
; #define PG8_MMA(ai, bj, At, Bt) do { __builtin_amdgcn_s_setprio(1); _Pragma("unroll") for (int m = 0; m < 4; ++m) _Pragma("unroll") for (int n = 0; n < 2; ++n) _Pragma("unroll") for (int k = 0; k < 2; ++k) \
;         acc[ai][bj][m][n] = __builtin_amdgcn_mfma_f32_16x16x32_bf16(Bt[n][k], At[m][k], acc[ai][bj][m][n], 0, 0, 0); __builtin_amdgcn_s_setprio(0); } while (0)
; #define PG8_WAIT_V(n) asm volatile("s_waitcnt vmcnt(" #n ")" ::: "memory")
; #define PG8_WAIT_L(n) do { asm volatile("s_waitcnt lgkmcnt(" #n ")" ::: "memory"); __builtin_amdgcn_s_waitcnt(0xC07F); } while (0)
; #define PG8_BAR __builtin_amdgcn_s_barrier()
; #define PG8_SCHED __builtin_amdgcn_sched_barrier(0)
; template <class Epi, class Sched, bool SEG3 = false>
; __device__ __forceinline__ void gemm_phase(PG8_LAS unsigned char* lds, const Gemm g, const Sched& S, const Epi& E) {
;     ...
;             PG8_WAIT_V(8); PG8_WAIT_L(0); PG8_BAR; if (cur.half != 0) { PG8_MMA(1, 0, At, B0); PG8_MMA(1, 1, At, B1); } PG8_BAR; PG8_SCHED;
;             PG8_LDB(B0, 1, 0); PG8_LDB(B1, 1, 1); PG8_SCHED; PG8_LDA(At, 1, 0); PG8_STAGE(PG8_SA(0, 1), a2 + hsA, voffA);
;             PG8_WAIT_V(8); PG8_WAIT_L(0); PG8_BAR; if (cur.half != 1) { PG8_MMA(0, 0, At, B0); PG8_MMA(0, 1, At, B1); } PG8_BAR; PG8_SCHED;
	v_mfma_f32_16x16x32_bf16 v[62:65], v[152:155], v[184:187], v[62:65]
	v_mfma_f32_16x16x32_bf16 v[58:61], v[160:163], v[184:187], v[58:61]
	v_mfma_f32_16x16x32_bf16 v[46:49], v[152:155], v[192:195], v[46:49]
	v_mfma_f32_16x16x32_bf16 v[42:45], v[160:163], v[192:195], v[42:45]
	v_mfma_f32_16x16x32_bf16 v[30:33], v[152:155], v[200:203], v[30:33]
	v_mfma_f32_16x16x32_bf16 v[26:29], v[160:163], v[200:203], v[26:29]
	v_mfma_f32_16x16x32_bf16 v[14:17], v[152:155], v[208:211], v[14:17]
	v_mfma_f32_16x16x32_bf16 v[10:13], v[160:163], v[208:211], v[10:13]
	v_mfma_f32_16x16x32_bf16 v[62:65], v[156:159], v[188:191], v[62:65]
	v_mfma_f32_16x16x32_bf16 v[58:61], v[164:167], v[188:191], v[58:61]
	v_mfma_f32_16x16x32_bf16 v[46:49], v[156:159], v[196:199], v[46:49]
	v_mfma_f32_16x16x32_bf16 v[42:45], v[164:167], v[196:199], v[42:45]
	v_mfma_f32_16x16x32_bf16 v[30:33], v[156:159], v[204:207], v[30:33]
	v_mfma_f32_16x16x32_bf16 v[26:29], v[164:167], v[204:207], v[26:29]
	v_mfma_f32_16x16x32_bf16 v[14:17], v[156:159], v[212:215], v[14:17]
	v_mfma_f32_16x16x32_bf16 v[10:13], v[164:167], v[212:215], v[10:13]
	v_mfma_f32_16x16x32_bf16 v[54:57], v[168:171], v[184:187], v[54:57]
	v_mfma_f32_16x16x32_bf16 v[50:53], v[176:179], v[184:187], v[50:53]
	v_mfma_f32_16x16x32_bf16 v[38:41], v[168:171], v[192:195], v[38:41]
	v_mfma_f32_16x16x32_bf16 v[34:37], v[176:179], v[192:195], v[34:37]
	v_mfma_f32_16x16x32_bf16 v[22:25], v[168:171], v[200:203], v[22:25]
	v_mfma_f32_16x16x32_bf16 v[18:21], v[176:179], v[200:203], v[18:21]
	v_mfma_f32_16x16x32_bf16 v[6:9], v[168:171], v[208:211], v[6:9]
	v_mfma_f32_16x16x32_bf16 v[2:5], v[176:179], v[208:211], v[2:5]
	v_mfma_f32_16x16x32_bf16 v[54:57], v[172:175], v[188:191], v[54:57]
	v_mfma_f32_16x16x32_bf16 v[50:53], v[180:183], v[188:191], v[50:53]
	v_mfma_f32_16x16x32_bf16 v[38:41], v[172:175], v[196:199], v[38:41]
	v_mfma_f32_16x16x32_bf16 v[34:37], v[180:183], v[196:199], v[34:37]
	v_mfma_f32_16x16x32_bf16 v[22:25], v[172:175], v[204:207], v[22:25]
	v_mfma_f32_16x16x32_bf16 v[18:21], v[180:183], v[204:207], v[18:21]
	v_mfma_f32_16x16x32_bf16 v[6:9], v[172:175], v[212:215], v[6:9]
	v_mfma_f32_16x16x32_bf16 v[2:5], v[180:183], v[212:215], v[2:5]
	s_barrier
	v_add_u32_e32 v164, s56, v146
	v_add_u32_e32 v180, s57, v146
	ds_read_b128 v[152:155], v164
	ds_read_b128 v[156:159], v164 offset:1024
	ds_read_b128 v[160:163], v164 offset:2048
	ds_read_b128 v[164:167], v164 offset:3072
	ds_read_b128 v[168:171], v180
	ds_read_b128 v[172:175], v180 offset:1024
	ds_read_b128 v[176:179], v180 offset:2048
	ds_read_b128 v[180:183], v180 offset:3072
	s_add_u32 s0, s42, 0x40000
	s_addc_u32 s1, s43, 0
	s_mov_b32 m0, s84
	v_lshl_add_u64 v[222:223], s[0:1], 0, v[132:133]
	ds_read_b128 v[184:187], v151 offset:32768
	ds_read_b128 v[188:191], v151 offset:33792
	ds_read_b128 v[192:195], v151 offset:34816
	ds_read_b128 v[196:199], v151 offset:35840
	ds_read_b128 v[200:203], v151 offset:36864
	ds_read_b128 v[204:207], v151 offset:37888
	ds_read_b128 v[208:211], v151 offset:38912
	ds_read_b128 v[212:215], v151 offset:39936
	global_load_lds_dwordx4 v[222:223], off
	v_lshl_add_u64 v[222:223], s[0:1], 0, v[134:135]
	s_mov_b32 m0, s85
	s_nop 0
	global_load_lds_dwordx4 v[222:223], off
	s_waitcnt vmcnt(8)
	s_waitcnt lgkmcnt(0)
	s_waitcnt lgkmcnt(0)
	s_barrier
	v_mfma_f32_16x16x32_bf16 v[126:129], v[152:155], v[184:187], v[126:129]
	v_mfma_f32_16x16x32_bf16 v[122:125], v[160:163], v[184:187], v[122:125]
	v_mfma_f32_16x16x32_bf16 v[110:113], v[152:155], v[192:195], v[110:113]
	v_mfma_f32_16x16x32_bf16 v[106:109], v[160:163], v[192:195], v[106:109]
	v_mfma_f32_16x16x32_bf16 v[94:97], v[152:155], v[200:203], v[94:97]
	v_mfma_f32_16x16x32_bf16 v[90:93], v[160:163], v[200:203], v[90:93]
	v_mfma_f32_16x16x32_bf16 v[78:81], v[152:155], v[208:211], v[78:81]
	v_mfma_f32_16x16x32_bf16 v[74:77], v[160:163], v[208:211], v[74:77]
	v_mfma_f32_16x16x32_bf16 v[126:129], v[156:159], v[188:191], v[126:129]
	v_mfma_f32_16x16x32_bf16 v[122:125], v[164:167], v[188:191], v[122:125]
	v_mfma_f32_16x16x32_bf16 v[110:113], v[156:159], v[196:199], v[110:113]
	v_mfma_f32_16x16x32_bf16 v[106:109], v[164:167], v[196:199], v[106:109]
	v_mfma_f32_16x16x32_bf16 v[94:97], v[156:159], v[204:207], v[94:97]
	v_mfma_f32_16x16x32_bf16 v[90:93], v[164:167], v[204:207], v[90:93]
	v_mfma_f32_16x16x32_bf16 v[78:81], v[156:159], v[212:215], v[78:81]
	v_mfma_f32_16x16x32_bf16 v[74:77], v[164:167], v[212:215], v[74:77]
	v_mfma_f32_16x16x32_bf16 v[118:121], v[168:171], v[184:187], v[118:121]
	v_mfma_f32_16x16x32_bf16 v[114:117], v[176:179], v[184:187], v[114:117]
	v_mfma_f32_16x16x32_bf16 v[102:105], v[168:171], v[192:195], v[102:105]
	v_mfma_f32_16x16x32_bf16 v[98:101], v[176:179], v[192:195], v[98:101]
	v_mfma_f32_16x16x32_bf16 v[86:89], v[168:171], v[200:203], v[86:89]
	v_mfma_f32_16x16x32_bf16 v[82:85], v[176:179], v[200:203], v[82:85]
	v_mfma_f32_16x16x32_bf16 v[70:73], v[168:171], v[208:211], v[70:73]
	v_mfma_f32_16x16x32_bf16 v[66:69], v[176:179], v[208:211], v[66:69]
	v_mfma_f32_16x16x32_bf16 v[118:121], v[172:175], v[188:191], v[118:121]
	v_mfma_f32_16x16x32_bf16 v[114:117], v[180:183], v[188:191], v[114:117]
	v_mfma_f32_16x16x32_bf16 v[102:105], v[172:175], v[196:199], v[102:105]
	v_mfma_f32_16x16x32_bf16 v[98:101], v[180:183], v[196:199], v[98:101]
	v_mfma_f32_16x16x32_bf16 v[86:89], v[172:175], v[204:207], v[86:89]
	v_mfma_f32_16x16x32_bf16 v[82:85], v[180:183], v[204:207], v[82:85]
	v_mfma_f32_16x16x32_bf16 v[70:73], v[172:175], v[212:215], v[70:73]
	v_mfma_f32_16x16x32_bf16 v[66:69], v[180:183], v[212:215], v[66:69]
	s_barrier
; #define PG8_STAGE(bufoff, gbase, voff) do { _Pragma("unroll") for (int _i = 0; _i < 2; ++_i) \
;         __builtin_amdgcn_global_load_lds((const unsigned*)((const char*)(gbase) + (voff)[_i]), (PG8_LAS unsigned*)(lds + (bufoff) + ldsw + _i * 8192), 16, 0, 0); } while (0)
; #define PG8_LDA(dst, b, h) do { _Pragma("unroll") for (int m = 0; m < 4; ++m) _Pragma("unroll") for (int k = 0; k < 2; ++k) dst[m][k] = *(const PG8_LAS bf16x8*)(lds + PG8_SA(b, h) + aoff + m * 2048 + k * 1024); } while (0)
; #define PG8_MMA(ai, bj, At, Bt) do { __builtin_amdgcn_s_setprio(1); _Pragma("unroll") for (int m = 0; m < 4; ++m) _Pragma("unroll") for (int n = 0; n < 2; ++n) _Pragma("unroll") for (int k = 0; k < 2; ++k) \
;         acc[ai][bj][m][n] = __builtin_amdgcn_mfma_f32_16x16x32_bf16(Bt[n][k], At[m][k], acc[ai][bj][m][n], 0, 0, 0); __builtin_amdgcn_s_setprio(0); } while (0)
; #define PG8_WAIT_V(n) asm volatile("s_waitcnt vmcnt(" #n ")" ::: "memory")
; #define PG8_WAIT_L(n) do { asm volatile("s_waitcnt lgkmcnt(" #n ")" ::: "memory"); __builtin_amdgcn_s_waitcnt(0xC07F); } while (0)
; #define PG8_BAR __builtin_amdgcn_s_barrier()
; #define PG8_SCHED __builtin_amdgcn_sched_barrier(0)
; template <class Epi, class Sched, bool SEG3 = false>
; __device__ __forceinline__ void gemm_phase(PG8_LAS unsigned char* lds, const Gemm g, const Sched& S, const Epi& E) {
;     ...
;             PG8_LDA(At, 1, 1); PG8_STAGE(PG8_SB(1, 0), b3, voffB); PG8_STAGE(PG8_SB(1, 1), b3 + hsB, voffB); PG8_STAGE(PG8_SA(1, 0), a3, voffA);
;             PG8_WAIT_V(8); PG8_WAIT_L(0); PG8_BAR; if (cur.half != 0) { PG8_MMA(1, 0, At, B0); PG8_MMA(1, 1, At, B1); } PG8_BAR; PG8_SCHED;
;         }
	s_mov_b32 m0, s86
	v_lshl_add_u64 v[142:143], v[142:143], 0, s[6:7]
	s_add_u32 s0, s40, 0x40080
	ds_read_b128 v[184:187], v151 offset:49152
	ds_read_b128 v[188:191], v151 offset:50176
	ds_read_b128 v[192:195], v151 offset:51200
	ds_read_b128 v[196:199], v151 offset:52224
	ds_read_b128 v[200:203], v151 offset:53248
	ds_read_b128 v[204:207], v151 offset:54272
	ds_read_b128 v[208:211], v151 offset:55296
	ds_read_b128 v[212:215], v151 offset:56320
	global_load_lds_dwordx4 v[142:143], off
	v_lshl_add_u64 v[142:143], v[216:217], 0, s[6:7]
	s_mov_b32 m0, s87
	s_addc_u32 s1, s41, 0
	global_load_lds_dwordx4 v[142:143], off
	v_lshl_add_u64 v[142:143], s[0:1], 0, v[130:131]
	s_mov_b32 m0, s90
	s_nop 0
	global_load_lds_dwordx4 v[142:143], off
	v_lshl_add_u64 v[142:143], s[0:1], 0, v[136:137]
	s_mov_b32 m0, s91
	s_nop 0
	global_load_lds_dwordx4 v[142:143], off
	v_lshl_add_u64 v[142:143], v[218:219], 0, s[6:7]
	s_mov_b32 m0, s88
	s_nop 0
	global_load_lds_dwordx4 v[142:143], off
	v_lshl_add_u64 v[142:143], v[220:221], 0, s[6:7]
	s_mov_b32 m0, s89
	s_nop 0
	global_load_lds_dwordx4 v[142:143], off
	s_waitcnt vmcnt(8)
	s_waitcnt lgkmcnt(0)
	s_waitcnt lgkmcnt(0)
	s_barrier
	v_mfma_f32_16x16x32_bf16 v[62:65], v[152:155], v[184:187], v[62:65]
	v_mfma_f32_16x16x32_bf16 v[58:61], v[160:163], v[184:187], v[58:61]
	v_mfma_f32_16x16x32_bf16 v[46:49], v[152:155], v[192:195], v[46:49]
	v_mfma_f32_16x16x32_bf16 v[42:45], v[160:163], v[192:195], v[42:45]
	v_mfma_f32_16x16x32_bf16 v[30:33], v[152:155], v[200:203], v[30:33]
	v_mfma_f32_16x16x32_bf16 v[26:29], v[160:163], v[200:203], v[26:29]
	v_mfma_f32_16x16x32_bf16 v[14:17], v[152:155], v[208:211], v[14:17]
	v_mfma_f32_16x16x32_bf16 v[10:13], v[160:163], v[208:211], v[10:13]
	v_mfma_f32_16x16x32_bf16 v[62:65], v[156:159], v[188:191], v[62:65]
	v_mfma_f32_16x16x32_bf16 v[58:61], v[164:167], v[188:191], v[58:61]
	v_mfma_f32_16x16x32_bf16 v[46:49], v[156:159], v[196:199], v[46:49]
	v_mfma_f32_16x16x32_bf16 v[42:45], v[164:167], v[196:199], v[42:45]
	v_mfma_f32_16x16x32_bf16 v[30:33], v[156:159], v[204:207], v[30:33]
	v_mfma_f32_16x16x32_bf16 v[26:29], v[164:167], v[204:207], v[26:29]
	v_mfma_f32_16x16x32_bf16 v[14:17], v[156:159], v[212:215], v[14:17]
	v_mfma_f32_16x16x32_bf16 v[10:13], v[164:167], v[212:215], v[10:13]
	v_mfma_f32_16x16x32_bf16 v[54:57], v[168:171], v[184:187], v[54:57]
	v_mfma_f32_16x16x32_bf16 v[50:53], v[176:179], v[184:187], v[50:53]
	v_mfma_f32_16x16x32_bf16 v[38:41], v[168:171], v[192:195], v[38:41]
	v_mfma_f32_16x16x32_bf16 v[34:37], v[176:179], v[192:195], v[34:37]
	v_mfma_f32_16x16x32_bf16 v[22:25], v[168:171], v[200:203], v[22:25]
	v_mfma_f32_16x16x32_bf16 v[18:21], v[176:179], v[200:203], v[18:21]
	v_mfma_f32_16x16x32_bf16 v[6:9], v[168:171], v[208:211], v[6:9]
	v_mfma_f32_16x16x32_bf16 v[2:5], v[176:179], v[208:211], v[2:5]
	v_mfma_f32_16x16x32_bf16 v[54:57], v[172:175], v[188:191], v[54:57]
	v_mfma_f32_16x16x32_bf16 v[50:53], v[180:183], v[188:191], v[50:53]
	v_mfma_f32_16x16x32_bf16 v[38:41], v[172:175], v[196:199], v[38:41]
	v_mfma_f32_16x16x32_bf16 v[34:37], v[180:183], v[196:199], v[34:37]
	v_mfma_f32_16x16x32_bf16 v[22:25], v[172:175], v[204:207], v[22:25]
	v_mfma_f32_16x16x32_bf16 v[18:21], v[180:183], v[204:207], v[18:21]
	v_mfma_f32_16x16x32_bf16 v[6:9], v[172:175], v[212:215], v[6:9]
	v_mfma_f32_16x16x32_bf16 v[2:5], v[180:183], v[212:215], v[2:5]
	s_barrier
	s_add_u32 s38, s38, 0x100
	s_addc_u32 s39, s39, 0
	s_add_u32 s96, s96, 0x100
	s_addc_u32 s97, s97, 0
	s_cmp_ge_i32 vcc_lo, s73
	s_mov_b32 s40, vcc_lo
	s_cbranch_scc0 .LBB0_269
	s_and_b64 vcc, exec, s[24:25]
	s_cbranch_vccz .LBB0_272

; #define PG8_STAGE(bufoff, gbase, voff) do { _Pragma("unroll") for (int _i = 0; _i < 2; ++_i) \
;         __builtin_amdgcn_global_load_lds((const unsigned*)((const char*)(gbase) + (voff)[_i]), (PG8_LAS unsigned*)(lds + (bufoff) + ldsw + _i * 8192), 16, 0, 0); } while (0)
; #define PG8_LDA(dst, b, h) do { _Pragma("unroll") for (int m = 0; m < 4; ++m) _Pragma("unroll") for (int k = 0; k < 2; ++k) dst[m][k] = *(const PG8_LAS bf16x8*)(lds + PG8_SA(b, h) + aoff + m * 2048 + k * 1024); } while (0)
; #define PG8_LDB(dst, b, h) do { _Pragma("unroll") for (int n = 0; n < 2; ++n) _Pragma("unroll") for (int k = 0; k < 2; ++k) dst[n][k] = *(const PG8_LAS bf16x8*)(lds + PG8_SB(b, h) + boff + n * 2048 + k * 1024); } while (0)
; #define PG8_MMA(ai, bj, At, Bt) do { __builtin_amdgcn_s_setprio(1); _Pragma("unroll") for (int m = 0; m < 4; ++m) _Pragma("unroll") for (int n = 0; n < 2; ++n) _Pragma("unroll") for (int k = 0; k < 2; ++k) \
;         acc[ai][bj][m][n] = __builtin_amdgcn_mfma_f32_16x16x32_bf16(Bt[n][k], At[m][k], acc[ai][bj][m][n], 0, 0, 0); __builtin_amdgcn_s_setprio(0); } while (0)
; #define PG8_WAIT_V(n) asm volatile("s_waitcnt vmcnt(" #n ")" ::: "memory")
; #define PG8_WAIT_L(n) do { asm volatile("s_waitcnt lgkmcnt(" #n ")" ::: "memory"); __builtin_amdgcn_s_waitcnt(0xC07F); } while (0)
; #define PG8_BAR __builtin_amdgcn_s_barrier()
; template <class Epi, class Sched, bool SEG3 = false>
; __device__ __forceinline__ void gemm_phase(PG8_LAS unsigned char* lds, const Gemm g, const Sched& S, const Epi& E) {
;     ...
;             const bool last = (t == ntc - 2);
;             const char* a1 = cA + (size_t)(t + 1) * kstep;
;             const char* a2 = last ? nA : cA + (size_t)(t + 2) * kstep; const char* b2 = last ? nB : cB + (size_t)(t + 2) * kstep;
;             const char* a3 = a2 + kstep; const char* b3 = b2 + kstep;
;             PG8_LDB(B0, 0, 0); PG8_LDB(B1, 0, 1); PG8_SCHED; PG8_LDA(At, 0, 0); PG8_STAGE(PG8_SA(1, 1), a1 + hsA, voffA);
;             PG8_WAIT_V(8); PG8_WAIT_L(0); PG8_BAR; if (cur.half != 1) { PG8_MMA(0, 0, At, B0); PG8_MMA(0, 1, At, B1); } PG8_BAR; PG8_SCHED;
;             PG8_LDA(At, 0, 1); PG8_STAGE(PG8_SB(0, 0), b2, voffB); PG8_STAGE(PG8_SB(0, 1), b2 + hsB, voffB); PG8_STAGE(PG8_SA(0, 0), a2, voffA);
;             PG8_WAIT_V(8); PG8_WAIT_L(0); PG8_BAR; if (cur.half != 0) { PG8_MMA(1, 0, At, B0); PG8_MMA(1, 1, At, B1); } PG8_BAR; PG8_SCHED;
.LBB0_313:
	v_add_u32_e32 v142, s54, v146
	ds_read_b128 v[152:155], v142
	ds_read_b128 v[156:159], v142 offset:1024
	ds_read_b128 v[160:163], v142 offset:2048
	ds_read_b128 v[164:167], v142 offset:3072
	v_add_u32_e32 v142, s55, v146
	ds_read_b128 v[168:171], v142
	ds_read_b128 v[172:175], v142 offset:1024
	ds_read_b128 v[176:179], v142 offset:2048
	ds_read_b128 v[180:183], v142 offset:3072
	s_add_i32 s93, s40, 2
	s_add_u32 s0, s38, 0xfffc0080
	s_addc_u32 s1, s39, -1
	s_cmp_eq_u32 s87, s40
	s_cselect_b32 s40, s90, s91
	s_cselect_b32 s43, s17, s1
	s_cselect_b32 s42, s29, s0
	s_cselect_b32 s41, s31, s92
	v_lshl_add_u64 v[142:143], s[38:39], 0, v[138:139]
	s_add_i32 m0, s77, 0xc000
	ds_read_b128 v[184:187], v151
	ds_read_b128 v[188:191], v151 offset:1024
	ds_read_b128 v[192:195], v151 offset:2048
	ds_read_b128 v[196:199], v151 offset:3072
	ds_read_b128 v[200:203], v151 offset:4096
	ds_read_b128 v[204:207], v151 offset:5120
	ds_read_b128 v[208:211], v151 offset:6144
	ds_read_b128 v[212:215], v151 offset:7168
	global_load_lds_dwordx4 v[142:143], off
	v_lshl_add_u64 v[142:143], s[38:39], 0, v[140:141]
	s_add_i32 m0, s77, 0xe000
	s_nop 0
	global_load_lds_dwordx4 v[142:143], off
	s_waitcnt vmcnt(8)
	s_waitcnt lgkmcnt(0)
	s_waitcnt lgkmcnt(0)
	s_barrier
	v_mfma_f32_16x16x32_bf16 v[126:129], v[152:155], v[184:187], v[126:129]
	v_mfma_f32_16x16x32_bf16 v[122:125], v[160:163], v[184:187], v[122:125]
	v_mfma_f32_16x16x32_bf16 v[110:113], v[152:155], v[192:195], v[110:113]
	v_mfma_f32_16x16x32_bf16 v[106:109], v[160:163], v[192:195], v[106:109]
	v_mfma_f32_16x16x32_bf16 v[94:97], v[152:155], v[200:203], v[94:97]
	v_mfma_f32_16x16x32_bf16 v[90:93], v[160:163], v[200:203], v[90:93]
	v_mfma_f32_16x16x32_bf16 v[78:81], v[152:155], v[208:211], v[78:81]
	v_mfma_f32_16x16x32_bf16 v[74:77], v[160:163], v[208:211], v[74:77]
	v_mfma_f32_16x16x32_bf16 v[126:129], v[156:159], v[188:191], v[126:129]
	v_mfma_f32_16x16x32_bf16 v[122:125], v[164:167], v[188:191], v[122:125]
	v_mfma_f32_16x16x32_bf16 v[110:113], v[156:159], v[196:199], v[110:113]
	v_mfma_f32_16x16x32_bf16 v[106:109], v[164:167], v[196:199], v[106:109]
	v_mfma_f32_16x16x32_bf16 v[94:97], v[156:159], v[204:207], v[94:97]
	v_mfma_f32_16x16x32_bf16 v[90:93], v[164:167], v[204:207], v[90:93]
	v_mfma_f32_16x16x32_bf16 v[78:81], v[156:159], v[212:215], v[78:81]
	v_mfma_f32_16x16x32_bf16 v[74:77], v[164:167], v[212:215], v[74:77]
	v_mfma_f32_16x16x32_bf16 v[118:121], v[168:171], v[184:187], v[118:121]
	v_mfma_f32_16x16x32_bf16 v[114:117], v[176:179], v[184:187], v[114:117]
	v_mfma_f32_16x16x32_bf16 v[102:105], v[168:171], v[192:195], v[102:105]
	v_mfma_f32_16x16x32_bf16 v[98:101], v[176:179], v[192:195], v[98:101]
	v_mfma_f32_16x16x32_bf16 v[86:89], v[168:171], v[200:203], v[86:89]
	v_mfma_f32_16x16x32_bf16 v[82:85], v[176:179], v[200:203], v[82:85]
	v_mfma_f32_16x16x32_bf16 v[70:73], v[168:171], v[208:211], v[70:73]
	v_mfma_f32_16x16x32_bf16 v[66:69], v[176:179], v[208:211], v[66:69]
	v_mfma_f32_16x16x32_bf16 v[118:121], v[172:175], v[188:191], v[118:121]
	v_mfma_f32_16x16x32_bf16 v[114:117], v[180:183], v[188:191], v[114:117]
	v_mfma_f32_16x16x32_bf16 v[102:105], v[172:175], v[196:199], v[102:105]
	v_mfma_f32_16x16x32_bf16 v[98:101], v[180:183], v[196:199], v[98:101]
	v_mfma_f32_16x16x32_bf16 v[86:89], v[172:175], v[204:207], v[86:89]
	v_mfma_f32_16x16x32_bf16 v[82:85], v[180:183], v[204:207], v[82:85]
	v_mfma_f32_16x16x32_bf16 v[70:73], v[172:175], v[212:215], v[70:73]
	v_mfma_f32_16x16x32_bf16 v[66:69], v[180:183], v[212:215], v[66:69]
	s_barrier
	s_mov_b32 m0, s19
	v_lshl_add_u64 v[142:143], s[40:41], 0, v[130:131]
	s_add_u32 s0, s40, 0x40000
	ds_read_b128 v[184:187], v151 offset:16384
	ds_read_b128 v[188:191], v151 offset:17408
	ds_read_b128 v[192:195], v151 offset:18432
	ds_read_b128 v[196:199], v151 offset:19456
	ds_read_b128 v[200:203], v151 offset:20480
	ds_read_b128 v[204:207], v151 offset:21504
	ds_read_b128 v[208:211], v151 offset:22528
	ds_read_b128 v[212:215], v151 offset:23552
	global_load_lds_dwordx4 v[142:143], off
	v_lshl_add_u64 v[216:217], s[40:41], 0, v[136:137]
	s_mov_b32 m0, s74
	s_addc_u32 s1, s41, 0
	global_load_lds_dwordx4 v[216:217], off
	v_lshl_add_u64 v[218:219], s[0:1], 0, v[130:131]
	s_mov_b32 m0, s75
	v_lshl_add_u64 v[220:221], s[42:43], 0, v[134:135]
	global_load_lds_dwordx4 v[218:219], off
	v_lshl_add_u64 v[218:219], s[0:1], 0, v[136:137]
	s_mov_b32 m0, s76
	s_nop 0
	global_load_lds_dwordx4 v[218:219], off
	v_lshl_add_u64 v[218:219], s[42:43], 0, v[132:133]
	s_mov_b32 m0, s77
	s_nop 0
	global_load_lds_dwordx4 v[218:219], off
	s_mov_b32 m0, s78
	s_nop 0
	global_load_lds_dwordx4 v[220:221], off
	s_waitcnt vmcnt(8)
	s_waitcnt lgkmcnt(0)
	s_waitcnt lgkmcnt(0)
	s_barrier
; #define PG8_STAGE(bufoff, gbase, voff) do { _Pragma("unroll") for (int _i = 0; _i < 2; ++_i) \
;         __builtin_amdgcn_global_load_lds((const unsigned*)((const char*)(gbase) + (voff)[_i]), (PG8_LAS unsigned*)(lds + (bufoff) + ldsw + _i * 8192), 16, 0, 0); } while (0)
; #define PG8_LDA(dst, b, h) do { _Pragma("unroll") for (int m = 0; m < 4; ++m) _Pragma("unroll") for (int k = 0; k < 2; ++k) dst[m][k] = *(const PG8_LAS bf16x8*)(lds + PG8_SA(b, h) + aoff + m * 2048 + k * 1024); } while (0)
; #define PG8_LDB(dst, b, h) do { _Pragma("unroll") for (int n = 0; n < 2; ++n) _Pragma("unroll") for (int k = 0; k < 2; ++k) dst[n][k] = *(const PG8_LAS bf16x8*)(lds + PG8_SB(b, h) + boff + n * 2048 + k * 1024); } while (0)
; #define PG8_MMA(ai, bj, At, Bt) do { __builtin_amdgcn_s_setprio(1); _Pragma("unroll") for (int m = 0; m < 4; ++m) _Pragma("unroll") for (int n = 0; n < 2; ++n) _Pragma("unroll") for (int k = 0; k < 2; ++k) \
;         acc[ai][bj][m][n] = __builtin_amdgcn_mfma_f32_16x16x32_bf16(Bt[n][k], At[m][k], acc[ai][bj][m][n], 0, 0, 0); __builtin_amdgcn_s_setprio(0); } while (0)
; #define PG8_WAIT_V(n) asm volatile("s_waitcnt vmcnt(" #n ")" ::: "memory")
; #define PG8_WAIT_L(n) do { asm volatile("s_waitcnt lgkmcnt(" #n ")" ::: "memory"); __builtin_amdgcn_s_waitcnt(0xC07F); } while (0)
; #define PG8_BAR __builtin_amdgcn_s_barrier()
; #define PG8_SCHED __builtin_amdgcn_sched_barrier(0)
; template <class Epi, class Sched, bool SEG3 = false>
; __device__ __forceinline__ void gemm_phase(PG8_LAS unsigned char* lds, const Gemm g, const Sched& S, const Epi& E) {
;     ...
;             PG8_WAIT_V(8); PG8_WAIT_L(0); PG8_BAR; if (cur.half != 0) { PG8_MMA(1, 0, At, B0); PG8_MMA(1, 1, At, B1); } PG8_BAR; PG8_SCHED;
;             PG8_LDB(B0, 1, 0); PG8_LDB(B1, 1, 1); PG8_SCHED; PG8_LDA(At, 1, 0); PG8_STAGE(PG8_SA(0, 1), a2 + hsA, voffA);
;             PG8_WAIT_V(8); PG8_WAIT_L(0); PG8_BAR; if (cur.half != 1) { PG8_MMA(0, 0, At, B0); PG8_MMA(0, 1, At, B1); } PG8_BAR; PG8_SCHED;
	v_mfma_f32_16x16x32_bf16 v[62:65], v[152:155], v[184:187], v[62:65]
	v_mfma_f32_16x16x32_bf16 v[58:61], v[160:163], v[184:187], v[58:61]
	v_mfma_f32_16x16x32_bf16 v[46:49], v[152:155], v[192:195], v[46:49]
	v_mfma_f32_16x16x32_bf16 v[42:45], v[160:163], v[192:195], v[42:45]
	v_mfma_f32_16x16x32_bf16 v[30:33], v[152:155], v[200:203], v[30:33]
	v_mfma_f32_16x16x32_bf16 v[26:29], v[160:163], v[200:203], v[26:29]
	v_mfma_f32_16x16x32_bf16 v[14:17], v[152:155], v[208:211], v[14:17]
	v_mfma_f32_16x16x32_bf16 v[10:13], v[160:163], v[208:211], v[10:13]
	v_mfma_f32_16x16x32_bf16 v[62:65], v[156:159], v[188:191], v[62:65]
	v_mfma_f32_16x16x32_bf16 v[58:61], v[164:167], v[188:191], v[58:61]
	v_mfma_f32_16x16x32_bf16 v[46:49], v[156:159], v[196:199], v[46:49]
	v_mfma_f32_16x16x32_bf16 v[42:45], v[164:167], v[196:199], v[42:45]
	v_mfma_f32_16x16x32_bf16 v[30:33], v[156:159], v[204:207], v[30:33]
	v_mfma_f32_16x16x32_bf16 v[26:29], v[164:167], v[204:207], v[26:29]
	v_mfma_f32_16x16x32_bf16 v[14:17], v[156:159], v[212:215], v[14:17]
	v_mfma_f32_16x16x32_bf16 v[10:13], v[164:167], v[212:215], v[10:13]
	v_mfma_f32_16x16x32_bf16 v[54:57], v[168:171], v[184:187], v[54:57]
	v_mfma_f32_16x16x32_bf16 v[50:53], v[176:179], v[184:187], v[50:53]
	v_mfma_f32_16x16x32_bf16 v[38:41], v[168:171], v[192:195], v[38:41]
	v_mfma_f32_16x16x32_bf16 v[34:37], v[176:179], v[192:195], v[34:37]
	v_mfma_f32_16x16x32_bf16 v[22:25], v[168:171], v[200:203], v[22:25]
	v_mfma_f32_16x16x32_bf16 v[18:21], v[176:179], v[200:203], v[18:21]
	v_mfma_f32_16x16x32_bf16 v[6:9], v[168:171], v[208:211], v[6:9]
	v_mfma_f32_16x16x32_bf16 v[2:5], v[176:179], v[208:211], v[2:5]
	v_mfma_f32_16x16x32_bf16 v[54:57], v[172:175], v[188:191], v[54:57]
	v_mfma_f32_16x16x32_bf16 v[50:53], v[180:183], v[188:191], v[50:53]
	v_mfma_f32_16x16x32_bf16 v[38:41], v[172:175], v[196:199], v[38:41]
	v_mfma_f32_16x16x32_bf16 v[34:37], v[180:183], v[196:199], v[34:37]
	v_mfma_f32_16x16x32_bf16 v[22:25], v[172:175], v[204:207], v[22:25]
	v_mfma_f32_16x16x32_bf16 v[18:21], v[180:183], v[204:207], v[18:21]
	v_mfma_f32_16x16x32_bf16 v[6:9], v[172:175], v[212:215], v[6:9]
	v_mfma_f32_16x16x32_bf16 v[2:5], v[180:183], v[212:215], v[2:5]
	s_barrier
	v_add_u32_e32 v164, s56, v146
	v_add_u32_e32 v180, s57, v146
	ds_read_b128 v[152:155], v164
	ds_read_b128 v[156:159], v164 offset:1024
	ds_read_b128 v[160:163], v164 offset:2048
	ds_read_b128 v[164:167], v164 offset:3072
	ds_read_b128 v[168:171], v180
	ds_read_b128 v[172:175], v180 offset:1024
	ds_read_b128 v[176:179], v180 offset:2048
	ds_read_b128 v[180:183], v180 offset:3072
	s_add_u32 s0, s42, 0x40000
	s_addc_u32 s1, s43, 0
	s_mov_b32 m0, s79
	v_lshl_add_u64 v[222:223], s[0:1], 0, v[132:133]
	ds_read_b128 v[184:187], v151 offset:32768
	ds_read_b128 v[188:191], v151 offset:33792
	ds_read_b128 v[192:195], v151 offset:34816
	ds_read_b128 v[196:199], v151 offset:35840
	ds_read_b128 v[200:203], v151 offset:36864
	ds_read_b128 v[204:207], v151 offset:37888
	ds_read_b128 v[208:211], v151 offset:38912
	ds_read_b128 v[212:215], v151 offset:39936
	global_load_lds_dwordx4 v[222:223], off
	v_lshl_add_u64 v[222:223], s[0:1], 0, v[134:135]
	s_mov_b32 m0, s80
	s_nop 0
	global_load_lds_dwordx4 v[222:223], off
	s_waitcnt vmcnt(8)
	s_waitcnt lgkmcnt(0)
	s_waitcnt lgkmcnt(0)
	s_barrier
	v_mfma_f32_16x16x32_bf16 v[126:129], v[152:155], v[184:187], v[126:129]
	v_mfma_f32_16x16x32_bf16 v[122:125], v[160:163], v[184:187], v[122:125]
	v_mfma_f32_16x16x32_bf16 v[110:113], v[152:155], v[192:195], v[110:113]
	v_mfma_f32_16x16x32_bf16 v[106:109], v[160:163], v[192:195], v[106:109]
	v_mfma_f32_16x16x32_bf16 v[94:97], v[152:155], v[200:203], v[94:97]
	v_mfma_f32_16x16x32_bf16 v[90:93], v[160:163], v[200:203], v[90:93]
	v_mfma_f32_16x16x32_bf16 v[78:81], v[152:155], v[208:211], v[78:81]
	v_mfma_f32_16x16x32_bf16 v[74:77], v[160:163], v[208:211], v[74:77]
	v_mfma_f32_16x16x32_bf16 v[126:129], v[156:159], v[188:191], v[126:129]
	v_mfma_f32_16x16x32_bf16 v[122:125], v[164:167], v[188:191], v[122:125]
	v_mfma_f32_16x16x32_bf16 v[110:113], v[156:159], v[196:199], v[110:113]
	v_mfma_f32_16x16x32_bf16 v[106:109], v[164:167], v[196:199], v[106:109]
	v_mfma_f32_16x16x32_bf16 v[94:97], v[156:159], v[204:207], v[94:97]
	v_mfma_f32_16x16x32_bf16 v[90:93], v[164:167], v[204:207], v[90:93]
	v_mfma_f32_16x16x32_bf16 v[78:81], v[156:159], v[212:215], v[78:81]
	v_mfma_f32_16x16x32_bf16 v[74:77], v[164:167], v[212:215], v[74:77]
	v_mfma_f32_16x16x32_bf16 v[118:121], v[168:171], v[184:187], v[118:121]
	v_mfma_f32_16x16x32_bf16 v[114:117], v[176:179], v[184:187], v[114:117]
	v_mfma_f32_16x16x32_bf16 v[102:105], v[168:171], v[192:195], v[102:105]
	v_mfma_f32_16x16x32_bf16 v[98:101], v[176:179], v[192:195], v[98:101]
	v_mfma_f32_16x16x32_bf16 v[86:89], v[168:171], v[200:203], v[86:89]
	v_mfma_f32_16x16x32_bf16 v[82:85], v[176:179], v[200:203], v[82:85]
	v_mfma_f32_16x16x32_bf16 v[70:73], v[168:171], v[208:211], v[70:73]
	v_mfma_f32_16x16x32_bf16 v[66:69], v[176:179], v[208:211], v[66:69]
	v_mfma_f32_16x16x32_bf16 v[118:121], v[172:175], v[188:191], v[118:121]
	v_mfma_f32_16x16x32_bf16 v[114:117], v[180:183], v[188:191], v[114:117]
	v_mfma_f32_16x16x32_bf16 v[102:105], v[172:175], v[196:199], v[102:105]
	v_mfma_f32_16x16x32_bf16 v[98:101], v[180:183], v[196:199], v[98:101]
	v_mfma_f32_16x16x32_bf16 v[86:89], v[172:175], v[204:207], v[86:89]
	v_mfma_f32_16x16x32_bf16 v[82:85], v[180:183], v[204:207], v[82:85]
	v_mfma_f32_16x16x32_bf16 v[70:73], v[172:175], v[212:215], v[70:73]
	v_mfma_f32_16x16x32_bf16 v[66:69], v[180:183], v[212:215], v[66:69]
	s_barrier
; #define PG8_STAGE(bufoff, gbase, voff) do { _Pragma("unroll") for (int _i = 0; _i < 2; ++_i) \
;         __builtin_amdgcn_global_load_lds((const unsigned*)((const char*)(gbase) + (voff)[_i]), (PG8_LAS unsigned*)(lds + (bufoff) + ldsw + _i * 8192), 16, 0, 0); } while (0)
; #define PG8_LDA(dst, b, h) do { _Pragma("unroll") for (int m = 0; m < 4; ++m) _Pragma("unroll") for (int k = 0; k < 2; ++k) dst[m][k] = *(const PG8_LAS bf16x8*)(lds + PG8_SA(b, h) + aoff + m * 2048 + k * 1024); } while (0)
; #define PG8_MMA(ai, bj, At, Bt) do { __builtin_amdgcn_s_setprio(1); _Pragma("unroll") for (int m = 0; m < 4; ++m) _Pragma("unroll") for (int n = 0; n < 2; ++n) _Pragma("unroll") for (int k = 0; k < 2; ++k) \
;         acc[ai][bj][m][n] = __builtin_amdgcn_mfma_f32_16x16x32_bf16(Bt[n][k], At[m][k], acc[ai][bj][m][n], 0, 0, 0); __builtin_amdgcn_s_setprio(0); } while (0)
; #define PG8_WAIT_V(n) asm volatile("s_waitcnt vmcnt(" #n ")" ::: "memory")
; #define PG8_WAIT_L(n) do { asm volatile("s_waitcnt lgkmcnt(" #n ")" ::: "memory"); __builtin_amdgcn_s_waitcnt(0xC07F); } while (0)
; #define PG8_BAR __builtin_amdgcn_s_barrier()
; #define PG8_SCHED __builtin_amdgcn_sched_barrier(0)
; template <class Epi, class Sched, bool SEG3 = false>
; __device__ __forceinline__ void gemm_phase(PG8_LAS unsigned char* lds, const Gemm g, const Sched& S, const Epi& E) {
;     ...
;             PG8_LDA(At, 1, 1); PG8_STAGE(PG8_SB(1, 0), b3, voffB); PG8_STAGE(PG8_SB(1, 1), b3 + hsB, voffB); PG8_STAGE(PG8_SA(1, 0), a3, voffA);
;             PG8_WAIT_V(8); PG8_WAIT_L(0); PG8_BAR; if (cur.half != 0) { PG8_MMA(1, 0, At, B0); PG8_MMA(1, 1, At, B1); } PG8_BAR; PG8_SCHED;
;         }
	s_mov_b32 m0, s81
	v_lshl_add_u64 v[142:143], v[142:143], 0, s[6:7]
	s_add_u32 s0, s40, 0x40080
	ds_read_b128 v[184:187], v151 offset:49152
	ds_read_b128 v[188:191], v151 offset:50176
	ds_read_b128 v[192:195], v151 offset:51200
	ds_read_b128 v[196:199], v151 offset:52224
	ds_read_b128 v[200:203], v151 offset:53248
	ds_read_b128 v[204:207], v151 offset:54272
	ds_read_b128 v[208:211], v151 offset:55296
	ds_read_b128 v[212:215], v151 offset:56320
	global_load_lds_dwordx4 v[142:143], off
	v_lshl_add_u64 v[142:143], v[216:217], 0, s[6:7]
	s_mov_b32 m0, s82
	s_addc_u32 s1, s41, 0
	global_load_lds_dwordx4 v[142:143], off
	v_lshl_add_u64 v[142:143], s[0:1], 0, v[130:131]
	s_mov_b32 m0, s85
	s_nop 0
	global_load_lds_dwordx4 v[142:143], off
	v_lshl_add_u64 v[142:143], s[0:1], 0, v[136:137]
	s_mov_b32 m0, s86
	s_nop 0
	global_load_lds_dwordx4 v[142:143], off
	v_lshl_add_u64 v[142:143], v[218:219], 0, s[6:7]
	s_mov_b32 m0, s83
	s_nop 0
	global_load_lds_dwordx4 v[142:143], off
	v_lshl_add_u64 v[142:143], v[220:221], 0, s[6:7]
	s_mov_b32 m0, s84
	s_nop 0
	global_load_lds_dwordx4 v[142:143], off
	s_waitcnt vmcnt(8)
	s_waitcnt lgkmcnt(0)
	s_waitcnt lgkmcnt(0)
	s_barrier
	v_mfma_f32_16x16x32_bf16 v[62:65], v[152:155], v[184:187], v[62:65]
	v_mfma_f32_16x16x32_bf16 v[58:61], v[160:163], v[184:187], v[58:61]
	v_mfma_f32_16x16x32_bf16 v[46:49], v[152:155], v[192:195], v[46:49]
	v_mfma_f32_16x16x32_bf16 v[42:45], v[160:163], v[192:195], v[42:45]
	v_mfma_f32_16x16x32_bf16 v[30:33], v[152:155], v[200:203], v[30:33]
	v_mfma_f32_16x16x32_bf16 v[26:29], v[160:163], v[200:203], v[26:29]
	v_mfma_f32_16x16x32_bf16 v[14:17], v[152:155], v[208:211], v[14:17]
	v_mfma_f32_16x16x32_bf16 v[10:13], v[160:163], v[208:211], v[10:13]
	v_mfma_f32_16x16x32_bf16 v[62:65], v[156:159], v[188:191], v[62:65]
	v_mfma_f32_16x16x32_bf16 v[58:61], v[164:167], v[188:191], v[58:61]
	v_mfma_f32_16x16x32_bf16 v[46:49], v[156:159], v[196:199], v[46:49]
	v_mfma_f32_16x16x32_bf16 v[42:45], v[164:167], v[196:199], v[42:45]
	v_mfma_f32_16x16x32_bf16 v[30:33], v[156:159], v[204:207], v[30:33]
	v_mfma_f32_16x16x32_bf16 v[26:29], v[164:167], v[204:207], v[26:29]
	v_mfma_f32_16x16x32_bf16 v[14:17], v[156:159], v[212:215], v[14:17]
	v_mfma_f32_16x16x32_bf16 v[10:13], v[164:167], v[212:215], v[10:13]
	v_mfma_f32_16x16x32_bf16 v[54:57], v[168:171], v[184:187], v[54:57]
	v_mfma_f32_16x16x32_bf16 v[50:53], v[176:179], v[184:187], v[50:53]
	v_mfma_f32_16x16x32_bf16 v[38:41], v[168:171], v[192:195], v[38:41]
	v_mfma_f32_16x16x32_bf16 v[34:37], v[176:179], v[192:195], v[34:37]
	v_mfma_f32_16x16x32_bf16 v[22:25], v[168:171], v[200:203], v[22:25]
	v_mfma_f32_16x16x32_bf16 v[18:21], v[176:179], v[200:203], v[18:21]
	v_mfma_f32_16x16x32_bf16 v[6:9], v[168:171], v[208:211], v[6:9]
	v_mfma_f32_16x16x32_bf16 v[2:5], v[176:179], v[208:211], v[2:5]
	v_mfma_f32_16x16x32_bf16 v[54:57], v[172:175], v[188:191], v[54:57]
	v_mfma_f32_16x16x32_bf16 v[50:53], v[180:183], v[188:191], v[50:53]
	v_mfma_f32_16x16x32_bf16 v[38:41], v[172:175], v[196:199], v[38:41]
	v_mfma_f32_16x16x32_bf16 v[34:37], v[180:183], v[196:199], v[34:37]
	v_mfma_f32_16x16x32_bf16 v[22:25], v[172:175], v[204:207], v[22:25]
	v_mfma_f32_16x16x32_bf16 v[18:21], v[180:183], v[204:207], v[18:21]
	v_mfma_f32_16x16x32_bf16 v[6:9], v[172:175], v[212:215], v[6:9]
	v_mfma_f32_16x16x32_bf16 v[2:5], v[180:183], v[212:215], v[2:5]
	s_barrier
	s_add_u32 s38, s38, 0x100
	s_addc_u32 s39, s39, 0
	s_add_u32 s91, s91, 0x100
	s_addc_u32 s92, s92, 0
	s_cmp_ge_i32 s93, s4
	s_mov_b32 s40, s93
	s_cbranch_scc0 .LBB0_313
	s_and_b64 vcc, exec, s[24:25]
	s_cbranch_vccz .LBB0_316

; #define PG8_STAGE(bufoff, gbase, voff) do { _Pragma("unroll") for (int _i = 0; _i < 2; ++_i) \
;         __builtin_amdgcn_global_load_lds((const unsigned*)((const char*)(gbase) + (voff)[_i]), (PG8_LAS unsigned*)(lds + (bufoff) + ldsw + _i * 8192), 16, 0, 0); } while (0)
; #define PG8_LDA(dst, b, h) do { _Pragma("unroll") for (int m = 0; m < 4; ++m) _Pragma("unroll") for (int k = 0; k < 2; ++k) dst[m][k] = *(const PG8_LAS bf16x8*)(lds + PG8_SA(b, h) + aoff + m * 2048 + k * 1024); } while (0)
; #define PG8_LDB(dst, b, h) do { _Pragma("unroll") for (int n = 0; n < 2; ++n) _Pragma("unroll") for (int k = 0; k < 2; ++k) dst[n][k] = *(const PG8_LAS bf16x8*)(lds + PG8_SB(b, h) + boff + n * 2048 + k * 1024); } while (0)
; #define PG8_MMA(ai, bj, At, Bt) do { __builtin_amdgcn_s_setprio(1); _Pragma("unroll") for (int m = 0; m < 4; ++m) _Pragma("unroll") for (int n = 0; n < 2; ++n) _Pragma("unroll") for (int k = 0; k < 2; ++k) \
;         acc[ai][bj][m][n] = __builtin_amdgcn_mfma_f32_16x16x32_bf16(Bt[n][k], At[m][k], acc[ai][bj][m][n], 0, 0, 0); __builtin_amdgcn_s_setprio(0); } while (0)
; #define PG8_WAIT_V(n) asm volatile("s_waitcnt vmcnt(" #n ")" ::: "memory")
; #define PG8_WAIT_L(n) do { asm volatile("s_waitcnt lgkmcnt(" #n ")" ::: "memory"); __builtin_amdgcn_s_waitcnt(0xC07F); } while (0)
; #define PG8_BAR __builtin_amdgcn_s_barrier()
; #define PG8_SCHED __builtin_amdgcn_sched_barrier(0)
; template <class Epi, class Sched, bool SEG3 = false>
; __device__ __forceinline__ void gemm_phase(PG8_LAS unsigned char* lds, const Gemm g, const Sched& S, const Epi& E) {
;     ...
;             PG8_LDB(B0, 0, 0); PG8_LDB(B1, 0, 1); PG8_SCHED; PG8_LDA(At, 0, 0); PG8_STAGE(PG8_SA(1, 1), a1 + hsA, voffA);
;             PG8_WAIT_V(8); PG8_WAIT_L(0); PG8_BAR; if (cur.half != 1) { PG8_MMA(0, 0, At, B0); PG8_MMA(0, 1, At, B1); } PG8_BAR; PG8_SCHED;
.Lfi_a_0:
	s_andn2_b64 vcc, exec, s[34:35]
	s_waitcnt lgkmcnt(0)
	s_barrier
	s_cbranch_vccnz .LBB0_437
	v_mfma_f32_16x16x32_bf16 v[138:141], v[146:149], v[186:189], v[138:141]
	v_mfma_f32_16x16x32_bf16 v[130:133], v[154:157], v[186:189], v[130:133]
	v_mfma_f32_16x16x32_bf16 v[122:125], v[146:149], v[178:181], v[122:125]
	v_mfma_f32_16x16x32_bf16 v[114:117], v[154:157], v[178:181], v[114:117]
	v_mfma_f32_16x16x32_bf16 v[106:109], v[146:149], v[170:173], v[106:109]
	v_mfma_f32_16x16x32_bf16 v[10:13], v[154:157], v[170:173], v[10:13]
	v_mfma_f32_16x16x32_bf16 v[90:93], v[146:149], v[162:165], v[90:93]
	v_mfma_f32_16x16x32_bf16 v[82:85], v[154:157], v[162:165], v[82:85]
	v_mfma_f32_16x16x32_bf16 v[138:141], v[150:153], v[190:193], v[138:141]
	v_mfma_f32_16x16x32_bf16 v[130:133], v[158:161], v[190:193], v[130:133]
	v_mfma_f32_16x16x32_bf16 v[122:125], v[150:153], v[182:185], v[122:125]
	v_mfma_f32_16x16x32_bf16 v[114:117], v[158:161], v[182:185], v[114:117]
	v_mfma_f32_16x16x32_bf16 v[106:109], v[150:153], v[174:177], v[106:109]
	v_mfma_f32_16x16x32_bf16 v[10:13], v[158:161], v[174:177], v[10:13]
	v_mfma_f32_16x16x32_bf16 v[90:93], v[150:153], v[166:169], v[90:93]
	v_mfma_f32_16x16x32_bf16 v[82:85], v[158:161], v[166:169], v[82:85]
	v_mfma_f32_16x16x32_bf16 v[142:145], v[2:5], v[186:189], v[142:145]
	v_mfma_f32_16x16x32_bf16 v[134:137], v[98:101], v[186:189], v[134:137]
	v_mfma_f32_16x16x32_bf16 v[126:129], v[2:5], v[178:181], v[126:129]
	v_mfma_f32_16x16x32_bf16 v[118:121], v[98:101], v[178:181], v[118:121]
	v_mfma_f32_16x16x32_bf16 v[110:113], v[2:5], v[170:173], v[110:113]
	v_mfma_f32_16x16x32_bf16 v[14:17], v[98:101], v[170:173], v[14:17]
	v_mfma_f32_16x16x32_bf16 v[94:97], v[2:5], v[162:165], v[94:97]
	v_mfma_f32_16x16x32_bf16 v[86:89], v[98:101], v[162:165], v[86:89]
	v_mfma_f32_16x16x32_bf16 v[142:145], v[6:9], v[190:193], v[142:145]
	v_mfma_f32_16x16x32_bf16 v[134:137], v[102:105], v[190:193], v[134:137]
	v_mfma_f32_16x16x32_bf16 v[126:129], v[6:9], v[182:185], v[126:129]
	v_mfma_f32_16x16x32_bf16 v[118:121], v[102:105], v[182:185], v[118:121]
	v_mfma_f32_16x16x32_bf16 v[110:113], v[6:9], v[174:177], v[110:113]
	v_mfma_f32_16x16x32_bf16 v[14:17], v[102:105], v[174:177], v[14:17]
	v_mfma_f32_16x16x32_bf16 v[94:97], v[6:9], v[166:169], v[94:97]
	v_mfma_f32_16x16x32_bf16 v[86:89], v[102:105], v[166:169], v[86:89]

; #define PG8_STAGE(bufoff, gbase, voff) do { _Pragma("unroll") for (int _i = 0; _i < 2; ++_i) \
;         __builtin_amdgcn_global_load_lds((const unsigned*)((const char*)(gbase) + (voff)[_i]), (PG8_LAS unsigned*)(lds + (bufoff) + ldsw + _i * 8192), 16, 0, 0); } while (0)
; #define PG8_LDA(dst, b, h) do { _Pragma("unroll") for (int m = 0; m < 4; ++m) _Pragma("unroll") for (int k = 0; k < 2; ++k) dst[m][k] = *(const PG8_LAS bf16x8*)(lds + PG8_SA(b, h) + aoff + m * 2048 + k * 1024); } while (0)
; #define PG8_LDB(dst, b, h) do { _Pragma("unroll") for (int n = 0; n < 2; ++n) _Pragma("unroll") for (int k = 0; k < 2; ++k) dst[n][k] = *(const PG8_LAS bf16x8*)(lds + PG8_SB(b, h) + boff + n * 2048 + k * 1024); } while (0)
; #define PG8_MMA(ai, bj, At, Bt) do { __builtin_amdgcn_s_setprio(1); _Pragma("unroll") for (int m = 0; m < 4; ++m) _Pragma("unroll") for (int n = 0; n < 2; ++n) _Pragma("unroll") for (int k = 0; k < 2; ++k) \
;         acc[ai][bj][m][n] = __builtin_amdgcn_mfma_f32_16x16x32_bf16(Bt[n][k], At[m][k], acc[ai][bj][m][n], 0, 0, 0); __builtin_amdgcn_s_setprio(0); } while (0)
; #define PG8_WAIT_V(n) asm volatile("s_waitcnt vmcnt(" #n ")" ::: "memory")
; #define PG8_WAIT_L(n) do { asm volatile("s_waitcnt lgkmcnt(" #n ")" ::: "memory"); __builtin_amdgcn_s_waitcnt(0xC07F); } while (0)
; #define PG8_BAR __builtin_amdgcn_s_barrier()
; #define PG8_SCHED __builtin_amdgcn_sched_barrier(0)
; template <class Epi, class Sched, bool SEG3 = false>
; __device__ __forceinline__ void gemm_phase(PG8_LAS unsigned char* lds, const Gemm g, const Sched& S, const Epi& E) {
;     ...
;             PG8_WAIT_V(8); PG8_WAIT_L(0); PG8_BAR; if (cur.half != 1) { PG8_MMA(0, 0, At, B0); PG8_MMA(0, 1, At, B1); } PG8_BAR; PG8_SCHED;
;             PG8_LDA(At, 0, 1); PG8_STAGE(PG8_SB(0, 0), b2, voffB); PG8_STAGE(PG8_SB(0, 1), b2 + hsB, voffB); PG8_STAGE(PG8_SA(0, 0), a2, voffA);
;             PG8_WAIT_V(8); PG8_WAIT_L(0); PG8_BAR; if (cur.half != 0) { PG8_MMA(1, 0, At, B0); PG8_MMA(1, 1, At, B1); } PG8_BAR; PG8_SCHED;
;             PG8_LDB(B0, 1, 0); PG8_LDB(B1, 1, 1); PG8_SCHED; PG8_LDA(At, 1, 0); PG8_STAGE(PG8_SA(0, 1), a2 + hsA, voffA);
;             PG8_WAIT_V(8); PG8_WAIT_L(0); PG8_BAR; if (cur.half != 1) { PG8_MMA(0, 0, At, B0); PG8_MMA(0, 1, At, B1); } PG8_BAR; PG8_SCHED;
.Lfi_b_0:
	s_mov_b32 s98, 0
	s_waitcnt lgkmcnt(0)
	s_barrier
	s_cbranch_vccnz .LBB0_439
	v_mfma_f32_16x16x32_bf16 v[74:77], v[146:149], v[186:189], v[74:77]
	v_mfma_f32_16x16x32_bf16 v[66:69], v[154:157], v[186:189], v[66:69]
	v_mfma_f32_16x16x32_bf16 v[58:61], v[146:149], v[178:181], v[58:61]
	v_mfma_f32_16x16x32_bf16 v[50:53], v[154:157], v[178:181], v[50:53]
	v_mfma_f32_16x16x32_bf16 v[42:45], v[146:149], v[170:173], v[42:45]
	v_mfma_f32_16x16x32_bf16 v[34:37], v[154:157], v[170:173], v[34:37]
	v_mfma_f32_16x16x32_bf16 v[26:29], v[146:149], v[162:165], v[26:29]
	v_mfma_f32_16x16x32_bf16 v[22:25], v[154:157], v[162:165], v[22:25]
	v_mfma_f32_16x16x32_bf16 v[74:77], v[150:153], v[190:193], v[74:77]
	v_mfma_f32_16x16x32_bf16 v[66:69], v[158:161], v[190:193], v[66:69]
	v_mfma_f32_16x16x32_bf16 v[58:61], v[150:153], v[182:185], v[58:61]
	v_mfma_f32_16x16x32_bf16 v[50:53], v[158:161], v[182:185], v[50:53]
	v_mfma_f32_16x16x32_bf16 v[42:45], v[150:153], v[174:177], v[42:45]
	v_mfma_f32_16x16x32_bf16 v[34:37], v[158:161], v[174:177], v[34:37]
	v_mfma_f32_16x16x32_bf16 v[26:29], v[150:153], v[166:169], v[26:29]
	v_mfma_f32_16x16x32_bf16 v[22:25], v[158:161], v[166:169], v[22:25]
	v_mfma_f32_16x16x32_bf16 v[78:81], v[2:5], v[186:189], v[78:81]
	v_mfma_f32_16x16x32_bf16 v[62:65], v[2:5], v[178:181], v[62:65]
	v_mfma_f32_16x16x32_bf16 v[46:49], v[2:5], v[170:173], v[46:49]
	v_mfma_f32_16x16x32_bf16 v[2:5], v[2:5], v[162:165], v[30:33]
	v_mfma_f32_16x16x32_bf16 v[70:73], v[98:101], v[186:189], v[70:73]
	v_mfma_f32_16x16x32_bf16 v[54:57], v[98:101], v[178:181], v[54:57]
	v_mfma_f32_16x16x32_bf16 v[38:41], v[98:101], v[170:173], v[38:41]
	v_mfma_f32_16x16x32_bf16 v[30:33], v[6:9], v[166:169], v[2:5]
	v_mfma_f32_16x16x32_bf16 v[2:5], v[98:101], v[162:165], v[18:21]
	v_mfma_f32_16x16x32_bf16 v[78:81], v[6:9], v[190:193], v[78:81]
	v_mfma_f32_16x16x32_bf16 v[70:73], v[102:105], v[190:193], v[70:73]
	v_mfma_f32_16x16x32_bf16 v[62:65], v[6:9], v[182:185], v[62:65]
	v_mfma_f32_16x16x32_bf16 v[54:57], v[102:105], v[182:185], v[54:57]
	v_mfma_f32_16x16x32_bf16 v[46:49], v[6:9], v[174:177], v[46:49]
	v_mfma_f32_16x16x32_bf16 v[38:41], v[102:105], v[174:177], v[38:41]
	v_mfma_f32_16x16x32_bf16 v[18:21], v[102:105], v[166:169], v[2:5]
.LBB0_439:
	s_barrier
	s_nop 0
	v_add_u32_e32 v2, s56, v219
	v_add_u32_e32 v102, s61, v219
	ds_read_b128 v[146:149], v2
	ds_read_b128 v[150:153], v2 offset:1024
	ds_read_b128 v[154:157], v2 offset:2048
	ds_read_b128 v[158:161], v2 offset:3072
	ds_read_b128 v[2:5], v102
	ds_read_b128 v[6:9], v102 offset:1024
	ds_read_b128 v[98:101], v102 offset:2048
	ds_read_b128 v[102:105], v102 offset:3072
	s_add_u32 s42, s42, 0x40000
	s_addc_u32 s43, s43, 0
	s_mov_b32 m0, s52
	v_lshl_add_u64 v[228:229], s[42:43], 0, v[194:195]
	ds_read_b128 v[186:189], v223 offset:32768
	ds_read_b128 v[190:193], v223 offset:33792
	ds_read_b128 v[178:181], v223 offset:34816
	ds_read_b128 v[182:185], v223 offset:35840
	ds_read_b128 v[170:173], v223 offset:36864
	ds_read_b128 v[174:177], v223 offset:37888
	ds_read_b128 v[162:165], v223 offset:38912
	ds_read_b128 v[166:169], v223 offset:39936
	global_load_lds_dwordx4 v[228:229], off
	v_lshl_add_u64 v[228:229], s[42:43], 0, v[198:199]
	s_mov_b32 m0, s53
	s_and_b64 vcc, exec, s[4:5]
	global_load_lds_dwordx4 v[228:229], off
	s_waitcnt vmcnt(8)
	s_waitcnt lgkmcnt(0)
	s_waitcnt lgkmcnt(0)
	s_barrier
	s_cbranch_vccnz .LBB0_441
	v_mfma_f32_16x16x32_bf16 v[138:141], v[146:149], v[186:189], v[138:141]
	v_mfma_f32_16x16x32_bf16 v[130:133], v[154:157], v[186:189], v[130:133]
	v_mfma_f32_16x16x32_bf16 v[122:125], v[146:149], v[178:181], v[122:125]
	v_mfma_f32_16x16x32_bf16 v[114:117], v[154:157], v[178:181], v[114:117]
	v_mfma_f32_16x16x32_bf16 v[106:109], v[146:149], v[170:173], v[106:109]
	v_mfma_f32_16x16x32_bf16 v[10:13], v[154:157], v[170:173], v[10:13]
	v_mfma_f32_16x16x32_bf16 v[90:93], v[146:149], v[162:165], v[90:93]
	v_mfma_f32_16x16x32_bf16 v[82:85], v[154:157], v[162:165], v[82:85]
	v_mfma_f32_16x16x32_bf16 v[138:141], v[150:153], v[190:193], v[138:141]
	v_mfma_f32_16x16x32_bf16 v[130:133], v[158:161], v[190:193], v[130:133]
	v_mfma_f32_16x16x32_bf16 v[122:125], v[150:153], v[182:185], v[122:125]
	v_mfma_f32_16x16x32_bf16 v[114:117], v[158:161], v[182:185], v[114:117]
	v_mfma_f32_16x16x32_bf16 v[106:109], v[150:153], v[174:177], v[106:109]
	v_mfma_f32_16x16x32_bf16 v[10:13], v[158:161], v[174:177], v[10:13]
	v_mfma_f32_16x16x32_bf16 v[90:93], v[150:153], v[166:169], v[90:93]
	v_mfma_f32_16x16x32_bf16 v[82:85], v[158:161], v[166:169], v[82:85]
	v_mfma_f32_16x16x32_bf16 v[142:145], v[2:5], v[186:189], v[142:145]
	v_mfma_f32_16x16x32_bf16 v[134:137], v[98:101], v[186:189], v[134:137]
	v_mfma_f32_16x16x32_bf16 v[126:129], v[2:5], v[178:181], v[126:129]
	v_mfma_f32_16x16x32_bf16 v[118:121], v[98:101], v[178:181], v[118:121]
	v_mfma_f32_16x16x32_bf16 v[110:113], v[2:5], v[170:173], v[110:113]
	v_mfma_f32_16x16x32_bf16 v[14:17], v[98:101], v[170:173], v[14:17]
	v_mfma_f32_16x16x32_bf16 v[94:97], v[2:5], v[162:165], v[94:97]
	v_mfma_f32_16x16x32_bf16 v[86:89], v[98:101], v[162:165], v[86:89]
	v_mfma_f32_16x16x32_bf16 v[142:145], v[6:9], v[190:193], v[142:145]
	v_mfma_f32_16x16x32_bf16 v[134:137], v[102:105], v[190:193], v[134:137]
	v_mfma_f32_16x16x32_bf16 v[126:129], v[6:9], v[182:185], v[126:129]
	v_mfma_f32_16x16x32_bf16 v[118:121], v[102:105], v[182:185], v[118:121]
	v_mfma_f32_16x16x32_bf16 v[110:113], v[6:9], v[174:177], v[110:113]
	v_mfma_f32_16x16x32_bf16 v[14:17], v[102:105], v[174:177], v[14:17]
	v_mfma_f32_16x16x32_bf16 v[94:97], v[6:9], v[166:169], v[94:97]
	v_mfma_f32_16x16x32_bf16 v[86:89], v[102:105], v[166:169], v[86:89]
; #define PG8_STAGE(bufoff, gbase, voff) do { _Pragma("unroll") for (int _i = 0; _i < 2; ++_i) \
;         __builtin_amdgcn_global_load_lds((const unsigned*)((const char*)(gbase) + (voff)[_i]), (PG8_LAS unsigned*)(lds + (bufoff) + ldsw + _i * 8192), 16, 0, 0); } while (0)
; #define PG8_LDA(dst, b, h) do { _Pragma("unroll") for (int m = 0; m < 4; ++m) _Pragma("unroll") for (int k = 0; k < 2; ++k) dst[m][k] = *(const PG8_LAS bf16x8*)(lds + PG8_SA(b, h) + aoff + m * 2048 + k * 1024); } while (0)
; #define PG8_MMA(ai, bj, At, Bt) do { __builtin_amdgcn_s_setprio(1); _Pragma("unroll") for (int m = 0; m < 4; ++m) _Pragma("unroll") for (int n = 0; n < 2; ++n) _Pragma("unroll") for (int k = 0; k < 2; ++k) \
;         acc[ai][bj][m][n] = __builtin_amdgcn_mfma_f32_16x16x32_bf16(Bt[n][k], At[m][k], acc[ai][bj][m][n], 0, 0, 0); __builtin_amdgcn_s_setprio(0); } while (0)
; #define PG8_WAIT_V(n) asm volatile("s_waitcnt vmcnt(" #n ")" ::: "memory")
; #define PG8_WAIT_L(n) do { asm volatile("s_waitcnt lgkmcnt(" #n ")" ::: "memory"); __builtin_amdgcn_s_waitcnt(0xC07F); } while (0)
; #define PG8_BAR __builtin_amdgcn_s_barrier()
; #define PG8_SCHED __builtin_amdgcn_sched_barrier(0)
; template <class Epi, class Sched, bool SEG3 = false>
; __device__ __forceinline__ void gemm_phase(PG8_LAS unsigned char* lds, const Gemm g, const Sched& S, const Epi& E) {
;     ...
;             PG8_LDA(At, 1, 1); PG8_STAGE(PG8_SB(1, 0), b3, voffB); PG8_STAGE(PG8_SB(1, 1), b3 + hsB, voffB); PG8_STAGE(PG8_SA(1, 0), a3, voffA);
;             PG8_WAIT_V(8); PG8_WAIT_L(0); PG8_BAR; if (cur.half != 0) { PG8_MMA(1, 0, At, B0); PG8_MMA(1, 1, At, B1); } PG8_BAR; PG8_SCHED;
.LBB0_441:
	s_barrier
	s_mov_b32 m0, s57
	v_lshl_add_u64 v[210:211], v[210:211], 0, s[12:13]
	s_add_u32 s4, s40, 0x40080
	ds_read_b128 v[186:189], v223 offset:49152
	ds_read_b128 v[190:193], v223 offset:50176
	ds_read_b128 v[178:181], v223 offset:51200
	ds_read_b128 v[182:185], v223 offset:52224
	ds_read_b128 v[170:173], v223 offset:53248
	ds_read_b128 v[174:177], v223 offset:54272
	ds_read_b128 v[162:165], v223 offset:55296
	ds_read_b128 v[166:169], v223 offset:56320
	global_load_lds_dwordx4 v[210:211], off
	v_lshl_add_u64 v[210:211], v[212:213], 0, s[12:13]
	s_mov_b32 m0, s58
	s_addc_u32 s5, s41, 0
	global_load_lds_dwordx4 v[210:211], off
	v_lshl_add_u64 v[210:211], s[4:5], 0, v[196:197]
	s_mov_b32 m0, s62
	s_and_b64 vcc, exec, s[6:7]
	global_load_lds_dwordx4 v[210:211], off
	v_lshl_add_u64 v[210:211], s[4:5], 0, v[200:201]
	s_mov_b32 m0, s63
	s_nop 0
	global_load_lds_dwordx4 v[210:211], off
	v_lshl_add_u64 v[210:211], v[214:215], 0, s[12:13]
	s_mov_b32 m0, s59
	s_nop 0
	global_load_lds_dwordx4 v[210:211], off
	v_lshl_add_u64 v[210:211], v[216:217], 0, s[12:13]
	s_mov_b32 m0, s60
	s_nop 0
	global_load_lds_dwordx4 v[210:211], off
	s_waitcnt vmcnt(8)
	s_waitcnt lgkmcnt(0)
	s_waitcnt lgkmcnt(0)
	s_barrier
	s_cbranch_vccnz .LBB0_434
	v_mfma_f32_16x16x32_bf16 v[74:77], v[146:149], v[186:189], v[74:77]
	v_mfma_f32_16x16x32_bf16 v[66:69], v[154:157], v[186:189], v[66:69]
	v_mfma_f32_16x16x32_bf16 v[58:61], v[146:149], v[178:181], v[58:61]
	v_mfma_f32_16x16x32_bf16 v[50:53], v[154:157], v[178:181], v[50:53]
	v_mfma_f32_16x16x32_bf16 v[42:45], v[146:149], v[170:173], v[42:45]
	v_mfma_f32_16x16x32_bf16 v[34:37], v[154:157], v[170:173], v[34:37]
	v_mfma_f32_16x16x32_bf16 v[26:29], v[146:149], v[162:165], v[26:29]
	v_mfma_f32_16x16x32_bf16 v[22:25], v[154:157], v[162:165], v[22:25]
	v_mfma_f32_16x16x32_bf16 v[74:77], v[150:153], v[190:193], v[74:77]
	v_mfma_f32_16x16x32_bf16 v[66:69], v[158:161], v[190:193], v[66:69]
	v_mfma_f32_16x16x32_bf16 v[58:61], v[150:153], v[182:185], v[58:61]
	v_mfma_f32_16x16x32_bf16 v[50:53], v[158:161], v[182:185], v[50:53]
	v_mfma_f32_16x16x32_bf16 v[42:45], v[150:153], v[174:177], v[42:45]
	v_mfma_f32_16x16x32_bf16 v[34:37], v[158:161], v[174:177], v[34:37]
	v_mfma_f32_16x16x32_bf16 v[26:29], v[150:153], v[166:169], v[26:29]
	v_mfma_f32_16x16x32_bf16 v[22:25], v[158:161], v[166:169], v[22:25]
	v_mfma_f32_16x16x32_bf16 v[78:81], v[2:5], v[186:189], v[78:81]
	v_mfma_f32_16x16x32_bf16 v[62:65], v[2:5], v[178:181], v[62:65]
	v_mfma_f32_16x16x32_bf16 v[46:49], v[2:5], v[170:173], v[46:49]
	v_mfma_f32_16x16x32_bf16 v[2:5], v[2:5], v[162:165], v[30:33]
	v_mfma_f32_16x16x32_bf16 v[70:73], v[98:101], v[186:189], v[70:73]
	v_mfma_f32_16x16x32_bf16 v[54:57], v[98:101], v[178:181], v[54:57]
	v_mfma_f32_16x16x32_bf16 v[38:41], v[98:101], v[170:173], v[38:41]
	v_mfma_f32_16x16x32_bf16 v[30:33], v[6:9], v[166:169], v[2:5]
	v_mfma_f32_16x16x32_bf16 v[2:5], v[98:101], v[162:165], v[18:21]
	v_mfma_f32_16x16x32_bf16 v[78:81], v[6:9], v[190:193], v[78:81]
	v_mfma_f32_16x16x32_bf16 v[70:73], v[102:105], v[190:193], v[70:73]
	v_mfma_f32_16x16x32_bf16 v[62:65], v[6:9], v[182:185], v[62:65]
	v_mfma_f32_16x16x32_bf16 v[54:57], v[102:105], v[182:185], v[54:57]
	v_mfma_f32_16x16x32_bf16 v[46:49], v[6:9], v[174:177], v[46:49]
	v_mfma_f32_16x16x32_bf16 v[38:41], v[102:105], v[174:177], v[38:41]
	v_mfma_f32_16x16x32_bf16 v[18:21], v[102:105], v[166:169], v[2:5]
	s_branch .LBB0_434

; #define PG8_STAGE(bufoff, gbase, voff) do { _Pragma("unroll") for (int _i = 0; _i < 2; ++_i) \
;         __builtin_amdgcn_global_load_lds((const unsigned*)((const char*)(gbase) + (voff)[_i]), (PG8_LAS unsigned*)(lds + (bufoff) + ldsw + _i * 8192), 16, 0, 0); } while (0)
; #define PG8_LDA(dst, b, h) do { _Pragma("unroll") for (int m = 0; m < 4; ++m) _Pragma("unroll") for (int k = 0; k < 2; ++k) dst[m][k] = *(const PG8_LAS bf16x8*)(lds + PG8_SA(b, h) + aoff + m * 2048 + k * 1024); } while (0)
; #define PG8_MMA(ai, bj, At, Bt) do { __builtin_amdgcn_s_setprio(1); _Pragma("unroll") for (int m = 0; m < 4; ++m) _Pragma("unroll") for (int n = 0; n < 2; ++n) _Pragma("unroll") for (int k = 0; k < 2; ++k) \
;         acc[ai][bj][m][n] = __builtin_amdgcn_mfma_f32_16x16x32_bf16(Bt[n][k], At[m][k], acc[ai][bj][m][n], 0, 0, 0); __builtin_amdgcn_s_setprio(0); } while (0)
; #define PG8_WAIT_V(n) asm volatile("s_waitcnt vmcnt(" #n ")" ::: "memory")
; #define PG8_WAIT_L(n) do { asm volatile("s_waitcnt lgkmcnt(" #n ")" ::: "memory"); __builtin_amdgcn_s_waitcnt(0xC07F); } while (0)
; #define PG8_BAR __builtin_amdgcn_s_barrier()
; #define PG8_SCHED __builtin_amdgcn_sched_barrier(0)
; template <class Epi, class Sched, bool SEG3 = false>
; __device__ __forceinline__ void gemm_phase(PG8_LAS unsigned char* lds, const Gemm g, const Sched& S, const Epi& E) {
;     ...
;             PG8_WAIT_V(8); PG8_WAIT_L(0); PG8_BAR; if (cur.half != 1) { PG8_MMA(0, 0, At, B0); PG8_MMA(0, 1, At, B1); } PG8_BAR; PG8_SCHED;
;             PG8_LDA(At, 0, 1); PG8_STAGE(PG8_SB(0, 0), b2, voffB); PG8_STAGE(PG8_SB(0, 1), b2 + hsB, voffB); PG8_STAGE(PG8_SA(0, 0), a2, voffA);
;             PG8_WAIT_V(8); PG8_WAIT_L(0); PG8_BAR; if (cur.half != 0) { PG8_MMA(1, 0, At, B0); PG8_MMA(1, 1, At, B1); } PG8_BAR; PG8_SCHED;
.Lfi_a_1:
	s_waitcnt lgkmcnt(0)
	s_barrier
	v_mfma_f32_16x16x32_bf16 v[142:145], v[98:101], v[178:181], v[142:145]
	v_mfma_f32_16x16x32_bf16 v[138:141], v[122:125], v[178:181], v[138:141]
	v_mfma_f32_16x16x32_bf16 v[118:121], v[98:101], v[186:189], v[118:121]
	v_mfma_f32_16x16x32_bf16 v[114:117], v[122:125], v[186:189], v[114:117]
	v_mfma_f32_16x16x32_bf16 v[94:97], v[98:101], v[194:197], v[94:97]
	v_mfma_f32_16x16x32_bf16 v[90:93], v[122:125], v[194:197], v[90:93]
	v_mfma_f32_16x16x32_bf16 v[78:81], v[98:101], v[210:213], v[78:81]
	v_mfma_f32_16x16x32_bf16 v[74:77], v[122:125], v[210:213], v[74:77]
	v_mfma_f32_16x16x32_bf16 v[142:145], v[110:113], v[182:185], v[142:145]
	v_mfma_f32_16x16x32_bf16 v[138:141], v[134:137], v[182:185], v[138:141]
	v_mfma_f32_16x16x32_bf16 v[118:121], v[110:113], v[190:193], v[118:121]
	v_mfma_f32_16x16x32_bf16 v[114:117], v[134:137], v[190:193], v[114:117]
	v_mfma_f32_16x16x32_bf16 v[94:97], v[110:113], v[206:209], v[94:97]
	v_mfma_f32_16x16x32_bf16 v[90:93], v[134:137], v[206:209], v[90:93]
	v_mfma_f32_16x16x32_bf16 v[78:81], v[110:113], v[214:217], v[78:81]
	v_mfma_f32_16x16x32_bf16 v[74:77], v[134:137], v[214:217], v[74:77]
	v_mfma_f32_16x16x32_bf16 v[130:133], v[146:149], v[178:181], v[130:133]
	v_mfma_f32_16x16x32_bf16 v[126:129], v[170:173], v[178:181], v[126:129]
	v_mfma_f32_16x16x32_bf16 v[106:109], v[146:149], v[186:189], v[106:109]
	v_mfma_f32_16x16x32_bf16 v[102:105], v[170:173], v[186:189], v[102:105]
	v_mfma_f32_16x16x32_bf16 v[86:89], v[146:149], v[194:197], v[86:89]
	v_mfma_f32_16x16x32_bf16 v[82:85], v[170:173], v[194:197], v[82:85]
	v_mfma_f32_16x16x32_bf16 v[70:73], v[146:149], v[210:213], v[70:73]
	v_mfma_f32_16x16x32_bf16 v[66:69], v[170:173], v[210:213], v[66:69]
	v_mfma_f32_16x16x32_bf16 v[130:133], v[150:153], v[182:185], v[130:133]
	v_mfma_f32_16x16x32_bf16 v[126:129], v[174:177], v[182:185], v[126:129]
	v_mfma_f32_16x16x32_bf16 v[106:109], v[150:153], v[190:193], v[106:109]
	v_mfma_f32_16x16x32_bf16 v[102:105], v[174:177], v[190:193], v[102:105]
	v_mfma_f32_16x16x32_bf16 v[86:89], v[150:153], v[206:209], v[86:89]
	v_mfma_f32_16x16x32_bf16 v[82:85], v[174:177], v[206:209], v[82:85]
	v_mfma_f32_16x16x32_bf16 v[70:73], v[150:153], v[214:217], v[70:73]
	v_mfma_f32_16x16x32_bf16 v[66:69], v[174:177], v[214:217], v[66:69]
	s_barrier
	s_mov_b32 m0, s42
	v_lshl_add_u64 v[218:219], s[34:35], 0, v[156:157]
	s_add_u32 s28, s34, 0xb0000
	ds_read_b128 v[178:181], v201 offset:16384
	ds_read_b128 v[182:185], v201 offset:17408
	ds_read_b128 v[186:189], v201 offset:18432
	ds_read_b128 v[190:193], v201 offset:19456
	ds_read_b128 v[194:197], v201 offset:20480
	ds_read_b128 v[206:209], v201 offset:21504
	ds_read_b128 v[210:213], v201 offset:22528
	ds_read_b128 v[214:217], v201 offset:23552
	global_load_lds_dwordx4 v[218:219], off
	v_lshl_add_u64 v[220:221], s[34:35], 0, v[160:161]
	s_mov_b32 m0, s43
	s_addc_u32 s29, s35, 0
	global_load_lds_dwordx4 v[220:221], off
	v_lshl_add_u64 v[222:223], s[28:29], 0, v[156:157]
	s_mov_b32 m0, s44
	v_lshl_add_u64 v[224:225], s[36:37], 0, v[158:159]
	global_load_lds_dwordx4 v[222:223], off
	v_lshl_add_u64 v[222:223], s[28:29], 0, v[160:161]
	s_mov_b32 m0, s45
	s_nop 0
	global_load_lds_dwordx4 v[222:223], off
	v_lshl_add_u64 v[222:223], s[36:37], 0, v[154:155]
	s_mov_b32 m0, s46
	s_nop 0
	global_load_lds_dwordx4 v[222:223], off
	s_mov_b32 m0, s47
	s_nop 0
	global_load_lds_dwordx4 v[224:225], off
	s_cmp_lg_u32 s98, 0
	s_cbranch_scc1 .Lfi_b_1
	s_waitcnt vmcnt(8)
.Lfi_b_1:
	s_mov_b32 s98, 0
	s_waitcnt lgkmcnt(0)
	s_barrier
	v_mfma_f32_16x16x32_bf16 v[62:65], v[98:101], v[178:181], v[62:65]
	v_mfma_f32_16x16x32_bf16 v[58:61], v[122:125], v[178:181], v[58:61]
	v_mfma_f32_16x16x32_bf16 v[46:49], v[98:101], v[186:189], v[46:49]
	v_mfma_f32_16x16x32_bf16 v[42:45], v[122:125], v[186:189], v[42:45]
	v_mfma_f32_16x16x32_bf16 v[30:33], v[98:101], v[194:197], v[30:33]
	v_mfma_f32_16x16x32_bf16 v[26:29], v[122:125], v[194:197], v[26:29]
	v_mfma_f32_16x16x32_bf16 v[14:17], v[98:101], v[210:213], v[14:17]
	v_mfma_f32_16x16x32_bf16 v[10:13], v[122:125], v[210:213], v[10:13]
	v_mfma_f32_16x16x32_bf16 v[62:65], v[110:113], v[182:185], v[62:65]
	v_mfma_f32_16x16x32_bf16 v[58:61], v[134:137], v[182:185], v[58:61]
	v_mfma_f32_16x16x32_bf16 v[46:49], v[110:113], v[190:193], v[46:49]
	v_mfma_f32_16x16x32_bf16 v[42:45], v[134:137], v[190:193], v[42:45]
	v_mfma_f32_16x16x32_bf16 v[30:33], v[110:113], v[206:209], v[30:33]
	v_mfma_f32_16x16x32_bf16 v[26:29], v[134:137], v[206:209], v[26:29]
	v_mfma_f32_16x16x32_bf16 v[14:17], v[110:113], v[214:217], v[14:17]
	v_mfma_f32_16x16x32_bf16 v[10:13], v[134:137], v[214:217], v[10:13]
	v_mfma_f32_16x16x32_bf16 v[54:57], v[146:149], v[178:181], v[54:57]
	v_mfma_f32_16x16x32_bf16 v[50:53], v[170:173], v[178:181], v[50:53]
	v_mfma_f32_16x16x32_bf16 v[38:41], v[146:149], v[186:189], v[38:41]
	v_mfma_f32_16x16x32_bf16 v[34:37], v[170:173], v[186:189], v[34:37]
	v_mfma_f32_16x16x32_bf16 v[22:25], v[146:149], v[194:197], v[22:25]
	v_mfma_f32_16x16x32_bf16 v[18:21], v[170:173], v[194:197], v[18:21]
	v_mfma_f32_16x16x32_bf16 v[6:9], v[146:149], v[210:213], v[6:9]
	v_mfma_f32_16x16x32_bf16 v[2:5], v[170:173], v[210:213], v[2:5]
	v_mfma_f32_16x16x32_bf16 v[54:57], v[150:153], v[182:185], v[54:57]
	v_mfma_f32_16x16x32_bf16 v[50:53], v[174:177], v[182:185], v[50:53]
	v_mfma_f32_16x16x32_bf16 v[38:41], v[150:153], v[190:193], v[38:41]
	v_mfma_f32_16x16x32_bf16 v[34:37], v[174:177], v[190:193], v[34:37]
	v_mfma_f32_16x16x32_bf16 v[22:25], v[150:153], v[206:209], v[22:25]
	v_mfma_f32_16x16x32_bf16 v[18:21], v[174:177], v[206:209], v[18:21]
	v_mfma_f32_16x16x32_bf16 v[6:9], v[150:153], v[214:217], v[6:9]
	v_mfma_f32_16x16x32_bf16 v[2:5], v[174:177], v[214:217], v[2:5]
	s_barrier
; #define PG8_STAGE(bufoff, gbase, voff) do { _Pragma("unroll") for (int _i = 0; _i < 2; ++_i) \
;         __builtin_amdgcn_global_load_lds((const unsigned*)((const char*)(gbase) + (voff)[_i]), (PG8_LAS unsigned*)(lds + (bufoff) + ldsw + _i * 8192), 16, 0, 0); } while (0)
; #define PG8_LDA(dst, b, h) do { _Pragma("unroll") for (int m = 0; m < 4; ++m) _Pragma("unroll") for (int k = 0; k < 2; ++k) dst[m][k] = *(const PG8_LAS bf16x8*)(lds + PG8_SA(b, h) + aoff + m * 2048 + k * 1024); } while (0)
; #define PG8_LDB(dst, b, h) do { _Pragma("unroll") for (int n = 0; n < 2; ++n) _Pragma("unroll") for (int k = 0; k < 2; ++k) dst[n][k] = *(const PG8_LAS bf16x8*)(lds + PG8_SB(b, h) + boff + n * 2048 + k * 1024); } while (0)
; #define PG8_MMA(ai, bj, At, Bt) do { __builtin_amdgcn_s_setprio(1); _Pragma("unroll") for (int m = 0; m < 4; ++m) _Pragma("unroll") for (int n = 0; n < 2; ++n) _Pragma("unroll") for (int k = 0; k < 2; ++k) \
;         acc[ai][bj][m][n] = __builtin_amdgcn_mfma_f32_16x16x32_bf16(Bt[n][k], At[m][k], acc[ai][bj][m][n], 0, 0, 0); __builtin_amdgcn_s_setprio(0); } while (0)
; #define PG8_WAIT_V(n) asm volatile("s_waitcnt vmcnt(" #n ")" ::: "memory")
; #define PG8_WAIT_L(n) do { asm volatile("s_waitcnt lgkmcnt(" #n ")" ::: "memory"); __builtin_amdgcn_s_waitcnt(0xC07F); } while (0)
; #define PG8_BAR __builtin_amdgcn_s_barrier()
; #define PG8_SCHED __builtin_amdgcn_sched_barrier(0)
; template <class Epi, class Sched, bool SEG3 = false>
; __device__ __forceinline__ void gemm_phase(PG8_LAS unsigned char* lds, const Gemm g, const Sched& S, const Epi& E) {
;     ...
;             PG8_LDB(B0, 1, 0); PG8_LDB(B1, 1, 1); PG8_SCHED; PG8_LDA(At, 1, 0); PG8_STAGE(PG8_SA(0, 1), a2 + hsA, voffA);
;             PG8_WAIT_V(8); PG8_WAIT_L(0); PG8_BAR; if (cur.half != 1) { PG8_MMA(0, 0, At, B0); PG8_MMA(0, 1, At, B1); } PG8_BAR; PG8_SCHED;
;             PG8_LDA(At, 1, 1); PG8_STAGE(PG8_SB(1, 0), b3, voffB); PG8_STAGE(PG8_SB(1, 1), b3 + hsB, voffB); PG8_STAGE(PG8_SA(1, 0), a3, voffA);
;             PG8_WAIT_V(8); PG8_WAIT_L(0); PG8_BAR; if (cur.half != 0) { PG8_MMA(1, 0, At, B0); PG8_MMA(1, 1, At, B1); } PG8_BAR; PG8_SCHED;
;         }
	ds_read_b128 v[98:101], v202
	ds_read_b128 v[110:113], v202 offset:1024
	ds_read_b128 v[122:125], v202 offset:2048
	ds_read_b128 v[134:137], v202 offset:3072
	ds_read_b128 v[146:149], v203
	ds_read_b128 v[150:153], v203 offset:1024
	ds_read_b128 v[170:173], v203 offset:2048
	ds_read_b128 v[174:177], v203 offset:3072
	s_add_u32 s28, s36, 0xb0000
	s_addc_u32 s29, s37, 0
	s_mov_b32 m0, s48
	v_lshl_add_u64 v[226:227], s[28:29], 0, v[154:155]
	ds_read_b128 v[178:181], v201 offset:32768
	ds_read_b128 v[182:185], v201 offset:33792
	ds_read_b128 v[186:189], v201 offset:34816
	ds_read_b128 v[190:193], v201 offset:35840
	ds_read_b128 v[194:197], v201 offset:36864
	ds_read_b128 v[206:209], v201 offset:37888
	ds_read_b128 v[210:213], v201 offset:38912
	ds_read_b128 v[214:217], v201 offset:39936
	global_load_lds_dwordx4 v[226:227], off
	v_lshl_add_u64 v[226:227], s[28:29], 0, v[158:159]
	s_mov_b32 m0, s49
	s_nop 0
	global_load_lds_dwordx4 v[226:227], off
	s_waitcnt vmcnt(8)
	s_waitcnt lgkmcnt(0)
	s_waitcnt lgkmcnt(0)
	s_barrier
	v_mfma_f32_16x16x32_bf16 v[142:145], v[98:101], v[178:181], v[142:145]
	v_mfma_f32_16x16x32_bf16 v[138:141], v[122:125], v[178:181], v[138:141]
	v_mfma_f32_16x16x32_bf16 v[118:121], v[98:101], v[186:189], v[118:121]
	v_mfma_f32_16x16x32_bf16 v[114:117], v[122:125], v[186:189], v[114:117]
	v_mfma_f32_16x16x32_bf16 v[94:97], v[98:101], v[194:197], v[94:97]
	v_mfma_f32_16x16x32_bf16 v[90:93], v[122:125], v[194:197], v[90:93]
	v_mfma_f32_16x16x32_bf16 v[78:81], v[98:101], v[210:213], v[78:81]
	v_mfma_f32_16x16x32_bf16 v[74:77], v[122:125], v[210:213], v[74:77]
	v_mfma_f32_16x16x32_bf16 v[142:145], v[110:113], v[182:185], v[142:145]
	v_mfma_f32_16x16x32_bf16 v[138:141], v[134:137], v[182:185], v[138:141]
	v_mfma_f32_16x16x32_bf16 v[118:121], v[110:113], v[190:193], v[118:121]
	v_mfma_f32_16x16x32_bf16 v[114:117], v[134:137], v[190:193], v[114:117]
	v_mfma_f32_16x16x32_bf16 v[94:97], v[110:113], v[206:209], v[94:97]
	v_mfma_f32_16x16x32_bf16 v[90:93], v[134:137], v[206:209], v[90:93]
	v_mfma_f32_16x16x32_bf16 v[78:81], v[110:113], v[214:217], v[78:81]
	v_mfma_f32_16x16x32_bf16 v[74:77], v[134:137], v[214:217], v[74:77]
	v_mfma_f32_16x16x32_bf16 v[130:133], v[146:149], v[178:181], v[130:133]
	v_mfma_f32_16x16x32_bf16 v[126:129], v[170:173], v[178:181], v[126:129]
	v_mfma_f32_16x16x32_bf16 v[106:109], v[146:149], v[186:189], v[106:109]
	v_mfma_f32_16x16x32_bf16 v[102:105], v[170:173], v[186:189], v[102:105]
	v_mfma_f32_16x16x32_bf16 v[86:89], v[146:149], v[194:197], v[86:89]
	v_mfma_f32_16x16x32_bf16 v[82:85], v[170:173], v[194:197], v[82:85]
	v_mfma_f32_16x16x32_bf16 v[70:73], v[146:149], v[210:213], v[70:73]
	v_mfma_f32_16x16x32_bf16 v[66:69], v[170:173], v[210:213], v[66:69]
	v_mfma_f32_16x16x32_bf16 v[130:133], v[150:153], v[182:185], v[130:133]
	v_mfma_f32_16x16x32_bf16 v[126:129], v[174:177], v[182:185], v[126:129]
	v_mfma_f32_16x16x32_bf16 v[106:109], v[150:153], v[190:193], v[106:109]
	v_mfma_f32_16x16x32_bf16 v[102:105], v[174:177], v[190:193], v[102:105]
	v_mfma_f32_16x16x32_bf16 v[86:89], v[150:153], v[206:209], v[86:89]
	v_mfma_f32_16x16x32_bf16 v[82:85], v[174:177], v[206:209], v[82:85]
	v_mfma_f32_16x16x32_bf16 v[70:73], v[150:153], v[214:217], v[70:73]
	v_mfma_f32_16x16x32_bf16 v[66:69], v[174:177], v[214:217], v[66:69]
	s_barrier
	s_mov_b32 m0, s52
	v_lshl_add_u64 v[218:219], v[218:219], 0, s[20:21]
	s_add_u32 s28, s34, 0xb0080
	ds_read_b128 v[178:181], v201 offset:49152
	ds_read_b128 v[182:185], v201 offset:50176
	ds_read_b128 v[186:189], v201 offset:51200
	ds_read_b128 v[190:193], v201 offset:52224
	ds_read_b128 v[194:197], v201 offset:53248
	ds_read_b128 v[206:209], v201 offset:54272
	ds_read_b128 v[210:213], v201 offset:55296
	ds_read_b128 v[214:217], v201 offset:56320
	global_load_lds_dwordx4 v[218:219], off
	v_lshl_add_u64 v[218:219], v[220:221], 0, s[20:21]
	s_mov_b32 m0, s53
	s_addc_u32 s29, s35, 0
	global_load_lds_dwordx4 v[218:219], off
	v_lshl_add_u64 v[218:219], s[28:29], 0, v[156:157]
	s_mov_b32 m0, s56
	s_nop 0
	global_load_lds_dwordx4 v[218:219], off
	v_lshl_add_u64 v[218:219], s[28:29], 0, v[160:161]
	s_mov_b32 m0, s57
	s_nop 0
	global_load_lds_dwordx4 v[218:219], off
	v_lshl_add_u64 v[218:219], v[222:223], 0, s[20:21]
	s_mov_b32 m0, s54
	s_nop 0
	global_load_lds_dwordx4 v[218:219], off
	v_lshl_add_u64 v[218:219], v[224:225], 0, s[20:21]
	s_mov_b32 m0, s55
	s_nop 0
	global_load_lds_dwordx4 v[218:219], off
	s_waitcnt vmcnt(8)
	s_waitcnt lgkmcnt(0)
	s_waitcnt lgkmcnt(0)
	s_barrier
	v_mfma_f32_16x16x32_bf16 v[62:65], v[98:101], v[178:181], v[62:65]
	v_mfma_f32_16x16x32_bf16 v[58:61], v[122:125], v[178:181], v[58:61]
	v_mfma_f32_16x16x32_bf16 v[46:49], v[98:101], v[186:189], v[46:49]
	v_mfma_f32_16x16x32_bf16 v[42:45], v[122:125], v[186:189], v[42:45]
	v_mfma_f32_16x16x32_bf16 v[30:33], v[98:101], v[194:197], v[30:33]
	v_mfma_f32_16x16x32_bf16 v[26:29], v[122:125], v[194:197], v[26:29]
	v_mfma_f32_16x16x32_bf16 v[14:17], v[98:101], v[210:213], v[14:17]
	v_mfma_f32_16x16x32_bf16 v[10:13], v[122:125], v[210:213], v[10:13]
	v_mfma_f32_16x16x32_bf16 v[62:65], v[110:113], v[182:185], v[62:65]
	v_mfma_f32_16x16x32_bf16 v[58:61], v[134:137], v[182:185], v[58:61]
	v_mfma_f32_16x16x32_bf16 v[46:49], v[110:113], v[190:193], v[46:49]
	v_mfma_f32_16x16x32_bf16 v[42:45], v[134:137], v[190:193], v[42:45]
	v_mfma_f32_16x16x32_bf16 v[30:33], v[110:113], v[206:209], v[30:33]
	v_mfma_f32_16x16x32_bf16 v[26:29], v[134:137], v[206:209], v[26:29]
	v_mfma_f32_16x16x32_bf16 v[14:17], v[110:113], v[214:217], v[14:17]
	v_mfma_f32_16x16x32_bf16 v[10:13], v[134:137], v[214:217], v[10:13]
	v_mfma_f32_16x16x32_bf16 v[54:57], v[146:149], v[178:181], v[54:57]
	v_mfma_f32_16x16x32_bf16 v[50:53], v[170:173], v[178:181], v[50:53]
	v_mfma_f32_16x16x32_bf16 v[38:41], v[146:149], v[186:189], v[38:41]
	v_mfma_f32_16x16x32_bf16 v[34:37], v[170:173], v[186:189], v[34:37]
	v_mfma_f32_16x16x32_bf16 v[22:25], v[146:149], v[194:197], v[22:25]
	v_mfma_f32_16x16x32_bf16 v[18:21], v[170:173], v[194:197], v[18:21]
	v_mfma_f32_16x16x32_bf16 v[6:9], v[146:149], v[210:213], v[6:9]
	v_mfma_f32_16x16x32_bf16 v[2:5], v[170:173], v[210:213], v[2:5]
	v_mfma_f32_16x16x32_bf16 v[54:57], v[150:153], v[182:185], v[54:57]
	v_mfma_f32_16x16x32_bf16 v[50:53], v[174:177], v[182:185], v[50:53]
	v_mfma_f32_16x16x32_bf16 v[38:41], v[150:153], v[190:193], v[38:41]
	v_mfma_f32_16x16x32_bf16 v[34:37], v[174:177], v[190:193], v[34:37]
	v_mfma_f32_16x16x32_bf16 v[22:25], v[150:153], v[206:209], v[22:25]
	v_mfma_f32_16x16x32_bf16 v[18:21], v[174:177], v[206:209], v[18:21]
	v_mfma_f32_16x16x32_bf16 v[6:9], v[150:153], v[214:217], v[6:9]
	v_mfma_f32_16x16x32_bf16 v[2:5], v[174:177], v[214:217], v[2:5]
	s_barrier
	s_add_u32 s66, s66, 0x100
	s_addc_u32 s67, s67, 0
	s_cmp_ge_i32 s68, s51
	s_mov_b64 s[28:29], s[30:31]
	s_mov_b32 s34, s68
	s_cbranch_scc0 .LBB0_554
	s_and_b64 vcc, exec, s[24:25]
	s_cbranch_vccz .LBB0_557

; #define PG8_STAGE(bufoff, gbase, voff) do { _Pragma("unroll") for (int _i = 0; _i < 2; ++_i) \
;         __builtin_amdgcn_global_load_lds((const unsigned*)((const char*)(gbase) + (voff)[_i]), (PG8_LAS unsigned*)(lds + (bufoff) + ldsw + _i * 8192), 16, 0, 0); } while (0)
; #define PG8_LDA(dst, b, h) do { _Pragma("unroll") for (int m = 0; m < 4; ++m) _Pragma("unroll") for (int k = 0; k < 2; ++k) dst[m][k] = *(const PG8_LAS bf16x8*)(lds + PG8_SA(b, h) + aoff + m * 2048 + k * 1024); } while (0)
; #define PG8_MMA(ai, bj, At, Bt) do { __builtin_amdgcn_s_setprio(1); _Pragma("unroll") for (int m = 0; m < 4; ++m) _Pragma("unroll") for (int n = 0; n < 2; ++n) _Pragma("unroll") for (int k = 0; k < 2; ++k) \
;         acc[ai][bj][m][n] = __builtin_amdgcn_mfma_f32_16x16x32_bf16(Bt[n][k], At[m][k], acc[ai][bj][m][n], 0, 0, 0); __builtin_amdgcn_s_setprio(0); } while (0)
; #define PG8_WAIT_V(n) asm volatile("s_waitcnt vmcnt(" #n ")" ::: "memory")
; #define PG8_WAIT_L(n) do { asm volatile("s_waitcnt lgkmcnt(" #n ")" ::: "memory"); __builtin_amdgcn_s_waitcnt(0xC07F); } while (0)
; #define PG8_BAR __builtin_amdgcn_s_barrier()
; #define PG8_SCHED __builtin_amdgcn_sched_barrier(0)
; template <class Epi, class Sched, bool SEG3 = false>
; __device__ __forceinline__ void gemm_phase(PG8_LAS unsigned char* lds, const Gemm g, const Sched& S, const Epi& E) {
;     ...
;             PG8_WAIT_V(8); PG8_WAIT_L(0); PG8_BAR; if (cur.half != 1) { PG8_MMA(0, 0, At, B0); PG8_MMA(0, 1, At, B1); } PG8_BAR; PG8_SCHED;
;             PG8_LDA(At, 0, 1); PG8_STAGE(PG8_SB(0, 0), b2, voffB); PG8_STAGE(PG8_SB(0, 1), b2 + hsB, voffB); PG8_STAGE(PG8_SA(0, 0), a2, voffA);
;             PG8_WAIT_V(8); PG8_WAIT_L(0); PG8_BAR; if (cur.half != 0) { PG8_MMA(1, 0, At, B0); PG8_MMA(1, 1, At, B1); } PG8_BAR; PG8_SCHED;
.Lfi_a_2:
	s_waitcnt lgkmcnt(0)
	s_barrier
	v_mfma_f32_16x16x32_bf16 v[142:145], v[10:13], v[212:215], v[142:145]
	v_mfma_f32_16x16x32_bf16 v[138:141], v[34:37], v[212:215], v[138:141]
	v_mfma_f32_16x16x32_bf16 v[126:129], v[10:13], v[220:223], v[126:129]
	v_mfma_f32_16x16x32_bf16 v[122:125], v[34:37], v[220:223], v[122:125]
	v_mfma_f32_16x16x32_bf16 v[110:113], v[10:13], v[228:231], v[110:113]
	v_mfma_f32_16x16x32_bf16 v[106:109], v[34:37], v[228:231], v[106:109]
	v_mfma_f32_16x16x32_bf16 v[94:97], v[10:13], v[236:239], v[94:97]
	v_mfma_f32_16x16x32_bf16 v[90:93], v[34:37], v[236:239], v[90:93]
	v_mfma_f32_16x16x32_bf16 v[142:145], v[14:17], v[216:219], v[142:145]
	v_mfma_f32_16x16x32_bf16 v[138:141], v[38:41], v[216:219], v[138:141]
	v_mfma_f32_16x16x32_bf16 v[126:129], v[14:17], v[224:227], v[126:129]
	v_mfma_f32_16x16x32_bf16 v[122:125], v[38:41], v[224:227], v[122:125]
	v_mfma_f32_16x16x32_bf16 v[110:113], v[14:17], v[232:235], v[110:113]
	v_mfma_f32_16x16x32_bf16 v[106:109], v[38:41], v[232:235], v[106:109]
	v_mfma_f32_16x16x32_bf16 v[94:97], v[14:17], v[240:243], v[94:97]
	v_mfma_f32_16x16x32_bf16 v[90:93], v[38:41], v[240:243], v[90:93]
	v_mfma_f32_16x16x32_bf16 v[134:137], v[146:149], v[212:215], v[134:137]
	v_mfma_f32_16x16x32_bf16 v[130:133], v[178:181], v[212:215], v[130:133]
	v_mfma_f32_16x16x32_bf16 v[118:121], v[146:149], v[220:223], v[118:121]
	v_mfma_f32_16x16x32_bf16 v[114:117], v[178:181], v[220:223], v[114:117]
	v_mfma_f32_16x16x32_bf16 v[102:105], v[146:149], v[228:231], v[102:105]
	v_mfma_f32_16x16x32_bf16 v[98:101], v[178:181], v[228:231], v[98:101]
	v_mfma_f32_16x16x32_bf16 v[86:89], v[146:149], v[236:239], v[86:89]
	v_mfma_f32_16x16x32_bf16 v[82:85], v[178:181], v[236:239], v[82:85]
	v_mfma_f32_16x16x32_bf16 v[134:137], v[174:177], v[216:219], v[134:137]
	v_mfma_f32_16x16x32_bf16 v[130:133], v[182:185], v[216:219], v[130:133]
	v_mfma_f32_16x16x32_bf16 v[118:121], v[174:177], v[224:227], v[118:121]
	v_mfma_f32_16x16x32_bf16 v[114:117], v[182:185], v[224:227], v[114:117]
	v_mfma_f32_16x16x32_bf16 v[102:105], v[174:177], v[232:235], v[102:105]
	v_mfma_f32_16x16x32_bf16 v[98:101], v[182:185], v[232:235], v[98:101]
	v_mfma_f32_16x16x32_bf16 v[86:89], v[174:177], v[240:243], v[86:89]
	v_mfma_f32_16x16x32_bf16 v[82:85], v[182:185], v[240:243], v[82:85]
	s_barrier
	s_mov_b32 m0, s69
	v_lshl_add_u64 v[244:245], s[10:11], 0, v[152:153]
	s_add_u32 s54, s10, 0x40000
	ds_read_b128 v[212:215], v189 offset:16384
	ds_read_b128 v[216:219], v189 offset:17408
	ds_read_b128 v[220:223], v189 offset:18432
	ds_read_b128 v[224:227], v189 offset:19456
	ds_read_b128 v[228:231], v189 offset:20480
	ds_read_b128 v[232:235], v189 offset:21504
	ds_read_b128 v[236:239], v189 offset:22528
	ds_read_b128 v[240:243], v189 offset:23552
	global_load_lds_dwordx4 v[244:245], off
	v_lshl_add_u64 v[246:247], s[10:11], 0, v[156:157]
	s_mov_b32 m0, s70
	s_addc_u32 s55, s11, 0
	global_load_lds_dwordx4 v[246:247], off
	v_lshl_add_u64 v[248:249], s[54:55], 0, v[152:153]
	s_mov_b32 m0, s71
	v_lshl_add_u64 v[250:251], s[12:13], 0, v[154:155]
	global_load_lds_dwordx4 v[248:249], off
	v_lshl_add_u64 v[248:249], s[54:55], 0, v[156:157]
	s_mov_b32 m0, s72
	s_nop 0
	global_load_lds_dwordx4 v[248:249], off
	v_lshl_add_u64 v[248:249], s[12:13], 0, v[150:151]
	s_mov_b32 m0, s73
	s_nop 0
	global_load_lds_dwordx4 v[248:249], off
	s_mov_b32 m0, s74
	s_nop 0
	global_load_lds_dwordx4 v[250:251], off
	s_cmp_lg_u32 s98, 0
	s_cbranch_scc1 .Lfi_b_2
	s_waitcnt vmcnt(8)
.Lfi_b_2:
	s_mov_b32 s98, 0
	s_waitcnt lgkmcnt(0)
	s_barrier
	v_mfma_f32_16x16x32_bf16 v[78:81], v[10:13], v[212:215], v[78:81]
	v_mfma_f32_16x16x32_bf16 v[74:77], v[34:37], v[212:215], v[74:77]
	v_mfma_f32_16x16x32_bf16 v[62:65], v[10:13], v[220:223], v[62:65]
	v_mfma_f32_16x16x32_bf16 v[58:61], v[34:37], v[220:223], v[58:61]
	v_mfma_f32_16x16x32_bf16 v[46:49], v[10:13], v[228:231], v[46:49]
	v_mfma_f32_16x16x32_bf16 v[42:45], v[34:37], v[228:231], v[42:45]
	v_mfma_f32_16x16x32_bf16 v[10:13], v[10:13], v[236:239], v[22:25]
	v_mfma_f32_16x16x32_bf16 v[78:81], v[14:17], v[216:219], v[78:81]
	v_mfma_f32_16x16x32_bf16 v[74:77], v[38:41], v[216:219], v[74:77]
	v_mfma_f32_16x16x32_bf16 v[62:65], v[14:17], v[224:227], v[62:65]
	v_mfma_f32_16x16x32_bf16 v[58:61], v[38:41], v[224:227], v[58:61]
	v_mfma_f32_16x16x32_bf16 v[46:49], v[14:17], v[232:235], v[46:49]
	v_mfma_f32_16x16x32_bf16 v[42:45], v[38:41], v[232:235], v[42:45]
	v_mfma_f32_16x16x32_bf16 v[10:13], v[14:17], v[240:243], v[10:13]
	v_mfma_f32_16x16x32_bf16 v[14:17], v[34:37], v[236:239], v[18:21]
	v_mfma_f32_16x16x32_bf16 v[14:17], v[38:41], v[240:243], v[14:17]
	v_mfma_f32_16x16x32_bf16 v[18:21], v[146:149], v[212:215], v[70:73]
	v_mfma_f32_16x16x32_bf16 v[34:37], v[174:177], v[216:219], v[18:21]
	v_mfma_f32_16x16x32_bf16 v[18:21], v[178:181], v[212:215], v[66:69]
	v_mfma_f32_16x16x32_bf16 v[38:41], v[182:185], v[216:219], v[18:21]
	v_mfma_f32_16x16x32_bf16 v[18:21], v[146:149], v[220:223], v[54:57]
	v_mfma_f32_16x16x32_bf16 v[54:57], v[174:177], v[224:227], v[18:21]
	v_mfma_f32_16x16x32_bf16 v[18:21], v[178:181], v[220:223], v[50:53]
	v_mfma_f32_16x16x32_bf16 v[50:53], v[182:185], v[224:227], v[18:21]
	v_mfma_f32_16x16x32_bf16 v[18:21], v[146:149], v[228:231], v[30:33]
	v_mfma_f32_16x16x32_bf16 v[30:33], v[174:177], v[232:235], v[18:21]
	v_mfma_f32_16x16x32_bf16 v[18:21], v[178:181], v[228:231], v[26:29]
	v_mfma_f32_16x16x32_bf16 v[6:9], v[146:149], v[236:239], v[6:9]
	v_mfma_f32_16x16x32_bf16 v[2:5], v[178:181], v[236:239], v[2:5]
	v_mfma_f32_16x16x32_bf16 v[26:29], v[182:185], v[232:235], v[18:21]
	v_mfma_f32_16x16x32_bf16 v[6:9], v[174:177], v[240:243], v[6:9]
	v_mfma_f32_16x16x32_bf16 v[2:5], v[182:185], v[240:243], v[2:5]
	s_barrier
; #define PG8_STAGE(bufoff, gbase, voff) do { _Pragma("unroll") for (int _i = 0; _i < 2; ++_i) \
;         __builtin_amdgcn_global_load_lds((const unsigned*)((const char*)(gbase) + (voff)[_i]), (PG8_LAS unsigned*)(lds + (bufoff) + ldsw + _i * 8192), 16, 0, 0); } while (0)
; #define PG8_LDA(dst, b, h) do { _Pragma("unroll") for (int m = 0; m < 4; ++m) _Pragma("unroll") for (int k = 0; k < 2; ++k) dst[m][k] = *(const PG8_LAS bf16x8*)(lds + PG8_SA(b, h) + aoff + m * 2048 + k * 1024); } while (0)
; #define PG8_LDB(dst, b, h) do { _Pragma("unroll") for (int n = 0; n < 2; ++n) _Pragma("unroll") for (int k = 0; k < 2; ++k) dst[n][k] = *(const PG8_LAS bf16x8*)(lds + PG8_SB(b, h) + boff + n * 2048 + k * 1024); } while (0)
; #define PG8_MMA(ai, bj, At, Bt) do { __builtin_amdgcn_s_setprio(1); _Pragma("unroll") for (int m = 0; m < 4; ++m) _Pragma("unroll") for (int n = 0; n < 2; ++n) _Pragma("unroll") for (int k = 0; k < 2; ++k) \
;         acc[ai][bj][m][n] = __builtin_amdgcn_mfma_f32_16x16x32_bf16(Bt[n][k], At[m][k], acc[ai][bj][m][n], 0, 0, 0); __builtin_amdgcn_s_setprio(0); } while (0)
; #define PG8_WAIT_V(n) asm volatile("s_waitcnt vmcnt(" #n ")" ::: "memory")
; #define PG8_WAIT_L(n) do { asm volatile("s_waitcnt lgkmcnt(" #n ")" ::: "memory"); __builtin_amdgcn_s_waitcnt(0xC07F); } while (0)
; #define PG8_BAR __builtin_amdgcn_s_barrier()
; #define PG8_SCHED __builtin_amdgcn_sched_barrier(0)
; template <class Epi, class Sched, bool SEG3 = false>
; __device__ __forceinline__ void gemm_phase(PG8_LAS unsigned char* lds, const Gemm g, const Sched& S, const Epi& E) {
;     ...
;             PG8_LDB(B0, 1, 0); PG8_LDB(B1, 1, 1); PG8_SCHED; PG8_LDA(At, 1, 0); PG8_STAGE(PG8_SA(0, 1), a2 + hsA, voffA);
;             PG8_WAIT_V(8); PG8_WAIT_L(0); PG8_BAR; if (cur.half != 1) { PG8_MMA(0, 0, At, B0); PG8_MMA(0, 1, At, B1); } PG8_BAR; PG8_SCHED;
;             PG8_LDA(At, 1, 1); PG8_STAGE(PG8_SB(1, 0), b3, voffB); PG8_STAGE(PG8_SB(1, 1), b3 + hsB, voffB); PG8_STAGE(PG8_SA(1, 0), a3, voffA);
;             PG8_WAIT_V(8); PG8_WAIT_L(0); PG8_BAR; if (cur.half != 0) { PG8_MMA(1, 0, At, B0); PG8_MMA(1, 1, At, B1); } PG8_BAR; PG8_SCHED;
;         }
	s_nop 0
	ds_read_b128 v[18:21], v190
	ds_read_b128 v[22:25], v190 offset:1024
	ds_read_b128 v[66:69], v190 offset:2048
	ds_read_b128 v[70:73], v190 offset:3072
	ds_read_b128 v[146:149], v191
	ds_read_b128 v[174:177], v191 offset:1024
	ds_read_b128 v[178:181], v191 offset:2048
	ds_read_b128 v[182:185], v191 offset:3072
	s_add_u32 s12, s12, 0x40000
	s_addc_u32 s13, s13, 0
	s_mov_b32 m0, s75
	v_lshl_add_u64 v[252:253], s[12:13], 0, v[150:151]
	ds_read_b128 v[212:215], v189 offset:32768
	ds_read_b128 v[216:219], v189 offset:33792
	ds_read_b128 v[220:223], v189 offset:34816
	ds_read_b128 v[224:227], v189 offset:35840
	ds_read_b128 v[228:231], v189 offset:36864
	ds_read_b128 v[232:235], v189 offset:37888
	ds_read_b128 v[236:239], v189 offset:38912
	ds_read_b128 v[240:243], v189 offset:39936
	global_load_lds_dwordx4 v[252:253], off
	v_lshl_add_u64 v[252:253], s[12:13], 0, v[154:155]
	s_mov_b32 m0, s76
	s_nop 0
	global_load_lds_dwordx4 v[252:253], off
	s_waitcnt vmcnt(8)
	s_waitcnt lgkmcnt(0)
	s_waitcnt lgkmcnt(0)
	s_barrier
	v_mfma_f32_16x16x32_bf16 v[142:145], v[18:21], v[212:215], v[142:145]
	v_mfma_f32_16x16x32_bf16 v[138:141], v[66:69], v[212:215], v[138:141]
	v_mfma_f32_16x16x32_bf16 v[126:129], v[18:21], v[220:223], v[126:129]
	v_mfma_f32_16x16x32_bf16 v[122:125], v[66:69], v[220:223], v[122:125]
	v_mfma_f32_16x16x32_bf16 v[110:113], v[18:21], v[228:231], v[110:113]
	v_mfma_f32_16x16x32_bf16 v[106:109], v[66:69], v[228:231], v[106:109]
	v_mfma_f32_16x16x32_bf16 v[94:97], v[18:21], v[236:239], v[94:97]
	v_mfma_f32_16x16x32_bf16 v[90:93], v[66:69], v[236:239], v[90:93]
	v_mfma_f32_16x16x32_bf16 v[142:145], v[22:25], v[216:219], v[142:145]
	v_mfma_f32_16x16x32_bf16 v[138:141], v[70:73], v[216:219], v[138:141]
	v_mfma_f32_16x16x32_bf16 v[126:129], v[22:25], v[224:227], v[126:129]
	v_mfma_f32_16x16x32_bf16 v[122:125], v[70:73], v[224:227], v[122:125]
	v_mfma_f32_16x16x32_bf16 v[110:113], v[22:25], v[232:235], v[110:113]
	v_mfma_f32_16x16x32_bf16 v[106:109], v[70:73], v[232:235], v[106:109]
	v_mfma_f32_16x16x32_bf16 v[94:97], v[22:25], v[240:243], v[94:97]
	v_mfma_f32_16x16x32_bf16 v[90:93], v[70:73], v[240:243], v[90:93]
	v_mfma_f32_16x16x32_bf16 v[134:137], v[146:149], v[212:215], v[134:137]
	v_mfma_f32_16x16x32_bf16 v[130:133], v[178:181], v[212:215], v[130:133]
	v_mfma_f32_16x16x32_bf16 v[118:121], v[146:149], v[220:223], v[118:121]
	v_mfma_f32_16x16x32_bf16 v[114:117], v[178:181], v[220:223], v[114:117]
	v_mfma_f32_16x16x32_bf16 v[102:105], v[146:149], v[228:231], v[102:105]
	v_mfma_f32_16x16x32_bf16 v[98:101], v[178:181], v[228:231], v[98:101]
	v_mfma_f32_16x16x32_bf16 v[86:89], v[146:149], v[236:239], v[86:89]
	v_mfma_f32_16x16x32_bf16 v[82:85], v[178:181], v[236:239], v[82:85]
	v_mfma_f32_16x16x32_bf16 v[134:137], v[174:177], v[216:219], v[134:137]
	v_mfma_f32_16x16x32_bf16 v[130:133], v[182:185], v[216:219], v[130:133]
	v_mfma_f32_16x16x32_bf16 v[118:121], v[174:177], v[224:227], v[118:121]
	v_mfma_f32_16x16x32_bf16 v[114:117], v[182:185], v[224:227], v[114:117]
	v_mfma_f32_16x16x32_bf16 v[102:105], v[174:177], v[232:235], v[102:105]
	v_mfma_f32_16x16x32_bf16 v[98:101], v[182:185], v[232:235], v[98:101]
	v_mfma_f32_16x16x32_bf16 v[86:89], v[174:177], v[240:243], v[86:89]
	v_mfma_f32_16x16x32_bf16 v[82:85], v[182:185], v[240:243], v[82:85]
	s_barrier
	s_mov_b32 m0, s79
	v_lshl_add_u64 v[244:245], v[244:245], 0, s[30:31]
	s_add_u32 s10, s10, 0x40080
	ds_read_b128 v[212:215], v189 offset:49152
	ds_read_b128 v[216:219], v189 offset:50176
	ds_read_b128 v[220:223], v189 offset:51200
	ds_read_b128 v[224:227], v189 offset:52224
	ds_read_b128 v[228:231], v189 offset:53248
	ds_read_b128 v[232:235], v189 offset:54272
	ds_read_b128 v[236:239], v189 offset:55296
	ds_read_b128 v[240:243], v189 offset:56320
	global_load_lds_dwordx4 v[244:245], off
	v_lshl_add_u64 v[244:245], v[246:247], 0, s[30:31]
	s_mov_b32 m0, s80
	s_addc_u32 s11, s11, 0
	global_load_lds_dwordx4 v[244:245], off
	v_lshl_add_u64 v[244:245], s[10:11], 0, v[152:153]
	s_mov_b32 m0, s84
	s_nop 0
	global_load_lds_dwordx4 v[244:245], off
	v_lshl_add_u64 v[244:245], s[10:11], 0, v[156:157]
	s_mov_b32 m0, s85
	s_nop 0
	global_load_lds_dwordx4 v[244:245], off
	v_lshl_add_u64 v[244:245], v[248:249], 0, s[30:31]
	s_mov_b32 m0, s82
	s_nop 0
	global_load_lds_dwordx4 v[244:245], off
	v_lshl_add_u64 v[244:245], v[250:251], 0, s[30:31]
	s_mov_b32 m0, s83
	s_nop 0
	global_load_lds_dwordx4 v[244:245], off
	s_waitcnt vmcnt(8)
	s_waitcnt lgkmcnt(0)
	s_waitcnt lgkmcnt(0)
	s_barrier
	v_mfma_f32_16x16x32_bf16 v[78:81], v[18:21], v[212:215], v[78:81]
	v_mfma_f32_16x16x32_bf16 v[62:65], v[18:21], v[220:223], v[62:65]
	v_mfma_f32_16x16x32_bf16 v[46:49], v[18:21], v[228:231], v[46:49]
	v_mfma_f32_16x16x32_bf16 v[10:13], v[18:21], v[236:239], v[10:13]
	v_mfma_f32_16x16x32_bf16 v[78:81], v[22:25], v[216:219], v[78:81]
	v_mfma_f32_16x16x32_bf16 v[74:77], v[66:69], v[212:215], v[74:77]
	v_mfma_f32_16x16x32_bf16 v[62:65], v[22:25], v[224:227], v[62:65]
	v_mfma_f32_16x16x32_bf16 v[58:61], v[66:69], v[220:223], v[58:61]
	v_mfma_f32_16x16x32_bf16 v[46:49], v[22:25], v[232:235], v[46:49]
	v_mfma_f32_16x16x32_bf16 v[42:45], v[66:69], v[228:231], v[42:45]
	v_mfma_f32_16x16x32_bf16 v[22:25], v[22:25], v[240:243], v[10:13]
	v_mfma_f32_16x16x32_bf16 v[10:13], v[66:69], v[236:239], v[14:17]
	v_mfma_f32_16x16x32_bf16 v[74:77], v[70:73], v[216:219], v[74:77]
	v_mfma_f32_16x16x32_bf16 v[58:61], v[70:73], v[224:227], v[58:61]
	v_mfma_f32_16x16x32_bf16 v[42:45], v[70:73], v[232:235], v[42:45]
	v_mfma_f32_16x16x32_bf16 v[18:21], v[70:73], v[240:243], v[10:13]
	v_mfma_f32_16x16x32_bf16 v[10:13], v[146:149], v[212:215], v[34:37]
	v_mfma_f32_16x16x32_bf16 v[70:73], v[174:177], v[216:219], v[10:13]
	v_mfma_f32_16x16x32_bf16 v[10:13], v[178:181], v[212:215], v[38:41]
	v_mfma_f32_16x16x32_bf16 v[66:69], v[182:185], v[216:219], v[10:13]
	v_mfma_f32_16x16x32_bf16 v[10:13], v[146:149], v[220:223], v[54:57]
	v_mfma_f32_16x16x32_bf16 v[54:57], v[174:177], v[224:227], v[10:13]
	v_mfma_f32_16x16x32_bf16 v[10:13], v[178:181], v[220:223], v[50:53]
	v_mfma_f32_16x16x32_bf16 v[50:53], v[182:185], v[224:227], v[10:13]
	v_mfma_f32_16x16x32_bf16 v[10:13], v[146:149], v[228:231], v[30:33]
	v_mfma_f32_16x16x32_bf16 v[30:33], v[174:177], v[232:235], v[10:13]
	v_mfma_f32_16x16x32_bf16 v[10:13], v[178:181], v[228:231], v[26:29]
	v_mfma_f32_16x16x32_bf16 v[6:9], v[146:149], v[236:239], v[6:9]
	v_mfma_f32_16x16x32_bf16 v[2:5], v[178:181], v[236:239], v[2:5]
	v_mfma_f32_16x16x32_bf16 v[26:29], v[182:185], v[232:235], v[10:13]
	v_mfma_f32_16x16x32_bf16 v[6:9], v[174:177], v[240:243], v[6:9]
	v_mfma_f32_16x16x32_bf16 v[2:5], v[182:185], v[240:243], v[2:5]
	s_barrier
	s_add_u32 s8, s8, 0x100
	s_addc_u32 s9, s9, 0
	s_add_u32 s17, s17, 0x100
	s_addc_u32 s19, s19, 0
	s_cmp_ge_i32 s20, s77
	s_mov_b32 s10, s20
	s_cbranch_scc0 .LBB0_655
	s_and_b64 vcc, exec, s[36:37]
	s_cbranch_vccz .LBB0_658

; #define PG8_STAGE(bufoff, gbase, voff) do { _Pragma("unroll") for (int _i = 0; _i < 2; ++_i) \
;         __builtin_amdgcn_global_load_lds((const unsigned*)((const char*)(gbase) + (voff)[_i]), (PG8_LAS unsigned*)(lds + (bufoff) + ldsw + _i * 8192), 16, 0, 0); } while (0)
; #define PG8_LDA(dst, b, h) do { _Pragma("unroll") for (int m = 0; m < 4; ++m) _Pragma("unroll") for (int k = 0; k < 2; ++k) dst[m][k] = *(const PG8_LAS bf16x8*)(lds + PG8_SA(b, h) + aoff + m * 2048 + k * 1024); } while (0)
; #define PG8_MMA(ai, bj, At, Bt) do { __builtin_amdgcn_s_setprio(1); _Pragma("unroll") for (int m = 0; m < 4; ++m) _Pragma("unroll") for (int n = 0; n < 2; ++n) _Pragma("unroll") for (int k = 0; k < 2; ++k) \
;         acc[ai][bj][m][n] = __builtin_amdgcn_mfma_f32_16x16x32_bf16(Bt[n][k], At[m][k], acc[ai][bj][m][n], 0, 0, 0); __builtin_amdgcn_s_setprio(0); } while (0)
; #define PG8_WAIT_V(n) asm volatile("s_waitcnt vmcnt(" #n ")" ::: "memory")
; #define PG8_WAIT_L(n) do { asm volatile("s_waitcnt lgkmcnt(" #n ")" ::: "memory"); __builtin_amdgcn_s_waitcnt(0xC07F); } while (0)
; #define PG8_BAR __builtin_amdgcn_s_barrier()
; #define PG8_SCHED __builtin_amdgcn_sched_barrier(0)
; template <class Epi, class Sched, bool SEG3 = false>
; __device__ __forceinline__ void gemm_phase(PG8_LAS unsigned char* lds, const Gemm g, const Sched& S, const Epi& E) {
;     ...
;             PG8_WAIT_V(8); PG8_WAIT_L(0); PG8_BAR; if (cur.half != 1) { PG8_MMA(0, 0, At, B0); PG8_MMA(0, 1, At, B1); } PG8_BAR; PG8_SCHED;
;             PG8_LDA(At, 0, 1); PG8_STAGE(PG8_SB(0, 0), b2, voffB); PG8_STAGE(PG8_SB(0, 1), b2 + hsB, voffB); PG8_STAGE(PG8_SA(0, 0), a2, voffA);
;             PG8_WAIT_V(8); PG8_WAIT_L(0); PG8_BAR; if (cur.half != 0) { PG8_MMA(1, 0, At, B0); PG8_MMA(1, 1, At, B1); } PG8_BAR; PG8_SCHED;
.Lfi_a_3:
	s_waitcnt lgkmcnt(0)
	s_barrier
	v_mfma_f32_16x16x32_bf16 v[136:139], v[124:127], v[164:167], v[136:139]
	v_mfma_f32_16x16x32_bf16 v[128:131], v[140:143], v[164:167], v[128:131]
	v_mfma_f32_16x16x32_bf16 v[112:115], v[124:127], v[172:175], v[112:115]
	v_mfma_f32_16x16x32_bf16 v[108:111], v[140:143], v[172:175], v[108:111]
	v_mfma_f32_16x16x32_bf16 v[94:97], v[124:127], v[180:183], v[94:97]
	v_mfma_f32_16x16x32_bf16 v[90:93], v[140:143], v[180:183], v[90:93]
	v_mfma_f32_16x16x32_bf16 v[78:81], v[124:127], v[188:191], v[78:81]
	v_mfma_f32_16x16x32_bf16 v[74:77], v[140:143], v[188:191], v[74:77]
	v_mfma_f32_16x16x32_bf16 v[136:139], v[132:135], v[168:171], v[136:139]
	v_mfma_f32_16x16x32_bf16 v[128:131], v[144:147], v[168:171], v[128:131]
	v_mfma_f32_16x16x32_bf16 v[112:115], v[132:135], v[176:179], v[112:115]
	v_mfma_f32_16x16x32_bf16 v[108:111], v[144:147], v[176:179], v[108:111]
	v_mfma_f32_16x16x32_bf16 v[94:97], v[132:135], v[184:187], v[94:97]
	v_mfma_f32_16x16x32_bf16 v[90:93], v[144:147], v[184:187], v[90:93]
	v_mfma_f32_16x16x32_bf16 v[78:81], v[132:135], v[192:195], v[78:81]
	v_mfma_f32_16x16x32_bf16 v[74:77], v[144:147], v[192:195], v[74:77]
	v_mfma_f32_16x16x32_bf16 v[120:123], v[148:151], v[164:167], v[120:123]
	v_mfma_f32_16x16x32_bf16 v[116:119], v[156:159], v[164:167], v[116:119]
	v_mfma_f32_16x16x32_bf16 v[104:107], v[148:151], v[172:175], v[104:107]
	v_mfma_f32_16x16x32_bf16 v[98:101], v[156:159], v[172:175], v[100:103]
	v_mfma_f32_16x16x32_bf16 v[86:89], v[148:151], v[180:183], v[86:89]
	v_mfma_f32_16x16x32_bf16 v[82:85], v[156:159], v[180:183], v[82:85]
	v_mfma_f32_16x16x32_bf16 v[70:73], v[148:151], v[188:191], v[70:73]
	v_mfma_f32_16x16x32_bf16 v[66:69], v[156:159], v[188:191], v[66:69]
	v_mfma_f32_16x16x32_bf16 v[120:123], v[152:155], v[168:171], v[120:123]
	v_mfma_f32_16x16x32_bf16 v[116:119], v[160:163], v[168:171], v[116:119]
	v_mfma_f32_16x16x32_bf16 v[104:107], v[152:155], v[176:179], v[104:107]
	v_mfma_f32_16x16x32_bf16 v[98:101], v[160:163], v[176:179], v[98:101]
	v_mfma_f32_16x16x32_bf16 v[86:89], v[152:155], v[184:187], v[86:89]
	v_mfma_f32_16x16x32_bf16 v[82:85], v[160:163], v[184:187], v[82:85]
	v_mfma_f32_16x16x32_bf16 v[70:73], v[152:155], v[192:195], v[70:73]
	v_mfma_f32_16x16x32_bf16 v[66:69], v[160:163], v[192:195], v[66:69]
	s_barrier
	s_mov_b32 m0, s46
	v_lshl_add_u64 v[214:215], s[28:29], 0, v[198:199]
	s_add_u32 s66, s28, 0x40000
	ds_read_b128 v[164:167], v233 offset:16384
	ds_read_b128 v[168:171], v233 offset:17408
	ds_read_b128 v[172:175], v233 offset:18432
	ds_read_b128 v[176:179], v233 offset:19456
	ds_read_b128 v[180:183], v233 offset:20480
	ds_read_b128 v[184:187], v233 offset:21504
	ds_read_b128 v[188:191], v233 offset:22528
	ds_read_b128 v[192:195], v233 offset:23552
	global_load_lds_dwordx4 v[214:215], off
	v_lshl_add_u64 v[216:217], s[28:29], 0, v[202:203]
	s_mov_b32 m0, s47
	s_addc_u32 s67, s29, 0
	global_load_lds_dwordx4 v[216:217], off
	v_lshl_add_u64 v[102:103], s[66:67], 0, v[198:199]
	s_mov_b32 m0, s48
	v_lshl_add_u64 v[218:219], s[30:31], 0, v[196:197]
	global_load_lds_dwordx4 v[102:103], off
	v_lshl_add_u64 v[102:103], s[66:67], 0, v[202:203]
	s_mov_b32 m0, s49
	v_lshl_add_u64 v[220:221], s[30:31], 0, v[200:201]
	global_load_lds_dwordx4 v[102:103], off
	s_mov_b32 m0, s50
	s_nop 0
	global_load_lds_dwordx4 v[218:219], off
	s_mov_b32 m0, s51
	s_nop 0
	global_load_lds_dwordx4 v[220:221], off
	s_cmp_lg_u32 s98, 0
	s_cbranch_scc1 .Lfi_b_3
	s_waitcnt vmcnt(8)
.Lfi_b_3:
	s_mov_b32 s98, 0
	s_waitcnt lgkmcnt(0)
	s_barrier
	v_mfma_f32_16x16x32_bf16 v[62:65], v[124:127], v[164:167], v[62:65]
	v_mfma_f32_16x16x32_bf16 v[58:61], v[140:143], v[164:167], v[58:61]
	v_mfma_f32_16x16x32_bf16 v[46:49], v[124:127], v[172:175], v[46:49]
	v_mfma_f32_16x16x32_bf16 v[42:45], v[140:143], v[172:175], v[42:45]
	v_mfma_f32_16x16x32_bf16 v[30:33], v[124:127], v[180:183], v[30:33]
	v_mfma_f32_16x16x32_bf16 v[26:29], v[140:143], v[180:183], v[26:29]
	v_mfma_f32_16x16x32_bf16 v[14:17], v[124:127], v[188:191], v[14:17]
	v_mfma_f32_16x16x32_bf16 v[10:13], v[140:143], v[188:191], v[10:13]
	v_mfma_f32_16x16x32_bf16 v[62:65], v[132:135], v[168:171], v[62:65]
	v_mfma_f32_16x16x32_bf16 v[58:61], v[144:147], v[168:171], v[58:61]
	v_mfma_f32_16x16x32_bf16 v[46:49], v[132:135], v[176:179], v[46:49]
	v_mfma_f32_16x16x32_bf16 v[42:45], v[144:147], v[176:179], v[42:45]
	v_mfma_f32_16x16x32_bf16 v[30:33], v[132:135], v[184:187], v[30:33]
	v_mfma_f32_16x16x32_bf16 v[26:29], v[144:147], v[184:187], v[26:29]
	v_mfma_f32_16x16x32_bf16 v[14:17], v[132:135], v[192:195], v[14:17]
	v_mfma_f32_16x16x32_bf16 v[10:13], v[144:147], v[192:195], v[10:13]
	v_mfma_f32_16x16x32_bf16 v[54:57], v[148:151], v[164:167], v[54:57]
	v_mfma_f32_16x16x32_bf16 v[50:53], v[156:159], v[164:167], v[50:53]
	v_mfma_f32_16x16x32_bf16 v[38:41], v[148:151], v[172:175], v[38:41]
	v_mfma_f32_16x16x32_bf16 v[34:37], v[156:159], v[172:175], v[34:37]
	v_mfma_f32_16x16x32_bf16 v[22:25], v[148:151], v[180:183], v[22:25]
	v_mfma_f32_16x16x32_bf16 v[18:21], v[156:159], v[180:183], v[18:21]
	v_mfma_f32_16x16x32_bf16 v[6:9], v[148:151], v[188:191], v[6:9]
	v_mfma_f32_16x16x32_bf16 v[2:5], v[156:159], v[188:191], v[2:5]
	v_mfma_f32_16x16x32_bf16 v[54:57], v[152:155], v[168:171], v[54:57]
	v_mfma_f32_16x16x32_bf16 v[50:53], v[160:163], v[168:171], v[50:53]
	v_mfma_f32_16x16x32_bf16 v[38:41], v[152:155], v[176:179], v[38:41]
	v_mfma_f32_16x16x32_bf16 v[34:37], v[160:163], v[176:179], v[34:37]
	v_mfma_f32_16x16x32_bf16 v[22:25], v[152:155], v[184:187], v[22:25]
	v_mfma_f32_16x16x32_bf16 v[18:21], v[160:163], v[184:187], v[18:21]
	v_mfma_f32_16x16x32_bf16 v[6:9], v[152:155], v[192:195], v[6:9]
	v_mfma_f32_16x16x32_bf16 v[2:5], v[160:163], v[192:195], v[2:5]
	s_barrier
; #define PG8_STAGE(bufoff, gbase, voff) do { _Pragma("unroll") for (int _i = 0; _i < 2; ++_i) \
;         __builtin_amdgcn_global_load_lds((const unsigned*)((const char*)(gbase) + (voff)[_i]), (PG8_LAS unsigned*)(lds + (bufoff) + ldsw + _i * 8192), 16, 0, 0); } while (0)
; #define PG8_LDA(dst, b, h) do { _Pragma("unroll") for (int m = 0; m < 4; ++m) _Pragma("unroll") for (int k = 0; k < 2; ++k) dst[m][k] = *(const PG8_LAS bf16x8*)(lds + PG8_SA(b, h) + aoff + m * 2048 + k * 1024); } while (0)
; #define PG8_LDB(dst, b, h) do { _Pragma("unroll") for (int n = 0; n < 2; ++n) _Pragma("unroll") for (int k = 0; k < 2; ++k) dst[n][k] = *(const PG8_LAS bf16x8*)(lds + PG8_SB(b, h) + boff + n * 2048 + k * 1024); } while (0)
; #define PG8_MMA(ai, bj, At, Bt) do { __builtin_amdgcn_s_setprio(1); _Pragma("unroll") for (int m = 0; m < 4; ++m) _Pragma("unroll") for (int n = 0; n < 2; ++n) _Pragma("unroll") for (int k = 0; k < 2; ++k) \
;         acc[ai][bj][m][n] = __builtin_amdgcn_mfma_f32_16x16x32_bf16(Bt[n][k], At[m][k], acc[ai][bj][m][n], 0, 0, 0); __builtin_amdgcn_s_setprio(0); } while (0)
; #define PG8_WAIT_V(n) asm volatile("s_waitcnt vmcnt(" #n ")" ::: "memory")
; #define PG8_WAIT_L(n) do { asm volatile("s_waitcnt lgkmcnt(" #n ")" ::: "memory"); __builtin_amdgcn_s_waitcnt(0xC07F); } while (0)
; #define PG8_BAR __builtin_amdgcn_s_barrier()
; #define PG8_SCHED __builtin_amdgcn_sched_barrier(0)
; template <class Epi, class Sched, bool SEG3 = false>
; __device__ __forceinline__ void gemm_phase(PG8_LAS unsigned char* lds, const Gemm g, const Sched& S, const Epi& E) {
;     ...
;             PG8_LDB(B0, 1, 0); PG8_LDB(B1, 1, 1); PG8_SCHED; PG8_LDA(At, 1, 0); PG8_STAGE(PG8_SA(0, 1), a2 + hsA, voffA);
;             PG8_WAIT_V(8); PG8_WAIT_L(0); PG8_BAR; if (cur.half != 1) { PG8_MMA(0, 0, At, B0); PG8_MMA(0, 1, At, B1); } PG8_BAR; PG8_SCHED;
;             PG8_LDA(At, 1, 1); PG8_STAGE(PG8_SB(1, 0), b3, voffB); PG8_STAGE(PG8_SB(1, 1), b3 + hsB, voffB); PG8_STAGE(PG8_SA(1, 0), a3, voffA);
;             PG8_WAIT_V(8); PG8_WAIT_L(0); PG8_BAR; if (cur.half != 0) { PG8_MMA(1, 0, At, B0); PG8_MMA(1, 1, At, B1); } PG8_BAR; PG8_SCHED;
;         }
	ds_read_b128 v[124:127], v234
	ds_read_b128 v[132:135], v234 offset:1024
	ds_read_b128 v[140:143], v234 offset:2048
	ds_read_b128 v[144:147], v234 offset:3072
	ds_read_b128 v[148:151], v235
	ds_read_b128 v[152:155], v235 offset:1024
	ds_read_b128 v[156:159], v235 offset:2048
	ds_read_b128 v[160:163], v235 offset:3072
	s_add_u32 s30, s30, 0x40000
	s_addc_u32 s31, s31, 0
	s_mov_b32 m0, s52
	v_lshl_add_u64 v[102:103], s[30:31], 0, v[196:197]
	ds_read_b128 v[164:167], v233 offset:32768
	ds_read_b128 v[168:171], v233 offset:33792
	ds_read_b128 v[172:175], v233 offset:34816
	ds_read_b128 v[176:179], v233 offset:35840
	ds_read_b128 v[180:183], v233 offset:36864
	ds_read_b128 v[184:187], v233 offset:37888
	ds_read_b128 v[188:191], v233 offset:38912
	ds_read_b128 v[192:195], v233 offset:39936
	global_load_lds_dwordx4 v[102:103], off
	v_lshl_add_u64 v[102:103], s[30:31], 0, v[200:201]
	s_mov_b32 m0, s53
	s_nop 0
	global_load_lds_dwordx4 v[102:103], off
	s_waitcnt vmcnt(8)
	s_waitcnt lgkmcnt(0)
	s_waitcnt lgkmcnt(0)
	s_barrier
	v_mfma_f32_16x16x32_bf16 v[136:139], v[124:127], v[164:167], v[136:139]
	v_mfma_f32_16x16x32_bf16 v[128:131], v[140:143], v[164:167], v[128:131]
	v_mfma_f32_16x16x32_bf16 v[112:115], v[124:127], v[172:175], v[112:115]
	v_mfma_f32_16x16x32_bf16 v[108:111], v[140:143], v[172:175], v[108:111]
	v_mfma_f32_16x16x32_bf16 v[94:97], v[124:127], v[180:183], v[94:97]
	v_mfma_f32_16x16x32_bf16 v[90:93], v[140:143], v[180:183], v[90:93]
	v_mfma_f32_16x16x32_bf16 v[78:81], v[124:127], v[188:191], v[78:81]
	v_mfma_f32_16x16x32_bf16 v[74:77], v[140:143], v[188:191], v[74:77]
	v_mfma_f32_16x16x32_bf16 v[136:139], v[132:135], v[168:171], v[136:139]
	v_mfma_f32_16x16x32_bf16 v[128:131], v[144:147], v[168:171], v[128:131]
	v_mfma_f32_16x16x32_bf16 v[112:115], v[132:135], v[176:179], v[112:115]
	v_mfma_f32_16x16x32_bf16 v[108:111], v[144:147], v[176:179], v[108:111]
	v_mfma_f32_16x16x32_bf16 v[94:97], v[132:135], v[184:187], v[94:97]
	v_mfma_f32_16x16x32_bf16 v[90:93], v[144:147], v[184:187], v[90:93]
	v_mfma_f32_16x16x32_bf16 v[78:81], v[132:135], v[192:195], v[78:81]
	v_mfma_f32_16x16x32_bf16 v[74:77], v[144:147], v[192:195], v[74:77]
	v_mfma_f32_16x16x32_bf16 v[120:123], v[148:151], v[164:167], v[120:123]
	v_mfma_f32_16x16x32_bf16 v[116:119], v[156:159], v[164:167], v[116:119]
	v_mfma_f32_16x16x32_bf16 v[102:105], v[148:151], v[172:175], v[104:107]
	v_mfma_f32_16x16x32_bf16 v[98:101], v[156:159], v[172:175], v[98:101]
	v_mfma_f32_16x16x32_bf16 v[86:89], v[148:151], v[180:183], v[86:89]
	v_mfma_f32_16x16x32_bf16 v[82:85], v[156:159], v[180:183], v[82:85]
	v_mfma_f32_16x16x32_bf16 v[70:73], v[148:151], v[188:191], v[70:73]
	v_mfma_f32_16x16x32_bf16 v[66:69], v[156:159], v[188:191], v[66:69]
	v_mfma_f32_16x16x32_bf16 v[120:123], v[152:155], v[168:171], v[120:123]
	v_mfma_f32_16x16x32_bf16 v[116:119], v[160:163], v[168:171], v[116:119]
	v_mfma_f32_16x16x32_bf16 v[104:107], v[152:155], v[176:179], v[102:105]
	v_mfma_f32_16x16x32_bf16 v[100:103], v[160:163], v[176:179], v[98:101]
	v_mfma_f32_16x16x32_bf16 v[86:89], v[152:155], v[184:187], v[86:89]
	v_mfma_f32_16x16x32_bf16 v[82:85], v[160:163], v[184:187], v[82:85]
	v_mfma_f32_16x16x32_bf16 v[70:73], v[152:155], v[192:195], v[70:73]
	v_mfma_f32_16x16x32_bf16 v[66:69], v[160:163], v[192:195], v[66:69]
	s_barrier
	s_mov_b32 m0, s55
	v_lshl_add_u64 v[98:99], v[214:215], 0, s[12:13]
	s_add_u32 s28, s28, 0x40080
	ds_read_b128 v[164:167], v233 offset:49152
	ds_read_b128 v[168:171], v233 offset:50176
	ds_read_b128 v[172:175], v233 offset:51200
	ds_read_b128 v[176:179], v233 offset:52224
	ds_read_b128 v[180:183], v233 offset:53248
	ds_read_b128 v[184:187], v233 offset:54272
	ds_read_b128 v[188:191], v233 offset:55296
	ds_read_b128 v[192:195], v233 offset:56320
	global_load_lds_dwordx4 v[98:99], off
	v_lshl_add_u64 v[98:99], v[216:217], 0, s[12:13]
	s_mov_b32 m0, s56
	s_addc_u32 s29, s29, 0
	global_load_lds_dwordx4 v[98:99], off
	v_lshl_add_u64 v[98:99], s[28:29], 0, v[198:199]
	s_mov_b32 m0, s59
	s_nop 0
	global_load_lds_dwordx4 v[98:99], off
	v_lshl_add_u64 v[98:99], s[28:29], 0, v[202:203]
	s_mov_b32 m0, s60
	s_nop 0
	global_load_lds_dwordx4 v[98:99], off
	v_lshl_add_u64 v[98:99], v[218:219], 0, s[12:13]
	s_mov_b32 m0, s57
	s_nop 0
	global_load_lds_dwordx4 v[98:99], off
	v_lshl_add_u64 v[98:99], v[220:221], 0, s[12:13]
	s_mov_b32 m0, s58
	s_nop 0
	global_load_lds_dwordx4 v[98:99], off
	s_waitcnt vmcnt(8)
	s_waitcnt lgkmcnt(0)
	s_waitcnt lgkmcnt(0)
	s_barrier
	v_mfma_f32_16x16x32_bf16 v[62:65], v[124:127], v[164:167], v[62:65]
	v_mfma_f32_16x16x32_bf16 v[58:61], v[140:143], v[164:167], v[58:61]
	v_mfma_f32_16x16x32_bf16 v[46:49], v[124:127], v[172:175], v[46:49]
	v_mfma_f32_16x16x32_bf16 v[42:45], v[140:143], v[172:175], v[42:45]
	v_mfma_f32_16x16x32_bf16 v[30:33], v[124:127], v[180:183], v[30:33]
	v_mfma_f32_16x16x32_bf16 v[26:29], v[140:143], v[180:183], v[26:29]
	v_mfma_f32_16x16x32_bf16 v[14:17], v[124:127], v[188:191], v[14:17]
	v_mfma_f32_16x16x32_bf16 v[10:13], v[140:143], v[188:191], v[10:13]
	v_mfma_f32_16x16x32_bf16 v[62:65], v[132:135], v[168:171], v[62:65]
	v_mfma_f32_16x16x32_bf16 v[58:61], v[144:147], v[168:171], v[58:61]
	v_mfma_f32_16x16x32_bf16 v[46:49], v[132:135], v[176:179], v[46:49]
	v_mfma_f32_16x16x32_bf16 v[42:45], v[144:147], v[176:179], v[42:45]
	v_mfma_f32_16x16x32_bf16 v[30:33], v[132:135], v[184:187], v[30:33]
	v_mfma_f32_16x16x32_bf16 v[26:29], v[144:147], v[184:187], v[26:29]
	v_mfma_f32_16x16x32_bf16 v[14:17], v[132:135], v[192:195], v[14:17]
	v_mfma_f32_16x16x32_bf16 v[10:13], v[144:147], v[192:195], v[10:13]
	v_mfma_f32_16x16x32_bf16 v[54:57], v[148:151], v[164:167], v[54:57]
	v_mfma_f32_16x16x32_bf16 v[50:53], v[156:159], v[164:167], v[50:53]
	v_mfma_f32_16x16x32_bf16 v[38:41], v[148:151], v[172:175], v[38:41]
	v_mfma_f32_16x16x32_bf16 v[34:37], v[156:159], v[172:175], v[34:37]
	v_mfma_f32_16x16x32_bf16 v[22:25], v[148:151], v[180:183], v[22:25]
	v_mfma_f32_16x16x32_bf16 v[18:21], v[156:159], v[180:183], v[18:21]
	v_mfma_f32_16x16x32_bf16 v[6:9], v[148:151], v[188:191], v[6:9]
	v_mfma_f32_16x16x32_bf16 v[2:5], v[156:159], v[188:191], v[2:5]
	v_mfma_f32_16x16x32_bf16 v[54:57], v[152:155], v[168:171], v[54:57]
	v_mfma_f32_16x16x32_bf16 v[50:53], v[160:163], v[168:171], v[50:53]
	v_mfma_f32_16x16x32_bf16 v[38:41], v[152:155], v[176:179], v[38:41]
	v_mfma_f32_16x16x32_bf16 v[34:37], v[160:163], v[176:179], v[34:37]
	v_mfma_f32_16x16x32_bf16 v[22:25], v[152:155], v[184:187], v[22:25]
	v_mfma_f32_16x16x32_bf16 v[18:21], v[160:163], v[184:187], v[18:21]
	v_mfma_f32_16x16x32_bf16 v[6:9], v[152:155], v[192:195], v[6:9]
	v_mfma_f32_16x16x32_bf16 v[2:5], v[160:163], v[192:195], v[2:5]
	s_barrier
	s_add_u32 s6, s6, 0x100
	s_addc_u32 s7, s7, 0
	s_add_u32 s19, s19, 0x100
	s_addc_u32 s27, s27, 0
	s_cmp_ge_i32 s65, s25
	s_mov_b32 s28, s65
	s_cbranch_scc0 .LBB0_2007
	s_and_b64 vcc, exec, s[14:15]
	s_cbranch_vccz .LBB0_2010

; #define PG8_STAGE(bufoff, gbase, voff) do { _Pragma("unroll") for (int _i = 0; _i < 2; ++_i) \
;         __builtin_amdgcn_global_load_lds((const unsigned*)((const char*)(gbase) + (voff)[_i]), (PG8_LAS unsigned*)(lds + (bufoff) + ldsw + _i * 8192), 16, 0, 0); } while (0)
; #define PG8_LDA(dst, b, h) do { _Pragma("unroll") for (int m = 0; m < 4; ++m) _Pragma("unroll") for (int k = 0; k < 2; ++k) dst[m][k] = *(const PG8_LAS bf16x8*)(lds + PG8_SA(b, h) + aoff + m * 2048 + k * 1024); } while (0)
; #define PG8_MMA(ai, bj, At, Bt) do { __builtin_amdgcn_s_setprio(1); _Pragma("unroll") for (int m = 0; m < 4; ++m) _Pragma("unroll") for (int n = 0; n < 2; ++n) _Pragma("unroll") for (int k = 0; k < 2; ++k) \
;         acc[ai][bj][m][n] = __builtin_amdgcn_mfma_f32_16x16x32_bf16(Bt[n][k], At[m][k], acc[ai][bj][m][n], 0, 0, 0); __builtin_amdgcn_s_setprio(0); } while (0)
; #define PG8_WAIT_V(n) asm volatile("s_waitcnt vmcnt(" #n ")" ::: "memory")
; #define PG8_WAIT_L(n) do { asm volatile("s_waitcnt lgkmcnt(" #n ")" ::: "memory"); __builtin_amdgcn_s_waitcnt(0xC07F); } while (0)
; #define PG8_BAR __builtin_amdgcn_s_barrier()
; #define PG8_SCHED __builtin_amdgcn_sched_barrier(0)
; template <class Epi, class Sched, bool SEG3 = false>
; __device__ __forceinline__ void gemm_phase(PG8_LAS unsigned char* lds, const Gemm g, const Sched& S, const Epi& E) {
;     ...
;             PG8_WAIT_V(8); PG8_WAIT_L(0); PG8_BAR; if (cur.half != 1) { PG8_MMA(0, 0, At, B0); PG8_MMA(0, 1, At, B1); } PG8_BAR; PG8_SCHED;
;             PG8_LDA(At, 0, 1); PG8_STAGE(PG8_SB(0, 0), b2, voffB); PG8_STAGE(PG8_SB(0, 1), b2 + hsB, voffB); PG8_STAGE(PG8_SA(0, 0), a2, voffA);
;             PG8_WAIT_V(8); PG8_WAIT_L(0); PG8_BAR; if (cur.half != 0) { PG8_MMA(1, 0, At, B0); PG8_MMA(1, 1, At, B1); } PG8_BAR; PG8_SCHED;
.Lfi_a_4:
	s_waitcnt lgkmcnt(0)
	s_barrier
	v_mfma_f32_16x16x32_bf16 v[158:161], v[34:37], v[162:165], v[158:161]
	v_mfma_f32_16x16x32_bf16 v[154:157], v[42:45], v[162:165], v[154:157]
	v_mfma_f32_16x16x32_bf16 v[134:137], v[34:37], v[186:189], v[134:137]
	v_mfma_f32_16x16x32_bf16 v[130:133], v[42:45], v[186:189], v[130:133]
	v_mfma_f32_16x16x32_bf16 v[110:113], v[34:37], v[194:197], v[110:113]
	v_mfma_f32_16x16x32_bf16 v[106:109], v[42:45], v[194:197], v[106:109]
	v_mfma_f32_16x16x32_bf16 v[94:97], v[34:37], v[202:205], v[94:97]
	v_mfma_f32_16x16x32_bf16 v[90:93], v[42:45], v[202:205], v[90:93]
	v_mfma_f32_16x16x32_bf16 v[158:161], v[38:41], v[166:169], v[158:161]
	v_mfma_f32_16x16x32_bf16 v[154:157], v[46:49], v[166:169], v[154:157]
	v_mfma_f32_16x16x32_bf16 v[134:137], v[38:41], v[190:193], v[134:137]
	v_mfma_f32_16x16x32_bf16 v[130:133], v[46:49], v[190:193], v[130:133]
	v_mfma_f32_16x16x32_bf16 v[110:113], v[38:41], v[198:201], v[110:113]
	v_mfma_f32_16x16x32_bf16 v[106:109], v[46:49], v[198:201], v[106:109]
	v_mfma_f32_16x16x32_bf16 v[94:97], v[38:41], v[214:217], v[94:97]
	v_mfma_f32_16x16x32_bf16 v[90:93], v[46:49], v[214:217], v[90:93]
	v_mfma_f32_16x16x32_bf16 v[146:149], v[114:117], v[162:165], v[146:149]
	v_mfma_f32_16x16x32_bf16 v[142:145], v[138:141], v[162:165], v[142:145]
	v_mfma_f32_16x16x32_bf16 v[122:125], v[114:117], v[186:189], v[122:125]
	v_mfma_f32_16x16x32_bf16 v[118:121], v[138:141], v[186:189], v[118:121]
	v_mfma_f32_16x16x32_bf16 v[102:105], v[114:117], v[194:197], v[102:105]
	v_mfma_f32_16x16x32_bf16 v[98:101], v[138:141], v[194:197], v[98:101]
	v_mfma_f32_16x16x32_bf16 v[86:89], v[114:117], v[202:205], v[86:89]
	v_mfma_f32_16x16x32_bf16 v[82:85], v[138:141], v[202:205], v[82:85]
	v_mfma_f32_16x16x32_bf16 v[146:149], v[126:129], v[166:169], v[146:149]
	v_mfma_f32_16x16x32_bf16 v[142:145], v[150:153], v[166:169], v[142:145]
	v_mfma_f32_16x16x32_bf16 v[122:125], v[126:129], v[190:193], v[122:125]
	v_mfma_f32_16x16x32_bf16 v[118:121], v[150:153], v[190:193], v[118:121]
	v_mfma_f32_16x16x32_bf16 v[102:105], v[126:129], v[198:201], v[102:105]
	v_mfma_f32_16x16x32_bf16 v[98:101], v[150:153], v[198:201], v[98:101]
	v_mfma_f32_16x16x32_bf16 v[86:89], v[126:129], v[214:217], v[86:89]
	v_mfma_f32_16x16x32_bf16 v[82:85], v[150:153], v[214:217], v[82:85]
	s_barrier
	s_mov_b32 m0, s48
	v_lshl_add_u64 v[218:219], s[40:41], 0, v[172:173]
	s_add_u32 s72, s40, 0x40000
	ds_read_b128 v[162:165], v209 offset:16384
	ds_read_b128 v[166:169], v209 offset:17408
	ds_read_b128 v[186:189], v209 offset:18432
	ds_read_b128 v[190:193], v209 offset:19456
	ds_read_b128 v[194:197], v209 offset:20480
	ds_read_b128 v[198:201], v209 offset:21504
	ds_read_b128 v[202:205], v209 offset:22528
	ds_read_b128 v[214:217], v209 offset:23552
	global_load_lds_dwordx4 v[218:219], off
	v_lshl_add_u64 v[220:221], s[40:41], 0, v[176:177]
	s_mov_b32 m0, s49
	s_addc_u32 s73, s41, 0
	global_load_lds_dwordx4 v[220:221], off
	v_lshl_add_u64 v[222:223], s[72:73], 0, v[172:173]
	s_mov_b32 m0, s50
	v_lshl_add_u64 v[224:225], s[42:43], 0, v[174:175]
	global_load_lds_dwordx4 v[222:223], off
	v_lshl_add_u64 v[222:223], s[72:73], 0, v[176:177]
	s_mov_b32 m0, s51
	s_nop 0
	global_load_lds_dwordx4 v[222:223], off
	v_lshl_add_u64 v[222:223], s[42:43], 0, v[170:171]
	s_mov_b32 m0, s52
	s_nop 0
	global_load_lds_dwordx4 v[222:223], off
	s_mov_b32 m0, s53
	s_nop 0
	global_load_lds_dwordx4 v[224:225], off
	s_cmp_lg_u32 s98, 0
	s_cbranch_scc1 .Lfi_b_4
	s_waitcnt vmcnt(8)
.Lfi_b_4:
	s_mov_b32 s98, 0
	s_waitcnt lgkmcnt(0)
	s_barrier
	v_mfma_f32_16x16x32_bf16 v[78:81], v[34:37], v[162:165], v[78:81]
	v_mfma_f32_16x16x32_bf16 v[74:77], v[42:45], v[162:165], v[74:77]
	v_mfma_f32_16x16x32_bf16 v[62:65], v[34:37], v[186:189], v[62:65]
	v_mfma_f32_16x16x32_bf16 v[58:61], v[42:45], v[186:189], v[58:61]
	v_mfma_f32_16x16x32_bf16 v[30:33], v[34:37], v[194:197], v[30:33]
	v_mfma_f32_16x16x32_bf16 v[26:29], v[42:45], v[194:197], v[26:29]
	v_mfma_f32_16x16x32_bf16 v[14:17], v[34:37], v[202:205], v[14:17]
	v_mfma_f32_16x16x32_bf16 v[10:13], v[42:45], v[202:205], v[10:13]
	v_mfma_f32_16x16x32_bf16 v[78:81], v[38:41], v[166:169], v[78:81]
	v_mfma_f32_16x16x32_bf16 v[74:77], v[46:49], v[166:169], v[74:77]
	v_mfma_f32_16x16x32_bf16 v[62:65], v[38:41], v[190:193], v[62:65]
	v_mfma_f32_16x16x32_bf16 v[58:61], v[46:49], v[190:193], v[58:61]
	v_mfma_f32_16x16x32_bf16 v[30:33], v[38:41], v[198:201], v[30:33]
	v_mfma_f32_16x16x32_bf16 v[26:29], v[46:49], v[198:201], v[26:29]
	v_mfma_f32_16x16x32_bf16 v[14:17], v[38:41], v[214:217], v[14:17]
	v_mfma_f32_16x16x32_bf16 v[10:13], v[46:49], v[214:217], v[10:13]
	v_mfma_f32_16x16x32_bf16 v[22:25], v[114:117], v[194:197], v[22:25]
	v_mfma_f32_16x16x32_bf16 v[18:21], v[138:141], v[194:197], v[18:21]
	v_mfma_f32_16x16x32_bf16 v[6:9], v[114:117], v[202:205], v[6:9]
	v_mfma_f32_16x16x32_bf16 v[2:5], v[138:141], v[202:205], v[2:5]
	v_mfma_f32_16x16x32_bf16 v[34:37], v[114:117], v[162:165], v[70:73]
	v_mfma_f32_16x16x32_bf16 v[38:41], v[138:141], v[162:165], v[66:69]
	v_mfma_f32_16x16x32_bf16 v[42:45], v[114:117], v[186:189], v[54:57]
	v_mfma_f32_16x16x32_bf16 v[46:49], v[138:141], v[186:189], v[50:53]
	v_mfma_f32_16x16x32_bf16 v[22:25], v[126:129], v[198:201], v[22:25]
	v_mfma_f32_16x16x32_bf16 v[18:21], v[150:153], v[198:201], v[18:21]
	v_mfma_f32_16x16x32_bf16 v[6:9], v[126:129], v[214:217], v[6:9]
	v_mfma_f32_16x16x32_bf16 v[2:5], v[150:153], v[214:217], v[2:5]
	v_mfma_f32_16x16x32_bf16 v[34:37], v[126:129], v[166:169], v[34:37]
	v_mfma_f32_16x16x32_bf16 v[38:41], v[150:153], v[166:169], v[38:41]
	v_mfma_f32_16x16x32_bf16 v[42:45], v[126:129], v[190:193], v[42:45]
	v_mfma_f32_16x16x32_bf16 v[46:49], v[150:153], v[190:193], v[46:49]
	s_barrier
; #define PG8_STAGE(bufoff, gbase, voff) do { _Pragma("unroll") for (int _i = 0; _i < 2; ++_i) \
;         __builtin_amdgcn_global_load_lds((const unsigned*)((const char*)(gbase) + (voff)[_i]), (PG8_LAS unsigned*)(lds + (bufoff) + ldsw + _i * 8192), 16, 0, 0); } while (0)
; #define PG8_LDA(dst, b, h) do { _Pragma("unroll") for (int m = 0; m < 4; ++m) _Pragma("unroll") for (int k = 0; k < 2; ++k) dst[m][k] = *(const PG8_LAS bf16x8*)(lds + PG8_SA(b, h) + aoff + m * 2048 + k * 1024); } while (0)
; #define PG8_LDB(dst, b, h) do { _Pragma("unroll") for (int n = 0; n < 2; ++n) _Pragma("unroll") for (int k = 0; k < 2; ++k) dst[n][k] = *(const PG8_LAS bf16x8*)(lds + PG8_SB(b, h) + boff + n * 2048 + k * 1024); } while (0)
; #define PG8_MMA(ai, bj, At, Bt) do { __builtin_amdgcn_s_setprio(1); _Pragma("unroll") for (int m = 0; m < 4; ++m) _Pragma("unroll") for (int n = 0; n < 2; ++n) _Pragma("unroll") for (int k = 0; k < 2; ++k) \
;         acc[ai][bj][m][n] = __builtin_amdgcn_mfma_f32_16x16x32_bf16(Bt[n][k], At[m][k], acc[ai][bj][m][n], 0, 0, 0); __builtin_amdgcn_s_setprio(0); } while (0)
; #define PG8_WAIT_V(n) asm volatile("s_waitcnt vmcnt(" #n ")" ::: "memory")
; #define PG8_WAIT_L(n) do { asm volatile("s_waitcnt lgkmcnt(" #n ")" ::: "memory"); __builtin_amdgcn_s_waitcnt(0xC07F); } while (0)
; #define PG8_BAR __builtin_amdgcn_s_barrier()
; #define PG8_SCHED __builtin_amdgcn_sched_barrier(0)
; template <class Epi, class Sched, bool SEG3 = false>
; __device__ __forceinline__ void gemm_phase(PG8_LAS unsigned char* lds, const Gemm g, const Sched& S, const Epi& E) {
;     ...
;             PG8_LDB(B0, 1, 0); PG8_LDB(B1, 1, 1); PG8_SCHED; PG8_LDA(At, 1, 0); PG8_STAGE(PG8_SA(0, 1), a2 + hsA, voffA);
;             PG8_WAIT_V(8); PG8_WAIT_L(0); PG8_BAR; if (cur.half != 1) { PG8_MMA(0, 0, At, B0); PG8_MMA(0, 1, At, B1); } PG8_BAR; PG8_SCHED;
;             PG8_LDA(At, 1, 1); PG8_STAGE(PG8_SB(1, 0), b3, voffB); PG8_STAGE(PG8_SB(1, 1), b3 + hsB, voffB); PG8_STAGE(PG8_SA(1, 0), a3, voffA);
;             PG8_WAIT_V(8); PG8_WAIT_L(0); PG8_BAR; if (cur.half != 0) { PG8_MMA(1, 0, At, B0); PG8_MMA(1, 1, At, B1); } PG8_BAR; PG8_SCHED;
;         }
	ds_read_b128 v[50:53], v210
	ds_read_b128 v[54:57], v210 offset:1024
	ds_read_b128 v[66:69], v210 offset:2048
	ds_read_b128 v[70:73], v210 offset:3072
	ds_read_b128 v[114:117], v211
	ds_read_b128 v[126:129], v211 offset:1024
	ds_read_b128 v[138:141], v211 offset:2048
	ds_read_b128 v[150:153], v211 offset:3072
	s_add_u32 s42, s42, 0x40000
	s_addc_u32 s43, s43, 0
	s_mov_b32 m0, s54
	v_lshl_add_u64 v[226:227], s[42:43], 0, v[170:171]
	ds_read_b128 v[162:165], v209 offset:32768
	ds_read_b128 v[166:169], v209 offset:33792
	ds_read_b128 v[186:189], v209 offset:34816
	ds_read_b128 v[190:193], v209 offset:35840
	ds_read_b128 v[194:197], v209 offset:36864
	ds_read_b128 v[198:201], v209 offset:37888
	ds_read_b128 v[202:205], v209 offset:38912
	ds_read_b128 v[214:217], v209 offset:39936
	global_load_lds_dwordx4 v[226:227], off
	v_lshl_add_u64 v[226:227], s[42:43], 0, v[174:175]
	s_mov_b32 m0, s55
	s_nop 0
	global_load_lds_dwordx4 v[226:227], off
	s_waitcnt vmcnt(8)
	s_waitcnt lgkmcnt(0)
	s_waitcnt lgkmcnt(0)
	s_barrier
	v_mfma_f32_16x16x32_bf16 v[158:161], v[50:53], v[162:165], v[158:161]
	v_mfma_f32_16x16x32_bf16 v[154:157], v[66:69], v[162:165], v[154:157]
	v_mfma_f32_16x16x32_bf16 v[134:137], v[50:53], v[186:189], v[134:137]
	v_mfma_f32_16x16x32_bf16 v[130:133], v[66:69], v[186:189], v[130:133]
	v_mfma_f32_16x16x32_bf16 v[110:113], v[50:53], v[194:197], v[110:113]
	v_mfma_f32_16x16x32_bf16 v[106:109], v[66:69], v[194:197], v[106:109]
	v_mfma_f32_16x16x32_bf16 v[94:97], v[50:53], v[202:205], v[94:97]
	v_mfma_f32_16x16x32_bf16 v[90:93], v[66:69], v[202:205], v[90:93]
	v_mfma_f32_16x16x32_bf16 v[158:161], v[54:57], v[166:169], v[158:161]
	v_mfma_f32_16x16x32_bf16 v[154:157], v[70:73], v[166:169], v[154:157]
	v_mfma_f32_16x16x32_bf16 v[134:137], v[54:57], v[190:193], v[134:137]
	v_mfma_f32_16x16x32_bf16 v[130:133], v[70:73], v[190:193], v[130:133]
	v_mfma_f32_16x16x32_bf16 v[110:113], v[54:57], v[198:201], v[110:113]
	v_mfma_f32_16x16x32_bf16 v[106:109], v[70:73], v[198:201], v[106:109]
	v_mfma_f32_16x16x32_bf16 v[94:97], v[54:57], v[214:217], v[94:97]
	v_mfma_f32_16x16x32_bf16 v[90:93], v[70:73], v[214:217], v[90:93]
	v_mfma_f32_16x16x32_bf16 v[146:149], v[114:117], v[162:165], v[146:149]
	v_mfma_f32_16x16x32_bf16 v[142:145], v[138:141], v[162:165], v[142:145]
	v_mfma_f32_16x16x32_bf16 v[122:125], v[114:117], v[186:189], v[122:125]
	v_mfma_f32_16x16x32_bf16 v[118:121], v[138:141], v[186:189], v[118:121]
	v_mfma_f32_16x16x32_bf16 v[102:105], v[114:117], v[194:197], v[102:105]
	v_mfma_f32_16x16x32_bf16 v[98:101], v[138:141], v[194:197], v[98:101]
	v_mfma_f32_16x16x32_bf16 v[86:89], v[114:117], v[202:205], v[86:89]
	v_mfma_f32_16x16x32_bf16 v[82:85], v[138:141], v[202:205], v[82:85]
	v_mfma_f32_16x16x32_bf16 v[146:149], v[126:129], v[166:169], v[146:149]
	v_mfma_f32_16x16x32_bf16 v[142:145], v[150:153], v[166:169], v[142:145]
	v_mfma_f32_16x16x32_bf16 v[122:125], v[126:129], v[190:193], v[122:125]
	v_mfma_f32_16x16x32_bf16 v[118:121], v[150:153], v[190:193], v[118:121]
	v_mfma_f32_16x16x32_bf16 v[102:105], v[126:129], v[198:201], v[102:105]
	v_mfma_f32_16x16x32_bf16 v[98:101], v[150:153], v[198:201], v[98:101]
	v_mfma_f32_16x16x32_bf16 v[86:89], v[126:129], v[214:217], v[86:89]
	v_mfma_f32_16x16x32_bf16 v[82:85], v[150:153], v[214:217], v[82:85]
	s_barrier
	s_mov_b32 m0, s58
	v_lshl_add_u64 v[218:219], v[218:219], 0, s[18:19]
	s_add_u32 s40, s40, 0x40080
	ds_read_b128 v[162:165], v209 offset:49152
	ds_read_b128 v[166:169], v209 offset:50176
	ds_read_b128 v[186:189], v209 offset:51200
	ds_read_b128 v[190:193], v209 offset:52224
	ds_read_b128 v[194:197], v209 offset:53248
	ds_read_b128 v[198:201], v209 offset:54272
	ds_read_b128 v[202:205], v209 offset:55296
	ds_read_b128 v[214:217], v209 offset:56320
	global_load_lds_dwordx4 v[218:219], off
	v_lshl_add_u64 v[218:219], v[220:221], 0, s[18:19]
	s_mov_b32 m0, s59
	s_addc_u32 s41, s41, 0
	global_load_lds_dwordx4 v[218:219], off
	v_lshl_add_u64 v[218:219], s[40:41], 0, v[172:173]
	s_mov_b32 m0, s62
	s_nop 0
	global_load_lds_dwordx4 v[218:219], off
	v_lshl_add_u64 v[218:219], s[40:41], 0, v[176:177]
	s_mov_b32 m0, s63
	s_nop 0
	global_load_lds_dwordx4 v[218:219], off
	v_lshl_add_u64 v[218:219], v[222:223], 0, s[18:19]
	s_mov_b32 m0, s60
	s_nop 0
	global_load_lds_dwordx4 v[218:219], off
	v_lshl_add_u64 v[218:219], v[224:225], 0, s[18:19]
	s_mov_b32 m0, s61
	s_nop 0
	global_load_lds_dwordx4 v[218:219], off
	s_waitcnt vmcnt(8)
	s_waitcnt lgkmcnt(0)
	s_waitcnt lgkmcnt(0)
	s_barrier
	v_mfma_f32_16x16x32_bf16 v[78:81], v[50:53], v[162:165], v[78:81]
	v_mfma_f32_16x16x32_bf16 v[74:77], v[66:69], v[162:165], v[74:77]
	v_mfma_f32_16x16x32_bf16 v[62:65], v[50:53], v[186:189], v[62:65]
	v_mfma_f32_16x16x32_bf16 v[58:61], v[66:69], v[186:189], v[58:61]
	v_mfma_f32_16x16x32_bf16 v[30:33], v[50:53], v[194:197], v[30:33]
	v_mfma_f32_16x16x32_bf16 v[26:29], v[66:69], v[194:197], v[26:29]
	v_mfma_f32_16x16x32_bf16 v[14:17], v[50:53], v[202:205], v[14:17]
	v_mfma_f32_16x16x32_bf16 v[10:13], v[66:69], v[202:205], v[10:13]
	v_mfma_f32_16x16x32_bf16 v[78:81], v[54:57], v[166:169], v[78:81]
	v_mfma_f32_16x16x32_bf16 v[74:77], v[70:73], v[166:169], v[74:77]
	v_mfma_f32_16x16x32_bf16 v[62:65], v[54:57], v[190:193], v[62:65]
	v_mfma_f32_16x16x32_bf16 v[58:61], v[70:73], v[190:193], v[58:61]
	v_mfma_f32_16x16x32_bf16 v[30:33], v[54:57], v[198:201], v[30:33]
	v_mfma_f32_16x16x32_bf16 v[26:29], v[70:73], v[198:201], v[26:29]
	v_mfma_f32_16x16x32_bf16 v[14:17], v[54:57], v[214:217], v[14:17]
	v_mfma_f32_16x16x32_bf16 v[10:13], v[70:73], v[214:217], v[10:13]
	v_mfma_f32_16x16x32_bf16 v[34:37], v[114:117], v[162:165], v[34:37]
	v_mfma_f32_16x16x32_bf16 v[70:73], v[126:129], v[166:169], v[34:37]
	v_mfma_f32_16x16x32_bf16 v[34:37], v[138:141], v[162:165], v[38:41]
	v_mfma_f32_16x16x32_bf16 v[66:69], v[150:153], v[166:169], v[34:37]
	v_mfma_f32_16x16x32_bf16 v[34:37], v[114:117], v[186:189], v[42:45]
	v_mfma_f32_16x16x32_bf16 v[54:57], v[126:129], v[190:193], v[34:37]
	v_mfma_f32_16x16x32_bf16 v[34:37], v[138:141], v[186:189], v[46:49]
	v_mfma_f32_16x16x32_bf16 v[22:25], v[114:117], v[194:197], v[22:25]
	v_mfma_f32_16x16x32_bf16 v[18:21], v[138:141], v[194:197], v[18:21]
	v_mfma_f32_16x16x32_bf16 v[6:9], v[114:117], v[202:205], v[6:9]
	v_mfma_f32_16x16x32_bf16 v[2:5], v[138:141], v[202:205], v[2:5]
	v_mfma_f32_16x16x32_bf16 v[50:53], v[150:153], v[190:193], v[34:37]
	v_mfma_f32_16x16x32_bf16 v[22:25], v[126:129], v[198:201], v[22:25]
	v_mfma_f32_16x16x32_bf16 v[18:21], v[150:153], v[198:201], v[18:21]
	v_mfma_f32_16x16x32_bf16 v[6:9], v[126:129], v[214:217], v[6:9]
	v_mfma_f32_16x16x32_bf16 v[2:5], v[150:153], v[214:217], v[2:5]
	s_barrier
	s_add_u32 s38, s38, 0x100
	s_addc_u32 s39, s39, 0
	s_add_u32 s68, s68, 0x100
	s_addc_u32 s69, s69, 0
	s_cmp_ge_i32 s70, s57
	s_mov_b32 s40, s70
	s_cbranch_scc0 .LBB0_2133
	s_and_b64 vcc, exec, s[22:23]
	s_cbranch_vccz .LBB0_2136

; #define PG8_STAGE(bufoff, gbase, voff) do { _Pragma("unroll") for (int _i = 0; _i < 2; ++_i) \
;         __builtin_amdgcn_global_load_lds((const unsigned*)((const char*)(gbase) + (voff)[_i]), (PG8_LAS unsigned*)(lds + (bufoff) + ldsw + _i * 8192), 16, 0, 0); } while (0)
; #define PG8_LDA(dst, b, h) do { _Pragma("unroll") for (int m = 0; m < 4; ++m) _Pragma("unroll") for (int k = 0; k < 2; ++k) dst[m][k] = *(const PG8_LAS bf16x8*)(lds + PG8_SA(b, h) + aoff + m * 2048 + k * 1024); } while (0)
; #define PG8_LDB(dst, b, h) do { _Pragma("unroll") for (int n = 0; n < 2; ++n) _Pragma("unroll") for (int k = 0; k < 2; ++k) dst[n][k] = *(const PG8_LAS bf16x8*)(lds + PG8_SB(b, h) + boff + n * 2048 + k * 1024); } while (0)
; #define PG8_MMA(ai, bj, At, Bt) do { __builtin_amdgcn_s_setprio(1); _Pragma("unroll") for (int m = 0; m < 4; ++m) _Pragma("unroll") for (int n = 0; n < 2; ++n) _Pragma("unroll") for (int k = 0; k < 2; ++k) \
;         acc[ai][bj][m][n] = __builtin_amdgcn_mfma_f32_16x16x32_bf16(Bt[n][k], At[m][k], acc[ai][bj][m][n], 0, 0, 0); __builtin_amdgcn_s_setprio(0); } while (0)
; #define PG8_WAIT_V(n) asm volatile("s_waitcnt vmcnt(" #n ")" ::: "memory")
; #define PG8_WAIT_L(n) do { asm volatile("s_waitcnt lgkmcnt(" #n ")" ::: "memory"); __builtin_amdgcn_s_waitcnt(0xC07F); } while (0)
; #define PG8_BAR __builtin_amdgcn_s_barrier()
; #define PG8_SCHED __builtin_amdgcn_sched_barrier(0)
; template <class Epi, class Sched, bool SEG3 = false>
; __device__ __forceinline__ void gemm_phase(PG8_LAS unsigned char* lds, const Gemm g, const Sched& S, const Epi& E) {
;     ...
;             PG8_WAIT_V(8); PG8_WAIT_L(0); PG8_BAR; if (cur.half != 0) { PG8_MMA(1, 0, At, B0); PG8_MMA(1, 1, At, B1); } PG8_BAR; PG8_SCHED;
;             PG8_LDB(B0, 1, 0); PG8_LDB(B1, 1, 1); PG8_SCHED; PG8_LDA(At, 1, 0); PG8_STAGE(PG8_SA(0, 1), a2 + hsA, voffA);
;             PG8_WAIT_V(8); PG8_WAIT_L(0); PG8_BAR; if (cur.half != 1) { PG8_MMA(0, 0, At, B0); PG8_MMA(0, 1, At, B1); } PG8_BAR; PG8_SCHED;
.Lfi_b_8:
	s_mov_b32 s98, 0
	s_waitcnt lgkmcnt(0)
	s_barrier
	v_mfma_f32_16x16x32_bf16 v[62:65], v[98:101], v[178:181], v[62:65]
	v_mfma_f32_16x16x32_bf16 v[58:61], v[122:125], v[178:181], v[58:61]
	v_mfma_f32_16x16x32_bf16 v[46:49], v[98:101], v[186:189], v[46:49]
	v_mfma_f32_16x16x32_bf16 v[42:45], v[122:125], v[186:189], v[42:45]
	v_mfma_f32_16x16x32_bf16 v[30:33], v[98:101], v[194:197], v[30:33]
	v_mfma_f32_16x16x32_bf16 v[26:29], v[122:125], v[194:197], v[26:29]
	v_mfma_f32_16x16x32_bf16 v[14:17], v[98:101], v[210:213], v[14:17]
	v_mfma_f32_16x16x32_bf16 v[10:13], v[122:125], v[210:213], v[10:13]
	v_mfma_f32_16x16x32_bf16 v[62:65], v[110:113], v[182:185], v[62:65]
	v_mfma_f32_16x16x32_bf16 v[58:61], v[134:137], v[182:185], v[58:61]
	v_mfma_f32_16x16x32_bf16 v[46:49], v[110:113], v[190:193], v[46:49]
	v_mfma_f32_16x16x32_bf16 v[42:45], v[134:137], v[190:193], v[42:45]
	v_mfma_f32_16x16x32_bf16 v[30:33], v[110:113], v[206:209], v[30:33]
	v_mfma_f32_16x16x32_bf16 v[26:29], v[134:137], v[206:209], v[26:29]
	v_mfma_f32_16x16x32_bf16 v[14:17], v[110:113], v[214:217], v[14:17]
	v_mfma_f32_16x16x32_bf16 v[10:13], v[134:137], v[214:217], v[10:13]
	v_mfma_f32_16x16x32_bf16 v[54:57], v[146:149], v[178:181], v[54:57]
	v_mfma_f32_16x16x32_bf16 v[50:53], v[170:173], v[178:181], v[50:53]
	v_mfma_f32_16x16x32_bf16 v[38:41], v[146:149], v[186:189], v[38:41]
	v_mfma_f32_16x16x32_bf16 v[34:37], v[170:173], v[186:189], v[34:37]
	v_mfma_f32_16x16x32_bf16 v[22:25], v[146:149], v[194:197], v[22:25]
	v_mfma_f32_16x16x32_bf16 v[18:21], v[170:173], v[194:197], v[18:21]
	v_mfma_f32_16x16x32_bf16 v[6:9], v[146:149], v[210:213], v[6:9]
	v_mfma_f32_16x16x32_bf16 v[2:5], v[170:173], v[210:213], v[2:5]
	v_mfma_f32_16x16x32_bf16 v[54:57], v[150:153], v[182:185], v[54:57]
	v_mfma_f32_16x16x32_bf16 v[50:53], v[174:177], v[182:185], v[50:53]
	v_mfma_f32_16x16x32_bf16 v[38:41], v[150:153], v[190:193], v[38:41]
	v_mfma_f32_16x16x32_bf16 v[34:37], v[174:177], v[190:193], v[34:37]
	v_mfma_f32_16x16x32_bf16 v[22:25], v[150:153], v[206:209], v[22:25]
	v_mfma_f32_16x16x32_bf16 v[18:21], v[174:177], v[206:209], v[18:21]
	v_mfma_f32_16x16x32_bf16 v[6:9], v[150:153], v[214:217], v[6:9]
	v_mfma_f32_16x16x32_bf16 v[2:5], v[174:177], v[214:217], v[2:5]
	s_barrier
	ds_read_b128 v[98:101], v202
	ds_read_b128 v[110:113], v202 offset:1024
	ds_read_b128 v[122:125], v202 offset:2048
	ds_read_b128 v[134:137], v202 offset:3072
	ds_read_b128 v[146:149], v203
	ds_read_b128 v[150:153], v203 offset:1024
	ds_read_b128 v[170:173], v203 offset:2048
	ds_read_b128 v[174:177], v203 offset:3072
	s_add_u32 s28, s36, 0xb0000
	s_addc_u32 s29, s37, 0
	s_mov_b32 m0, s48
	v_lshl_add_u64 v[226:227], s[28:29], 0, v[154:155]
	ds_read_b128 v[178:181], v201 offset:32768
	ds_read_b128 v[182:185], v201 offset:33792
	ds_read_b128 v[186:189], v201 offset:34816
	ds_read_b128 v[190:193], v201 offset:35840
	ds_read_b128 v[194:197], v201 offset:36864
	ds_read_b128 v[206:209], v201 offset:37888
	ds_read_b128 v[210:213], v201 offset:38912
	ds_read_b128 v[214:217], v201 offset:39936
	global_load_lds_dwordx4 v[226:227], off
	v_lshl_add_u64 v[226:227], s[28:29], 0, v[158:159]
	s_mov_b32 m0, s49
	s_nop 0
	global_load_lds_dwordx4 v[226:227], off
	s_waitcnt vmcnt(8)
	s_waitcnt lgkmcnt(0)
	s_waitcnt lgkmcnt(0)
	s_barrier
	v_mfma_f32_16x16x32_bf16 v[142:145], v[98:101], v[178:181], v[142:145]
	v_mfma_f32_16x16x32_bf16 v[138:141], v[122:125], v[178:181], v[138:141]
	v_mfma_f32_16x16x32_bf16 v[118:121], v[98:101], v[186:189], v[118:121]
	v_mfma_f32_16x16x32_bf16 v[114:117], v[122:125], v[186:189], v[114:117]
	v_mfma_f32_16x16x32_bf16 v[94:97], v[98:101], v[194:197], v[94:97]
	v_mfma_f32_16x16x32_bf16 v[90:93], v[122:125], v[194:197], v[90:93]
	v_mfma_f32_16x16x32_bf16 v[78:81], v[98:101], v[210:213], v[78:81]
	v_mfma_f32_16x16x32_bf16 v[74:77], v[122:125], v[210:213], v[74:77]
	v_mfma_f32_16x16x32_bf16 v[142:145], v[110:113], v[182:185], v[142:145]
	v_mfma_f32_16x16x32_bf16 v[138:141], v[134:137], v[182:185], v[138:141]
	v_mfma_f32_16x16x32_bf16 v[118:121], v[110:113], v[190:193], v[118:121]
	v_mfma_f32_16x16x32_bf16 v[114:117], v[134:137], v[190:193], v[114:117]
	v_mfma_f32_16x16x32_bf16 v[94:97], v[110:113], v[206:209], v[94:97]
	v_mfma_f32_16x16x32_bf16 v[90:93], v[134:137], v[206:209], v[90:93]
	v_mfma_f32_16x16x32_bf16 v[78:81], v[110:113], v[214:217], v[78:81]
	v_mfma_f32_16x16x32_bf16 v[74:77], v[134:137], v[214:217], v[74:77]
	v_mfma_f32_16x16x32_bf16 v[130:133], v[146:149], v[178:181], v[130:133]
	v_mfma_f32_16x16x32_bf16 v[126:129], v[170:173], v[178:181], v[126:129]
	v_mfma_f32_16x16x32_bf16 v[106:109], v[146:149], v[186:189], v[106:109]
	v_mfma_f32_16x16x32_bf16 v[102:105], v[170:173], v[186:189], v[102:105]
	v_mfma_f32_16x16x32_bf16 v[86:89], v[146:149], v[194:197], v[86:89]
	v_mfma_f32_16x16x32_bf16 v[82:85], v[170:173], v[194:197], v[82:85]
	v_mfma_f32_16x16x32_bf16 v[70:73], v[146:149], v[210:213], v[70:73]
	v_mfma_f32_16x16x32_bf16 v[66:69], v[170:173], v[210:213], v[66:69]
	v_mfma_f32_16x16x32_bf16 v[130:133], v[150:153], v[182:185], v[130:133]
	v_mfma_f32_16x16x32_bf16 v[126:129], v[174:177], v[182:185], v[126:129]
	v_mfma_f32_16x16x32_bf16 v[106:109], v[150:153], v[190:193], v[106:109]
	v_mfma_f32_16x16x32_bf16 v[102:105], v[174:177], v[190:193], v[102:105]
	v_mfma_f32_16x16x32_bf16 v[86:89], v[150:153], v[206:209], v[86:89]
	v_mfma_f32_16x16x32_bf16 v[82:85], v[174:177], v[206:209], v[82:85]
	v_mfma_f32_16x16x32_bf16 v[70:73], v[150:153], v[214:217], v[70:73]
	v_mfma_f32_16x16x32_bf16 v[66:69], v[174:177], v[214:217], v[66:69]
	s_barrier
; #define PG8_STAGE(bufoff, gbase, voff) do { _Pragma("unroll") for (int _i = 0; _i < 2; ++_i) \
;         __builtin_amdgcn_global_load_lds((const unsigned*)((const char*)(gbase) + (voff)[_i]), (PG8_LAS unsigned*)(lds + (bufoff) + ldsw + _i * 8192), 16, 0, 0); } while (0)
; #define PG8_LDA(dst, b, h) do { _Pragma("unroll") for (int m = 0; m < 4; ++m) _Pragma("unroll") for (int k = 0; k < 2; ++k) dst[m][k] = *(const PG8_LAS bf16x8*)(lds + PG8_SA(b, h) + aoff + m * 2048 + k * 1024); } while (0)
; #define PG8_MMA(ai, bj, At, Bt) do { __builtin_amdgcn_s_setprio(1); _Pragma("unroll") for (int m = 0; m < 4; ++m) _Pragma("unroll") for (int n = 0; n < 2; ++n) _Pragma("unroll") for (int k = 0; k < 2; ++k) \
;         acc[ai][bj][m][n] = __builtin_amdgcn_mfma_f32_16x16x32_bf16(Bt[n][k], At[m][k], acc[ai][bj][m][n], 0, 0, 0); __builtin_amdgcn_s_setprio(0); } while (0)
; #define PG8_WAIT_V(n) asm volatile("s_waitcnt vmcnt(" #n ")" ::: "memory")
; #define PG8_WAIT_L(n) do { asm volatile("s_waitcnt lgkmcnt(" #n ")" ::: "memory"); __builtin_amdgcn_s_waitcnt(0xC07F); } while (0)
; #define PG8_BAR __builtin_amdgcn_s_barrier()
; #define PG8_SCHED __builtin_amdgcn_sched_barrier(0)
; template <class Epi, class Sched, bool SEG3 = false>
; __device__ __forceinline__ void gemm_phase(PG8_LAS unsigned char* lds, const Gemm g, const Sched& S, const Epi& E) {
;     ...
;             PG8_LDA(At, 1, 1); PG8_STAGE(PG8_SB(1, 0), b3, voffB); PG8_STAGE(PG8_SB(1, 1), b3 + hsB, voffB); PG8_STAGE(PG8_SA(1, 0), a3, voffA);
;             PG8_WAIT_V(8); PG8_WAIT_L(0); PG8_BAR; if (cur.half != 0) { PG8_MMA(1, 0, At, B0); PG8_MMA(1, 1, At, B1); } PG8_BAR; PG8_SCHED;
;         }
	s_mov_b32 m0, s52
	v_lshl_add_u64 v[218:219], v[218:219], 0, s[20:21]
	s_add_u32 s28, s34, 0xb0080
	ds_read_b128 v[178:181], v201 offset:49152
	ds_read_b128 v[182:185], v201 offset:50176
	ds_read_b128 v[186:189], v201 offset:51200
	ds_read_b128 v[190:193], v201 offset:52224
	ds_read_b128 v[194:197], v201 offset:53248
	ds_read_b128 v[206:209], v201 offset:54272
	ds_read_b128 v[210:213], v201 offset:55296
	ds_read_b128 v[214:217], v201 offset:56320
	global_load_lds_dwordx4 v[218:219], off
	v_lshl_add_u64 v[218:219], v[220:221], 0, s[20:21]
	s_mov_b32 m0, s53
	s_addc_u32 s29, s35, 0
	global_load_lds_dwordx4 v[218:219], off
	v_lshl_add_u64 v[218:219], s[28:29], 0, v[156:157]
	s_mov_b32 m0, s56
	s_nop 0
	global_load_lds_dwordx4 v[218:219], off
	v_lshl_add_u64 v[218:219], s[28:29], 0, v[160:161]
	s_mov_b32 m0, s57
	s_nop 0
	global_load_lds_dwordx4 v[218:219], off
	v_lshl_add_u64 v[218:219], v[222:223], 0, s[20:21]
	s_mov_b32 m0, s54
	s_nop 0
	global_load_lds_dwordx4 v[218:219], off
	v_lshl_add_u64 v[218:219], v[224:225], 0, s[20:21]
	s_mov_b32 m0, s55
	s_nop 0
	global_load_lds_dwordx4 v[218:219], off
	s_waitcnt vmcnt(8)
	s_waitcnt lgkmcnt(0)
	s_waitcnt lgkmcnt(0)
	s_barrier
	v_mfma_f32_16x16x32_bf16 v[62:65], v[98:101], v[178:181], v[62:65]
	v_mfma_f32_16x16x32_bf16 v[58:61], v[122:125], v[178:181], v[58:61]
	v_mfma_f32_16x16x32_bf16 v[46:49], v[98:101], v[186:189], v[46:49]
	v_mfma_f32_16x16x32_bf16 v[42:45], v[122:125], v[186:189], v[42:45]
	v_mfma_f32_16x16x32_bf16 v[30:33], v[98:101], v[194:197], v[30:33]
	v_mfma_f32_16x16x32_bf16 v[26:29], v[122:125], v[194:197], v[26:29]
	v_mfma_f32_16x16x32_bf16 v[14:17], v[98:101], v[210:213], v[14:17]
	v_mfma_f32_16x16x32_bf16 v[10:13], v[122:125], v[210:213], v[10:13]
	v_mfma_f32_16x16x32_bf16 v[62:65], v[110:113], v[182:185], v[62:65]
	v_mfma_f32_16x16x32_bf16 v[58:61], v[134:137], v[182:185], v[58:61]
	v_mfma_f32_16x16x32_bf16 v[46:49], v[110:113], v[190:193], v[46:49]
	v_mfma_f32_16x16x32_bf16 v[42:45], v[134:137], v[190:193], v[42:45]
	v_mfma_f32_16x16x32_bf16 v[30:33], v[110:113], v[206:209], v[30:33]
	v_mfma_f32_16x16x32_bf16 v[26:29], v[134:137], v[206:209], v[26:29]
	v_mfma_f32_16x16x32_bf16 v[14:17], v[110:113], v[214:217], v[14:17]
	v_mfma_f32_16x16x32_bf16 v[10:13], v[134:137], v[214:217], v[10:13]
	v_mfma_f32_16x16x32_bf16 v[54:57], v[146:149], v[178:181], v[54:57]
	v_mfma_f32_16x16x32_bf16 v[50:53], v[170:173], v[178:181], v[50:53]
	v_mfma_f32_16x16x32_bf16 v[38:41], v[146:149], v[186:189], v[38:41]
	v_mfma_f32_16x16x32_bf16 v[34:37], v[170:173], v[186:189], v[34:37]
	v_mfma_f32_16x16x32_bf16 v[22:25], v[146:149], v[194:197], v[22:25]
	v_mfma_f32_16x16x32_bf16 v[18:21], v[170:173], v[194:197], v[18:21]
	v_mfma_f32_16x16x32_bf16 v[6:9], v[146:149], v[210:213], v[6:9]
	v_mfma_f32_16x16x32_bf16 v[2:5], v[170:173], v[210:213], v[2:5]
	v_mfma_f32_16x16x32_bf16 v[54:57], v[150:153], v[182:185], v[54:57]
	v_mfma_f32_16x16x32_bf16 v[50:53], v[174:177], v[182:185], v[50:53]
	v_mfma_f32_16x16x32_bf16 v[38:41], v[150:153], v[190:193], v[38:41]
	v_mfma_f32_16x16x32_bf16 v[34:37], v[174:177], v[190:193], v[34:37]
	v_mfma_f32_16x16x32_bf16 v[22:25], v[150:153], v[206:209], v[22:25]
	v_mfma_f32_16x16x32_bf16 v[18:21], v[174:177], v[206:209], v[18:21]
	v_mfma_f32_16x16x32_bf16 v[6:9], v[150:153], v[214:217], v[6:9]
	v_mfma_f32_16x16x32_bf16 v[2:5], v[174:177], v[214:217], v[2:5]
	s_barrier
	s_add_u32 s66, s66, 0x100
	s_addc_u32 s67, s67, 0
	s_cmp_lt_i32 s68, s51
	s_mov_b64 s[28:29], s[30:31]
	s_mov_b32 s34, s68
	s_cbranch_scc1 .LBB0_2579
	s_andn2_b64 vcc, exec, s[24:25]
	s_cbranch_vccnz .LBB0_2582

; #define PG8_STAGE(bufoff, gbase, voff) do { _Pragma("unroll") for (int _i = 0; _i < 2; ++_i) \
;         __builtin_amdgcn_global_load_lds((const unsigned*)((const char*)(gbase) + (voff)[_i]), (PG8_LAS unsigned*)(lds + (bufoff) + ldsw + _i * 8192), 16, 0, 0); } while (0)
; #define PG8_LDA(dst, b, h) do { _Pragma("unroll") for (int m = 0; m < 4; ++m) _Pragma("unroll") for (int k = 0; k < 2; ++k) dst[m][k] = *(const PG8_LAS bf16x8*)(lds + PG8_SA(b, h) + aoff + m * 2048 + k * 1024); } while (0)
; #define PG8_MMA(ai, bj, At, Bt) do { __builtin_amdgcn_s_setprio(1); _Pragma("unroll") for (int m = 0; m < 4; ++m) _Pragma("unroll") for (int n = 0; n < 2; ++n) _Pragma("unroll") for (int k = 0; k < 2; ++k) \
;         acc[ai][bj][m][n] = __builtin_amdgcn_mfma_f32_16x16x32_bf16(Bt[n][k], At[m][k], acc[ai][bj][m][n], 0, 0, 0); __builtin_amdgcn_s_setprio(0); } while (0)
; #define PG8_WAIT_V(n) asm volatile("s_waitcnt vmcnt(" #n ")" ::: "memory")
; #define PG8_WAIT_L(n) do { asm volatile("s_waitcnt lgkmcnt(" #n ")" ::: "memory"); __builtin_amdgcn_s_waitcnt(0xC07F); } while (0)
; #define PG8_BAR __builtin_amdgcn_s_barrier()
; #define PG8_SCHED __builtin_amdgcn_sched_barrier(0)
; template <class Epi, class Sched, bool SEG3 = false>
; __device__ __forceinline__ void gemm_phase(PG8_LAS unsigned char* lds, const Gemm g, const Sched& S, const Epi& E) {
;     ...
;             PG8_WAIT_V(8); PG8_WAIT_L(0); PG8_BAR; if (cur.half != 1) { PG8_MMA(0, 0, At, B0); PG8_MMA(0, 1, At, B1); } PG8_BAR; PG8_SCHED;
;             PG8_LDA(At, 0, 1); PG8_STAGE(PG8_SB(0, 0), b2, voffB); PG8_STAGE(PG8_SB(0, 1), b2 + hsB, voffB); PG8_STAGE(PG8_SA(0, 0), a2, voffA);
;             PG8_WAIT_V(8); PG8_WAIT_L(0); PG8_BAR; if (cur.half != 0) { PG8_MMA(1, 0, At, B0); PG8_MMA(1, 1, At, B1); } PG8_BAR; PG8_SCHED;
.Lfi_a_9:
	s_waitcnt lgkmcnt(0)
	s_barrier
	v_mfma_f32_16x16x32_bf16 v[142:145], v[10:13], v[214:217], v[142:145]
	v_mfma_f32_16x16x32_bf16 v[138:141], v[34:37], v[214:217], v[138:141]
	v_mfma_f32_16x16x32_bf16 v[126:129], v[10:13], v[222:225], v[126:129]
	v_mfma_f32_16x16x32_bf16 v[122:125], v[34:37], v[222:225], v[122:125]
	v_mfma_f32_16x16x32_bf16 v[110:113], v[10:13], v[230:233], v[110:113]
	v_mfma_f32_16x16x32_bf16 v[106:109], v[34:37], v[230:233], v[106:109]
	v_mfma_f32_16x16x32_bf16 v[94:97], v[10:13], v[238:241], v[94:97]
	v_mfma_f32_16x16x32_bf16 v[90:93], v[34:37], v[238:241], v[90:93]
	v_mfma_f32_16x16x32_bf16 v[142:145], v[14:17], v[218:221], v[142:145]
	v_mfma_f32_16x16x32_bf16 v[138:141], v[38:41], v[218:221], v[138:141]
	v_mfma_f32_16x16x32_bf16 v[126:129], v[14:17], v[226:229], v[126:129]
	v_mfma_f32_16x16x32_bf16 v[122:125], v[38:41], v[226:229], v[122:125]
	v_mfma_f32_16x16x32_bf16 v[110:113], v[14:17], v[234:237], v[110:113]
	v_mfma_f32_16x16x32_bf16 v[106:109], v[38:41], v[234:237], v[106:109]
	v_mfma_f32_16x16x32_bf16 v[94:97], v[14:17], v[242:245], v[94:97]
	v_mfma_f32_16x16x32_bf16 v[90:93], v[38:41], v[242:245], v[90:93]
	v_mfma_f32_16x16x32_bf16 v[134:137], v[146:149], v[214:217], v[134:137]
	v_mfma_f32_16x16x32_bf16 v[130:133], v[178:181], v[214:217], v[130:133]
	v_mfma_f32_16x16x32_bf16 v[118:121], v[146:149], v[222:225], v[118:121]
	v_mfma_f32_16x16x32_bf16 v[114:117], v[178:181], v[222:225], v[114:117]
	v_mfma_f32_16x16x32_bf16 v[102:105], v[146:149], v[230:233], v[102:105]
	v_mfma_f32_16x16x32_bf16 v[98:101], v[178:181], v[230:233], v[98:101]
	v_mfma_f32_16x16x32_bf16 v[86:89], v[146:149], v[238:241], v[86:89]
	v_mfma_f32_16x16x32_bf16 v[82:85], v[178:181], v[238:241], v[82:85]
	v_mfma_f32_16x16x32_bf16 v[134:137], v[174:177], v[218:221], v[134:137]
	v_mfma_f32_16x16x32_bf16 v[130:133], v[210:213], v[218:221], v[130:133]
	v_mfma_f32_16x16x32_bf16 v[118:121], v[174:177], v[226:229], v[118:121]
	v_mfma_f32_16x16x32_bf16 v[114:117], v[210:213], v[226:229], v[114:117]
	v_mfma_f32_16x16x32_bf16 v[102:105], v[174:177], v[234:237], v[102:105]
	v_mfma_f32_16x16x32_bf16 v[98:101], v[210:213], v[234:237], v[98:101]
	v_mfma_f32_16x16x32_bf16 v[86:89], v[174:177], v[242:245], v[86:89]
	v_mfma_f32_16x16x32_bf16 v[82:85], v[210:213], v[242:245], v[82:85]
	s_barrier
	s_mov_b32 m0, s67
	v_lshl_add_u64 v[182:183], s[10:11], 0, v[152:153]
	s_add_u32 s54, s10, 0x40000
	ds_read_b128 v[214:217], v187 offset:16384
	ds_read_b128 v[218:221], v187 offset:17408
	ds_read_b128 v[222:225], v187 offset:18432
	ds_read_b128 v[226:229], v187 offset:19456
	ds_read_b128 v[230:233], v187 offset:20480
	ds_read_b128 v[234:237], v187 offset:21504
	ds_read_b128 v[238:241], v187 offset:22528
	ds_read_b128 v[242:245], v187 offset:23552
	global_load_lds_dwordx4 v[182:183], off
	v_lshl_add_u64 v[246:247], s[10:11], 0, v[156:157]
	s_mov_b32 m0, s68
	s_addc_u32 s55, s11, 0
	global_load_lds_dwordx4 v[246:247], off
	v_lshl_add_u64 v[248:249], s[54:55], 0, v[152:153]
	s_mov_b32 m0, s69
	v_lshl_add_u64 v[250:251], s[12:13], 0, v[154:155]
	global_load_lds_dwordx4 v[248:249], off
	v_lshl_add_u64 v[248:249], s[54:55], 0, v[156:157]
	s_mov_b32 m0, s70
	s_nop 0
	global_load_lds_dwordx4 v[248:249], off
	v_lshl_add_u64 v[248:249], s[12:13], 0, v[150:151]
	s_mov_b32 m0, s71
	s_nop 0
	global_load_lds_dwordx4 v[248:249], off
	s_mov_b32 m0, s72
	s_nop 0
	global_load_lds_dwordx4 v[250:251], off
	s_cmp_lg_u32 s98, 0
	s_cbranch_scc1 .Lfi_b_9
	s_waitcnt vmcnt(8)
.Lfi_b_9:
	s_mov_b32 s98, 0
	s_waitcnt lgkmcnt(0)
	s_barrier
	v_mfma_f32_16x16x32_bf16 v[78:81], v[10:13], v[214:217], v[78:81]
	v_mfma_f32_16x16x32_bf16 v[74:77], v[34:37], v[214:217], v[74:77]
	v_mfma_f32_16x16x32_bf16 v[62:65], v[10:13], v[222:225], v[62:65]
	v_mfma_f32_16x16x32_bf16 v[58:61], v[34:37], v[222:225], v[58:61]
	v_mfma_f32_16x16x32_bf16 v[46:49], v[10:13], v[230:233], v[46:49]
	v_mfma_f32_16x16x32_bf16 v[42:45], v[34:37], v[230:233], v[42:45]
	v_mfma_f32_16x16x32_bf16 v[10:13], v[10:13], v[238:241], v[22:25]
	v_mfma_f32_16x16x32_bf16 v[78:81], v[14:17], v[218:221], v[78:81]
	v_mfma_f32_16x16x32_bf16 v[74:77], v[38:41], v[218:221], v[74:77]
	v_mfma_f32_16x16x32_bf16 v[62:65], v[14:17], v[226:229], v[62:65]
	v_mfma_f32_16x16x32_bf16 v[58:61], v[38:41], v[226:229], v[58:61]
	v_mfma_f32_16x16x32_bf16 v[46:49], v[14:17], v[234:237], v[46:49]
	v_mfma_f32_16x16x32_bf16 v[42:45], v[38:41], v[234:237], v[42:45]
	v_mfma_f32_16x16x32_bf16 v[10:13], v[14:17], v[242:245], v[10:13]
	v_mfma_f32_16x16x32_bf16 v[14:17], v[34:37], v[238:241], v[18:21]
	v_mfma_f32_16x16x32_bf16 v[14:17], v[38:41], v[242:245], v[14:17]
	v_mfma_f32_16x16x32_bf16 v[18:21], v[146:149], v[214:217], v[70:73]
	v_mfma_f32_16x16x32_bf16 v[34:37], v[174:177], v[218:221], v[18:21]
	v_mfma_f32_16x16x32_bf16 v[18:21], v[178:181], v[214:217], v[66:69]
	v_mfma_f32_16x16x32_bf16 v[38:41], v[210:213], v[218:221], v[18:21]
	v_mfma_f32_16x16x32_bf16 v[18:21], v[146:149], v[222:225], v[54:57]
	v_mfma_f32_16x16x32_bf16 v[54:57], v[174:177], v[226:229], v[18:21]
	v_mfma_f32_16x16x32_bf16 v[18:21], v[178:181], v[222:225], v[50:53]
	v_mfma_f32_16x16x32_bf16 v[50:53], v[210:213], v[226:229], v[18:21]
	v_mfma_f32_16x16x32_bf16 v[18:21], v[146:149], v[230:233], v[30:33]
	v_mfma_f32_16x16x32_bf16 v[30:33], v[174:177], v[234:237], v[18:21]
	v_mfma_f32_16x16x32_bf16 v[18:21], v[178:181], v[230:233], v[26:29]
	v_mfma_f32_16x16x32_bf16 v[6:9], v[146:149], v[238:241], v[6:9]
	v_mfma_f32_16x16x32_bf16 v[2:5], v[178:181], v[238:241], v[2:5]
	v_mfma_f32_16x16x32_bf16 v[26:29], v[210:213], v[234:237], v[18:21]
	v_mfma_f32_16x16x32_bf16 v[6:9], v[174:177], v[242:245], v[6:9]
	v_mfma_f32_16x16x32_bf16 v[2:5], v[210:213], v[242:245], v[2:5]
	s_barrier
; #define PG8_STAGE(bufoff, gbase, voff) do { _Pragma("unroll") for (int _i = 0; _i < 2; ++_i) \
;         __builtin_amdgcn_global_load_lds((const unsigned*)((const char*)(gbase) + (voff)[_i]), (PG8_LAS unsigned*)(lds + (bufoff) + ldsw + _i * 8192), 16, 0, 0); } while (0)
; #define PG8_LDA(dst, b, h) do { _Pragma("unroll") for (int m = 0; m < 4; ++m) _Pragma("unroll") for (int k = 0; k < 2; ++k) dst[m][k] = *(const PG8_LAS bf16x8*)(lds + PG8_SA(b, h) + aoff + m * 2048 + k * 1024); } while (0)
; #define PG8_LDB(dst, b, h) do { _Pragma("unroll") for (int n = 0; n < 2; ++n) _Pragma("unroll") for (int k = 0; k < 2; ++k) dst[n][k] = *(const PG8_LAS bf16x8*)(lds + PG8_SB(b, h) + boff + n * 2048 + k * 1024); } while (0)
; #define PG8_MMA(ai, bj, At, Bt) do { __builtin_amdgcn_s_setprio(1); _Pragma("unroll") for (int m = 0; m < 4; ++m) _Pragma("unroll") for (int n = 0; n < 2; ++n) _Pragma("unroll") for (int k = 0; k < 2; ++k) \
;         acc[ai][bj][m][n] = __builtin_amdgcn_mfma_f32_16x16x32_bf16(Bt[n][k], At[m][k], acc[ai][bj][m][n], 0, 0, 0); __builtin_amdgcn_s_setprio(0); } while (0)
; #define PG8_WAIT_V(n) asm volatile("s_waitcnt vmcnt(" #n ")" ::: "memory")
; #define PG8_WAIT_L(n) do { asm volatile("s_waitcnt lgkmcnt(" #n ")" ::: "memory"); __builtin_amdgcn_s_waitcnt(0xC07F); } while (0)
; #define PG8_BAR __builtin_amdgcn_s_barrier()
; #define PG8_SCHED __builtin_amdgcn_sched_barrier(0)
; template <class Epi, class Sched, bool SEG3 = false>
; __device__ __forceinline__ void gemm_phase(PG8_LAS unsigned char* lds, const Gemm g, const Sched& S, const Epi& E) {
;     ...
;             PG8_LDB(B0, 1, 0); PG8_LDB(B1, 1, 1); PG8_SCHED; PG8_LDA(At, 1, 0); PG8_STAGE(PG8_SA(0, 1), a2 + hsA, voffA);
;             PG8_WAIT_V(8); PG8_WAIT_L(0); PG8_BAR; if (cur.half != 1) { PG8_MMA(0, 0, At, B0); PG8_MMA(0, 1, At, B1); } PG8_BAR; PG8_SCHED;
;             PG8_LDA(At, 1, 1); PG8_STAGE(PG8_SB(1, 0), b3, voffB); PG8_STAGE(PG8_SB(1, 1), b3 + hsB, voffB); PG8_STAGE(PG8_SA(1, 0), a3, voffA);
;             PG8_WAIT_V(8); PG8_WAIT_L(0); PG8_BAR; if (cur.half != 0) { PG8_MMA(1, 0, At, B0); PG8_MMA(1, 1, At, B1); } PG8_BAR; PG8_SCHED;
;         }
	s_nop 0
	ds_read_b128 v[18:21], v188
	ds_read_b128 v[22:25], v188 offset:1024
	ds_read_b128 v[66:69], v188 offset:2048
	ds_read_b128 v[70:73], v188 offset:3072
	ds_read_b128 v[146:149], v189
	ds_read_b128 v[174:177], v189 offset:1024
	ds_read_b128 v[178:181], v189 offset:2048
	ds_read_b128 v[210:213], v189 offset:3072
	s_add_u32 s12, s12, 0x40000
	s_addc_u32 s13, s13, 0
	s_mov_b32 m0, s73
	v_lshl_add_u64 v[252:253], s[12:13], 0, v[150:151]
	ds_read_b128 v[214:217], v187 offset:32768
	ds_read_b128 v[218:221], v187 offset:33792
	ds_read_b128 v[222:225], v187 offset:34816
	ds_read_b128 v[226:229], v187 offset:35840
	ds_read_b128 v[230:233], v187 offset:36864
	ds_read_b128 v[234:237], v187 offset:37888
	ds_read_b128 v[238:241], v187 offset:38912
	ds_read_b128 v[242:245], v187 offset:39936
	global_load_lds_dwordx4 v[252:253], off
	v_lshl_add_u64 v[252:253], s[12:13], 0, v[154:155]
	s_mov_b32 m0, s74
	s_nop 0
	global_load_lds_dwordx4 v[252:253], off
	s_waitcnt vmcnt(8)
	s_waitcnt lgkmcnt(0)
	s_waitcnt lgkmcnt(0)
	s_barrier
	v_mfma_f32_16x16x32_bf16 v[142:145], v[18:21], v[214:217], v[142:145]
	v_mfma_f32_16x16x32_bf16 v[138:141], v[66:69], v[214:217], v[138:141]
	v_mfma_f32_16x16x32_bf16 v[126:129], v[18:21], v[222:225], v[126:129]
	v_mfma_f32_16x16x32_bf16 v[122:125], v[66:69], v[222:225], v[122:125]
	v_mfma_f32_16x16x32_bf16 v[110:113], v[18:21], v[230:233], v[110:113]
	v_mfma_f32_16x16x32_bf16 v[106:109], v[66:69], v[230:233], v[106:109]
	v_mfma_f32_16x16x32_bf16 v[94:97], v[18:21], v[238:241], v[94:97]
	v_mfma_f32_16x16x32_bf16 v[90:93], v[66:69], v[238:241], v[90:93]
	v_mfma_f32_16x16x32_bf16 v[142:145], v[22:25], v[218:221], v[142:145]
	v_mfma_f32_16x16x32_bf16 v[138:141], v[70:73], v[218:221], v[138:141]
	v_mfma_f32_16x16x32_bf16 v[126:129], v[22:25], v[226:229], v[126:129]
	v_mfma_f32_16x16x32_bf16 v[122:125], v[70:73], v[226:229], v[122:125]
	v_mfma_f32_16x16x32_bf16 v[110:113], v[22:25], v[234:237], v[110:113]
	v_mfma_f32_16x16x32_bf16 v[106:109], v[70:73], v[234:237], v[106:109]
	v_mfma_f32_16x16x32_bf16 v[94:97], v[22:25], v[242:245], v[94:97]
	v_mfma_f32_16x16x32_bf16 v[90:93], v[70:73], v[242:245], v[90:93]
	v_mfma_f32_16x16x32_bf16 v[134:137], v[146:149], v[214:217], v[134:137]
	v_mfma_f32_16x16x32_bf16 v[130:133], v[178:181], v[214:217], v[130:133]
	v_mfma_f32_16x16x32_bf16 v[118:121], v[146:149], v[222:225], v[118:121]
	v_mfma_f32_16x16x32_bf16 v[114:117], v[178:181], v[222:225], v[114:117]
	v_mfma_f32_16x16x32_bf16 v[102:105], v[146:149], v[230:233], v[102:105]
	v_mfma_f32_16x16x32_bf16 v[98:101], v[178:181], v[230:233], v[98:101]
	v_mfma_f32_16x16x32_bf16 v[86:89], v[146:149], v[238:241], v[86:89]
	v_mfma_f32_16x16x32_bf16 v[82:85], v[178:181], v[238:241], v[82:85]
	v_mfma_f32_16x16x32_bf16 v[134:137], v[174:177], v[218:221], v[134:137]
	v_mfma_f32_16x16x32_bf16 v[130:133], v[210:213], v[218:221], v[130:133]
	v_mfma_f32_16x16x32_bf16 v[118:121], v[174:177], v[226:229], v[118:121]
	v_mfma_f32_16x16x32_bf16 v[114:117], v[210:213], v[226:229], v[114:117]
	v_mfma_f32_16x16x32_bf16 v[102:105], v[174:177], v[234:237], v[102:105]
	v_mfma_f32_16x16x32_bf16 v[98:101], v[210:213], v[234:237], v[98:101]
	v_mfma_f32_16x16x32_bf16 v[86:89], v[174:177], v[242:245], v[86:89]
	v_mfma_f32_16x16x32_bf16 v[82:85], v[210:213], v[242:245], v[82:85]
	s_barrier
	s_mov_b32 m0, s77
	v_lshl_add_u64 v[182:183], v[182:183], 0, s[30:31]
	s_add_u32 s10, s10, 0x40080
	ds_read_b128 v[214:217], v187 offset:49152
	ds_read_b128 v[218:221], v187 offset:50176
	ds_read_b128 v[222:225], v187 offset:51200
	ds_read_b128 v[226:229], v187 offset:52224
	ds_read_b128 v[230:233], v187 offset:53248
	ds_read_b128 v[234:237], v187 offset:54272
	ds_read_b128 v[238:241], v187 offset:55296
	ds_read_b128 v[242:245], v187 offset:56320
	global_load_lds_dwordx4 v[182:183], off
	v_lshl_add_u64 v[182:183], v[246:247], 0, s[30:31]
	s_mov_b32 m0, s78
	s_addc_u32 s11, s11, 0
	global_load_lds_dwordx4 v[182:183], off
	v_lshl_add_u64 v[182:183], s[10:11], 0, v[152:153]
	s_mov_b32 m0, s82
	s_nop 0
	global_load_lds_dwordx4 v[182:183], off
	v_lshl_add_u64 v[182:183], s[10:11], 0, v[156:157]
	s_mov_b32 m0, s83
	s_nop 0
	global_load_lds_dwordx4 v[182:183], off
	v_lshl_add_u64 v[182:183], v[248:249], 0, s[30:31]
	s_mov_b32 m0, s80
	s_nop 0
	global_load_lds_dwordx4 v[182:183], off
	v_lshl_add_u64 v[182:183], v[250:251], 0, s[30:31]
	s_mov_b32 m0, s81
	s_nop 0
	global_load_lds_dwordx4 v[182:183], off
	s_waitcnt vmcnt(8)
	s_waitcnt lgkmcnt(0)
	s_waitcnt lgkmcnt(0)
	s_barrier
	v_mfma_f32_16x16x32_bf16 v[78:81], v[18:21], v[214:217], v[78:81]
	v_mfma_f32_16x16x32_bf16 v[62:65], v[18:21], v[222:225], v[62:65]
	v_mfma_f32_16x16x32_bf16 v[46:49], v[18:21], v[230:233], v[46:49]
	v_mfma_f32_16x16x32_bf16 v[10:13], v[18:21], v[238:241], v[10:13]
	v_mfma_f32_16x16x32_bf16 v[78:81], v[22:25], v[218:221], v[78:81]
	v_mfma_f32_16x16x32_bf16 v[74:77], v[66:69], v[214:217], v[74:77]
	v_mfma_f32_16x16x32_bf16 v[62:65], v[22:25], v[226:229], v[62:65]
	v_mfma_f32_16x16x32_bf16 v[58:61], v[66:69], v[222:225], v[58:61]
	v_mfma_f32_16x16x32_bf16 v[46:49], v[22:25], v[234:237], v[46:49]
	v_mfma_f32_16x16x32_bf16 v[42:45], v[66:69], v[230:233], v[42:45]
	v_mfma_f32_16x16x32_bf16 v[22:25], v[22:25], v[242:245], v[10:13]
	v_mfma_f32_16x16x32_bf16 v[10:13], v[66:69], v[238:241], v[14:17]
	v_mfma_f32_16x16x32_bf16 v[74:77], v[70:73], v[218:221], v[74:77]
	v_mfma_f32_16x16x32_bf16 v[58:61], v[70:73], v[226:229], v[58:61]
	v_mfma_f32_16x16x32_bf16 v[42:45], v[70:73], v[234:237], v[42:45]
	v_mfma_f32_16x16x32_bf16 v[18:21], v[70:73], v[242:245], v[10:13]
	v_mfma_f32_16x16x32_bf16 v[10:13], v[146:149], v[214:217], v[34:37]
	v_mfma_f32_16x16x32_bf16 v[70:73], v[174:177], v[218:221], v[10:13]
	v_mfma_f32_16x16x32_bf16 v[10:13], v[178:181], v[214:217], v[38:41]
	v_mfma_f32_16x16x32_bf16 v[66:69], v[210:213], v[218:221], v[10:13]
	v_mfma_f32_16x16x32_bf16 v[10:13], v[146:149], v[222:225], v[54:57]
	v_mfma_f32_16x16x32_bf16 v[54:57], v[174:177], v[226:229], v[10:13]
	v_mfma_f32_16x16x32_bf16 v[10:13], v[178:181], v[222:225], v[50:53]
	v_mfma_f32_16x16x32_bf16 v[50:53], v[210:213], v[226:229], v[10:13]
	v_mfma_f32_16x16x32_bf16 v[10:13], v[146:149], v[230:233], v[30:33]
	v_mfma_f32_16x16x32_bf16 v[30:33], v[174:177], v[234:237], v[10:13]
	v_mfma_f32_16x16x32_bf16 v[10:13], v[178:181], v[230:233], v[26:29]
	v_mfma_f32_16x16x32_bf16 v[6:9], v[146:149], v[238:241], v[6:9]
	v_mfma_f32_16x16x32_bf16 v[2:5], v[178:181], v[238:241], v[2:5]
	v_mfma_f32_16x16x32_bf16 v[26:29], v[210:213], v[234:237], v[10:13]
	v_mfma_f32_16x16x32_bf16 v[6:9], v[174:177], v[242:245], v[6:9]
	v_mfma_f32_16x16x32_bf16 v[2:5], v[210:213], v[242:245], v[2:5]
	s_barrier
	s_add_u32 s8, s8, 0x100
	s_addc_u32 s9, s9, 0
	s_add_u32 s17, s17, 0x100
	s_addc_u32 s19, s19, 0
	s_cmp_lt_i32 s20, s75
	s_mov_b32 s10, s20
	s_cbranch_scc1 .LBB0_2680
	s_andn2_b64 vcc, exec, s[36:37]
	s_cbranch_vccnz .LBB0_2683

; #define PG8_STAGE(bufoff, gbase, voff) do { _Pragma("unroll") for (int _i = 0; _i < 2; ++_i) \
;         __builtin_amdgcn_global_load_lds((const unsigned*)((const char*)(gbase) + (voff)[_i]), (PG8_LAS unsigned*)(lds + (bufoff) + ldsw + _i * 8192), 16, 0, 0); } while (0)
; #define PG8_LDA(dst, b, h) do { _Pragma("unroll") for (int m = 0; m < 4; ++m) _Pragma("unroll") for (int k = 0; k < 2; ++k) dst[m][k] = *(const PG8_LAS bf16x8*)(lds + PG8_SA(b, h) + aoff + m * 2048 + k * 1024); } while (0)
; #define PG8_LDB(dst, b, h) do { _Pragma("unroll") for (int n = 0; n < 2; ++n) _Pragma("unroll") for (int k = 0; k < 2; ++k) dst[n][k] = *(const PG8_LAS bf16x8*)(lds + PG8_SB(b, h) + boff + n * 2048 + k * 1024); } while (0)
; #define PG8_MMA(ai, bj, At, Bt) do { __builtin_amdgcn_s_setprio(1); _Pragma("unroll") for (int m = 0; m < 4; ++m) _Pragma("unroll") for (int n = 0; n < 2; ++n) _Pragma("unroll") for (int k = 0; k < 2; ++k) \
;         acc[ai][bj][m][n] = __builtin_amdgcn_mfma_f32_16x16x32_bf16(Bt[n][k], At[m][k], acc[ai][bj][m][n], 0, 0, 0); __builtin_amdgcn_s_setprio(0); } while (0)
; #define PG8_WAIT_V(n) asm volatile("s_waitcnt vmcnt(" #n ")" ::: "memory")
; #define PG8_WAIT_L(n) do { asm volatile("s_waitcnt lgkmcnt(" #n ")" ::: "memory"); __builtin_amdgcn_s_waitcnt(0xC07F); } while (0)
; #define PG8_BAR __builtin_amdgcn_s_barrier()
; #define PG8_SCHED __builtin_amdgcn_sched_barrier(0)
; template <class Epi, class Sched, bool SEG3 = false>
; __device__ __forceinline__ void gemm_phase(PG8_LAS unsigned char* lds, const Gemm g, const Sched& S, const Epi& E) {
;     ...
;             PG8_WAIT_V(8); PG8_WAIT_L(0); PG8_BAR; if (cur.half != 0) { PG8_MMA(1, 0, At, B0); PG8_MMA(1, 1, At, B1); } PG8_BAR; PG8_SCHED;
;             PG8_LDB(B0, 1, 0); PG8_LDB(B1, 1, 1); PG8_SCHED; PG8_LDA(At, 1, 0); PG8_STAGE(PG8_SA(0, 1), a2 + hsA, voffA);
;             PG8_WAIT_V(8); PG8_WAIT_L(0); PG8_BAR; if (cur.half != 1) { PG8_MMA(0, 0, At, B0); PG8_MMA(0, 1, At, B1); } PG8_BAR; PG8_SCHED;
.Lfi_b_10:
	s_mov_b32 s98, 0
	s_waitcnt lgkmcnt(0)
	s_barrier
	v_mfma_f32_16x16x32_bf16 v[62:65], v[124:127], v[164:167], v[62:65]
	v_mfma_f32_16x16x32_bf16 v[58:61], v[140:143], v[164:167], v[58:61]
	v_mfma_f32_16x16x32_bf16 v[46:49], v[124:127], v[172:175], v[46:49]
	v_mfma_f32_16x16x32_bf16 v[42:45], v[140:143], v[172:175], v[42:45]
	v_mfma_f32_16x16x32_bf16 v[30:33], v[124:127], v[180:183], v[30:33]
	v_mfma_f32_16x16x32_bf16 v[26:29], v[140:143], v[180:183], v[26:29]
	v_mfma_f32_16x16x32_bf16 v[14:17], v[124:127], v[188:191], v[14:17]
	v_mfma_f32_16x16x32_bf16 v[10:13], v[140:143], v[188:191], v[10:13]
	v_mfma_f32_16x16x32_bf16 v[62:65], v[132:135], v[168:171], v[62:65]
	v_mfma_f32_16x16x32_bf16 v[58:61], v[144:147], v[168:171], v[58:61]
	v_mfma_f32_16x16x32_bf16 v[46:49], v[132:135], v[176:179], v[46:49]
	v_mfma_f32_16x16x32_bf16 v[42:45], v[144:147], v[176:179], v[42:45]
	v_mfma_f32_16x16x32_bf16 v[30:33], v[132:135], v[184:187], v[30:33]
	v_mfma_f32_16x16x32_bf16 v[26:29], v[144:147], v[184:187], v[26:29]
	v_mfma_f32_16x16x32_bf16 v[14:17], v[132:135], v[192:195], v[14:17]
	v_mfma_f32_16x16x32_bf16 v[10:13], v[144:147], v[192:195], v[10:13]
	v_mfma_f32_16x16x32_bf16 v[54:57], v[148:151], v[164:167], v[54:57]
	v_mfma_f32_16x16x32_bf16 v[50:53], v[156:159], v[164:167], v[50:53]
	v_mfma_f32_16x16x32_bf16 v[38:41], v[148:151], v[172:175], v[38:41]
	v_mfma_f32_16x16x32_bf16 v[34:37], v[156:159], v[172:175], v[34:37]
	v_mfma_f32_16x16x32_bf16 v[22:25], v[148:151], v[180:183], v[22:25]
	v_mfma_f32_16x16x32_bf16 v[18:21], v[156:159], v[180:183], v[18:21]
	v_mfma_f32_16x16x32_bf16 v[6:9], v[148:151], v[188:191], v[6:9]
	v_mfma_f32_16x16x32_bf16 v[2:5], v[156:159], v[188:191], v[2:5]
	v_mfma_f32_16x16x32_bf16 v[54:57], v[152:155], v[168:171], v[54:57]
	v_mfma_f32_16x16x32_bf16 v[50:53], v[160:163], v[168:171], v[50:53]
	v_mfma_f32_16x16x32_bf16 v[38:41], v[152:155], v[176:179], v[38:41]
	v_mfma_f32_16x16x32_bf16 v[34:37], v[160:163], v[176:179], v[34:37]
	v_mfma_f32_16x16x32_bf16 v[22:25], v[152:155], v[184:187], v[22:25]
	v_mfma_f32_16x16x32_bf16 v[18:21], v[160:163], v[184:187], v[18:21]
	v_mfma_f32_16x16x32_bf16 v[6:9], v[152:155], v[192:195], v[6:9]
	v_mfma_f32_16x16x32_bf16 v[2:5], v[160:163], v[192:195], v[2:5]
	s_barrier
	ds_read_b128 v[124:127], v234
	ds_read_b128 v[132:135], v234 offset:1024
	ds_read_b128 v[140:143], v234 offset:2048
	ds_read_b128 v[144:147], v234 offset:3072
	ds_read_b128 v[148:151], v235
	ds_read_b128 v[152:155], v235 offset:1024
	ds_read_b128 v[156:159], v235 offset:2048
	ds_read_b128 v[160:163], v235 offset:3072
	s_add_u32 s30, s30, 0x40000
	s_addc_u32 s31, s31, 0
	s_mov_b32 m0, s52
	v_lshl_add_u64 v[102:103], s[30:31], 0, v[196:197]
	ds_read_b128 v[164:167], v233 offset:32768
	ds_read_b128 v[168:171], v233 offset:33792
	ds_read_b128 v[172:175], v233 offset:34816
	ds_read_b128 v[176:179], v233 offset:35840
	ds_read_b128 v[180:183], v233 offset:36864
	ds_read_b128 v[184:187], v233 offset:37888
	ds_read_b128 v[188:191], v233 offset:38912
	ds_read_b128 v[192:195], v233 offset:39936
	global_load_lds_dwordx4 v[102:103], off
	v_lshl_add_u64 v[102:103], s[30:31], 0, v[200:201]
	s_mov_b32 m0, s53
	s_nop 0
	global_load_lds_dwordx4 v[102:103], off
	s_waitcnt vmcnt(8)
	s_waitcnt lgkmcnt(0)
	s_waitcnt lgkmcnt(0)
	s_barrier
	v_mfma_f32_16x16x32_bf16 v[136:139], v[124:127], v[164:167], v[136:139]
	v_mfma_f32_16x16x32_bf16 v[128:131], v[140:143], v[164:167], v[128:131]
	v_mfma_f32_16x16x32_bf16 v[112:115], v[124:127], v[172:175], v[112:115]
	v_mfma_f32_16x16x32_bf16 v[108:111], v[140:143], v[172:175], v[108:111]
	v_mfma_f32_16x16x32_bf16 v[94:97], v[124:127], v[180:183], v[94:97]
	v_mfma_f32_16x16x32_bf16 v[90:93], v[140:143], v[180:183], v[90:93]
	v_mfma_f32_16x16x32_bf16 v[78:81], v[124:127], v[188:191], v[78:81]
	v_mfma_f32_16x16x32_bf16 v[74:77], v[140:143], v[188:191], v[74:77]
	v_mfma_f32_16x16x32_bf16 v[136:139], v[132:135], v[168:171], v[136:139]
	v_mfma_f32_16x16x32_bf16 v[128:131], v[144:147], v[168:171], v[128:131]
	v_mfma_f32_16x16x32_bf16 v[112:115], v[132:135], v[176:179], v[112:115]
	v_mfma_f32_16x16x32_bf16 v[108:111], v[144:147], v[176:179], v[108:111]
	v_mfma_f32_16x16x32_bf16 v[94:97], v[132:135], v[184:187], v[94:97]
	v_mfma_f32_16x16x32_bf16 v[90:93], v[144:147], v[184:187], v[90:93]
	v_mfma_f32_16x16x32_bf16 v[78:81], v[132:135], v[192:195], v[78:81]
	v_mfma_f32_16x16x32_bf16 v[74:77], v[144:147], v[192:195], v[74:77]
	v_mfma_f32_16x16x32_bf16 v[120:123], v[148:151], v[164:167], v[120:123]
	v_mfma_f32_16x16x32_bf16 v[116:119], v[156:159], v[164:167], v[116:119]
	v_mfma_f32_16x16x32_bf16 v[102:105], v[148:151], v[172:175], v[104:107]
	v_mfma_f32_16x16x32_bf16 v[98:101], v[156:159], v[172:175], v[98:101]
	v_mfma_f32_16x16x32_bf16 v[86:89], v[148:151], v[180:183], v[86:89]
	v_mfma_f32_16x16x32_bf16 v[82:85], v[156:159], v[180:183], v[82:85]
	v_mfma_f32_16x16x32_bf16 v[70:73], v[148:151], v[188:191], v[70:73]
	v_mfma_f32_16x16x32_bf16 v[66:69], v[156:159], v[188:191], v[66:69]
	v_mfma_f32_16x16x32_bf16 v[120:123], v[152:155], v[168:171], v[120:123]
	v_mfma_f32_16x16x32_bf16 v[116:119], v[160:163], v[168:171], v[116:119]
	v_mfma_f32_16x16x32_bf16 v[104:107], v[152:155], v[176:179], v[102:105]
	v_mfma_f32_16x16x32_bf16 v[100:103], v[160:163], v[176:179], v[98:101]
	v_mfma_f32_16x16x32_bf16 v[86:89], v[152:155], v[184:187], v[86:89]
	v_mfma_f32_16x16x32_bf16 v[82:85], v[160:163], v[184:187], v[82:85]
	v_mfma_f32_16x16x32_bf16 v[70:73], v[152:155], v[192:195], v[70:73]
	v_mfma_f32_16x16x32_bf16 v[66:69], v[160:163], v[192:195], v[66:69]
	s_barrier
; #define PG8_STAGE(bufoff, gbase, voff) do { _Pragma("unroll") for (int _i = 0; _i < 2; ++_i) \
;         __builtin_amdgcn_global_load_lds((const unsigned*)((const char*)(gbase) + (voff)[_i]), (PG8_LAS unsigned*)(lds + (bufoff) + ldsw + _i * 8192), 16, 0, 0); } while (0)
; #define PG8_LDA(dst, b, h) do { _Pragma("unroll") for (int m = 0; m < 4; ++m) _Pragma("unroll") for (int k = 0; k < 2; ++k) dst[m][k] = *(const PG8_LAS bf16x8*)(lds + PG8_SA(b, h) + aoff + m * 2048 + k * 1024); } while (0)
; #define PG8_MMA(ai, bj, At, Bt) do { __builtin_amdgcn_s_setprio(1); _Pragma("unroll") for (int m = 0; m < 4; ++m) _Pragma("unroll") for (int n = 0; n < 2; ++n) _Pragma("unroll") for (int k = 0; k < 2; ++k) \
;         acc[ai][bj][m][n] = __builtin_amdgcn_mfma_f32_16x16x32_bf16(Bt[n][k], At[m][k], acc[ai][bj][m][n], 0, 0, 0); __builtin_amdgcn_s_setprio(0); } while (0)
; #define PG8_WAIT_V(n) asm volatile("s_waitcnt vmcnt(" #n ")" ::: "memory")
; #define PG8_WAIT_L(n) do { asm volatile("s_waitcnt lgkmcnt(" #n ")" ::: "memory"); __builtin_amdgcn_s_waitcnt(0xC07F); } while (0)
; #define PG8_BAR __builtin_amdgcn_s_barrier()
; #define PG8_SCHED __builtin_amdgcn_sched_barrier(0)
; template <class Epi, class Sched, bool SEG3 = false>
; __device__ __forceinline__ void gemm_phase(PG8_LAS unsigned char* lds, const Gemm g, const Sched& S, const Epi& E) {
;     ...
;             PG8_LDA(At, 1, 1); PG8_STAGE(PG8_SB(1, 0), b3, voffB); PG8_STAGE(PG8_SB(1, 1), b3 + hsB, voffB); PG8_STAGE(PG8_SA(1, 0), a3, voffA);
;             PG8_WAIT_V(8); PG8_WAIT_L(0); PG8_BAR; if (cur.half != 0) { PG8_MMA(1, 0, At, B0); PG8_MMA(1, 1, At, B1); } PG8_BAR; PG8_SCHED;
	s_mov_b32 m0, s55
	v_lshl_add_u64 v[98:99], v[214:215], 0, s[12:13]
	s_add_u32 s28, s28, 0x40080
	ds_read_b128 v[164:167], v233 offset:49152
	ds_read_b128 v[168:171], v233 offset:50176
	ds_read_b128 v[172:175], v233 offset:51200
	ds_read_b128 v[176:179], v233 offset:52224
	ds_read_b128 v[180:183], v233 offset:53248
	ds_read_b128 v[184:187], v233 offset:54272
	ds_read_b128 v[188:191], v233 offset:55296
	ds_read_b128 v[192:195], v233 offset:56320
	global_load_lds_dwordx4 v[98:99], off
	v_lshl_add_u64 v[98:99], v[216:217], 0, s[12:13]
	s_mov_b32 m0, s56
	s_addc_u32 s29, s29, 0
	global_load_lds_dwordx4 v[98:99], off
	v_lshl_add_u64 v[98:99], s[28:29], 0, v[198:199]
	s_mov_b32 m0, s59
	s_nop 0
	global_load_lds_dwordx4 v[98:99], off
	v_lshl_add_u64 v[98:99], s[28:29], 0, v[202:203]
	s_mov_b32 m0, s60
	s_nop 0
	global_load_lds_dwordx4 v[98:99], off
	v_lshl_add_u64 v[98:99], v[218:219], 0, s[12:13]
	s_mov_b32 m0, s57
	s_nop 0
	global_load_lds_dwordx4 v[98:99], off
	v_lshl_add_u64 v[98:99], v[220:221], 0, s[12:13]
	s_mov_b32 m0, s58
	s_nop 0
	global_load_lds_dwordx4 v[98:99], off
	s_waitcnt vmcnt(8)
	s_waitcnt lgkmcnt(0)
	s_waitcnt lgkmcnt(0)
	s_barrier
	v_mfma_f32_16x16x32_bf16 v[62:65], v[124:127], v[164:167], v[62:65]
	v_mfma_f32_16x16x32_bf16 v[58:61], v[140:143], v[164:167], v[58:61]
	v_mfma_f32_16x16x32_bf16 v[46:49], v[124:127], v[172:175], v[46:49]
	v_mfma_f32_16x16x32_bf16 v[42:45], v[140:143], v[172:175], v[42:45]
	v_mfma_f32_16x16x32_bf16 v[30:33], v[124:127], v[180:183], v[30:33]
	v_mfma_f32_16x16x32_bf16 v[26:29], v[140:143], v[180:183], v[26:29]
	v_mfma_f32_16x16x32_bf16 v[14:17], v[124:127], v[188:191], v[14:17]
	v_mfma_f32_16x16x32_bf16 v[10:13], v[140:143], v[188:191], v[10:13]
	v_mfma_f32_16x16x32_bf16 v[62:65], v[132:135], v[168:171], v[62:65]
	v_mfma_f32_16x16x32_bf16 v[58:61], v[144:147], v[168:171], v[58:61]
	v_mfma_f32_16x16x32_bf16 v[46:49], v[132:135], v[176:179], v[46:49]
	v_mfma_f32_16x16x32_bf16 v[42:45], v[144:147], v[176:179], v[42:45]
	v_mfma_f32_16x16x32_bf16 v[30:33], v[132:135], v[184:187], v[30:33]
	v_mfma_f32_16x16x32_bf16 v[26:29], v[144:147], v[184:187], v[26:29]
	v_mfma_f32_16x16x32_bf16 v[14:17], v[132:135], v[192:195], v[14:17]
	v_mfma_f32_16x16x32_bf16 v[10:13], v[144:147], v[192:195], v[10:13]
	v_mfma_f32_16x16x32_bf16 v[54:57], v[148:151], v[164:167], v[54:57]
	v_mfma_f32_16x16x32_bf16 v[50:53], v[156:159], v[164:167], v[50:53]
	v_mfma_f32_16x16x32_bf16 v[38:41], v[148:151], v[172:175], v[38:41]
	v_mfma_f32_16x16x32_bf16 v[34:37], v[156:159], v[172:175], v[34:37]
	v_mfma_f32_16x16x32_bf16 v[22:25], v[148:151], v[180:183], v[22:25]
	v_mfma_f32_16x16x32_bf16 v[18:21], v[156:159], v[180:183], v[18:21]
	v_mfma_f32_16x16x32_bf16 v[6:9], v[148:151], v[188:191], v[6:9]
	v_mfma_f32_16x16x32_bf16 v[2:5], v[156:159], v[188:191], v[2:5]
	v_mfma_f32_16x16x32_bf16 v[54:57], v[152:155], v[168:171], v[54:57]
	v_mfma_f32_16x16x32_bf16 v[50:53], v[160:163], v[168:171], v[50:53]
	v_mfma_f32_16x16x32_bf16 v[38:41], v[152:155], v[176:179], v[38:41]
	v_mfma_f32_16x16x32_bf16 v[34:37], v[160:163], v[176:179], v[34:37]
	v_mfma_f32_16x16x32_bf16 v[22:25], v[152:155], v[184:187], v[22:25]
	v_mfma_f32_16x16x32_bf16 v[18:21], v[160:163], v[184:187], v[18:21]
	v_mfma_f32_16x16x32_bf16 v[6:9], v[152:155], v[192:195], v[6:9]
	v_mfma_f32_16x16x32_bf16 v[2:5], v[160:163], v[192:195], v[2:5]
	s_barrier
	s_add_u32 s6, s6, 0x100
	s_addc_u32 s7, s7, 0
	s_add_u32 s19, s19, 0x100
	s_addc_u32 s27, s27, 0
	s_cmp_lt_i32 s65, s25
	s_mov_b32 s28, s65
	s_cbranch_scc1 .LBB0_4031
	s_andn2_b64 vcc, exec, s[14:15]
	s_cbranch_vccnz .LBB0_4034

; #define PG8_STAGE(bufoff, gbase, voff) do { _Pragma("unroll") for (int _i = 0; _i < 2; ++_i) \
;         __builtin_amdgcn_global_load_lds((const unsigned*)((const char*)(gbase) + (voff)[_i]), (PG8_LAS unsigned*)(lds + (bufoff) + ldsw + _i * 8192), 16, 0, 0); } while (0)
; #define PG8_LDA(dst, b, h) do { _Pragma("unroll") for (int m = 0; m < 4; ++m) _Pragma("unroll") for (int k = 0; k < 2; ++k) dst[m][k] = *(const PG8_LAS bf16x8*)(lds + PG8_SA(b, h) + aoff + m * 2048 + k * 1024); } while (0)
; #define PG8_LDB(dst, b, h) do { _Pragma("unroll") for (int n = 0; n < 2; ++n) _Pragma("unroll") for (int k = 0; k < 2; ++k) dst[n][k] = *(const PG8_LAS bf16x8*)(lds + PG8_SB(b, h) + boff + n * 2048 + k * 1024); } while (0)
; #define PG8_MMA(ai, bj, At, Bt) do { __builtin_amdgcn_s_setprio(1); _Pragma("unroll") for (int m = 0; m < 4; ++m) _Pragma("unroll") for (int n = 0; n < 2; ++n) _Pragma("unroll") for (int k = 0; k < 2; ++k) \
;         acc[ai][bj][m][n] = __builtin_amdgcn_mfma_f32_16x16x32_bf16(Bt[n][k], At[m][k], acc[ai][bj][m][n], 0, 0, 0); __builtin_amdgcn_s_setprio(0); } while (0)
; #define PG8_WAIT_V(n) asm volatile("s_waitcnt vmcnt(" #n ")" ::: "memory")
; #define PG8_WAIT_L(n) do { asm volatile("s_waitcnt lgkmcnt(" #n ")" ::: "memory"); __builtin_amdgcn_s_waitcnt(0xC07F); } while (0)
; #define PG8_BAR __builtin_amdgcn_s_barrier()
; #define PG8_SCHED __builtin_amdgcn_sched_barrier(0)
; template <class Epi, class Sched, bool SEG3 = false>
; __device__ __forceinline__ void gemm_phase(PG8_LAS unsigned char* lds, const Gemm g, const Sched& S, const Epi& E) {
;     ...
;             PG8_WAIT_V(8); PG8_WAIT_L(0); PG8_BAR; if (cur.half != 0) { PG8_MMA(1, 0, At, B0); PG8_MMA(1, 1, At, B1); } PG8_BAR; PG8_SCHED;
;             PG8_LDB(B0, 1, 0); PG8_LDB(B1, 1, 1); PG8_SCHED; PG8_LDA(At, 1, 0); PG8_STAGE(PG8_SA(0, 1), a2 + hsA, voffA);
;             PG8_WAIT_V(8); PG8_WAIT_L(0); PG8_BAR; if (cur.half != 1) { PG8_MMA(0, 0, At, B0); PG8_MMA(0, 1, At, B1); } PG8_BAR; PG8_SCHED;
.Lfi_b_11:
	s_mov_b32 s98, 0
	s_waitcnt lgkmcnt(0)
	s_barrier
	v_mfma_f32_16x16x32_bf16 v[78:81], v[34:37], v[162:165], v[78:81]
	v_mfma_f32_16x16x32_bf16 v[74:77], v[42:45], v[162:165], v[74:77]
	v_mfma_f32_16x16x32_bf16 v[62:65], v[34:37], v[186:189], v[62:65]
	v_mfma_f32_16x16x32_bf16 v[58:61], v[42:45], v[186:189], v[58:61]
	v_mfma_f32_16x16x32_bf16 v[30:33], v[34:37], v[194:197], v[30:33]
	v_mfma_f32_16x16x32_bf16 v[26:29], v[42:45], v[194:197], v[26:29]
	v_mfma_f32_16x16x32_bf16 v[14:17], v[34:37], v[202:205], v[14:17]
	v_mfma_f32_16x16x32_bf16 v[10:13], v[42:45], v[202:205], v[10:13]
	v_mfma_f32_16x16x32_bf16 v[78:81], v[38:41], v[166:169], v[78:81]
	v_mfma_f32_16x16x32_bf16 v[74:77], v[46:49], v[166:169], v[74:77]
	v_mfma_f32_16x16x32_bf16 v[62:65], v[38:41], v[190:193], v[62:65]
	v_mfma_f32_16x16x32_bf16 v[58:61], v[46:49], v[190:193], v[58:61]
	v_mfma_f32_16x16x32_bf16 v[30:33], v[38:41], v[198:201], v[30:33]
	v_mfma_f32_16x16x32_bf16 v[26:29], v[46:49], v[198:201], v[26:29]
	v_mfma_f32_16x16x32_bf16 v[14:17], v[38:41], v[214:217], v[14:17]
	v_mfma_f32_16x16x32_bf16 v[10:13], v[46:49], v[214:217], v[10:13]
	v_mfma_f32_16x16x32_bf16 v[22:25], v[114:117], v[194:197], v[22:25]
	v_mfma_f32_16x16x32_bf16 v[18:21], v[138:141], v[194:197], v[18:21]
	v_mfma_f32_16x16x32_bf16 v[6:9], v[114:117], v[202:205], v[6:9]
	v_mfma_f32_16x16x32_bf16 v[2:5], v[138:141], v[202:205], v[2:5]
	v_mfma_f32_16x16x32_bf16 v[34:37], v[114:117], v[162:165], v[70:73]
	v_mfma_f32_16x16x32_bf16 v[38:41], v[138:141], v[162:165], v[66:69]
	v_mfma_f32_16x16x32_bf16 v[42:45], v[114:117], v[186:189], v[54:57]
	v_mfma_f32_16x16x32_bf16 v[46:49], v[138:141], v[186:189], v[50:53]
	v_mfma_f32_16x16x32_bf16 v[22:25], v[126:129], v[198:201], v[22:25]
	v_mfma_f32_16x16x32_bf16 v[18:21], v[150:153], v[198:201], v[18:21]
	v_mfma_f32_16x16x32_bf16 v[6:9], v[126:129], v[214:217], v[6:9]
	v_mfma_f32_16x16x32_bf16 v[2:5], v[150:153], v[214:217], v[2:5]
	v_mfma_f32_16x16x32_bf16 v[34:37], v[126:129], v[166:169], v[34:37]
	v_mfma_f32_16x16x32_bf16 v[38:41], v[150:153], v[166:169], v[38:41]
	v_mfma_f32_16x16x32_bf16 v[42:45], v[126:129], v[190:193], v[42:45]
	v_mfma_f32_16x16x32_bf16 v[46:49], v[150:153], v[190:193], v[46:49]
	s_barrier
	ds_read_b128 v[50:53], v210
	ds_read_b128 v[54:57], v210 offset:1024
	ds_read_b128 v[66:69], v210 offset:2048
	ds_read_b128 v[70:73], v210 offset:3072
	ds_read_b128 v[114:117], v211
	ds_read_b128 v[126:129], v211 offset:1024
	ds_read_b128 v[138:141], v211 offset:2048
	ds_read_b128 v[150:153], v211 offset:3072
	s_add_u32 s42, s42, 0x40000
	s_addc_u32 s43, s43, 0
	s_mov_b32 m0, s54
	v_lshl_add_u64 v[226:227], s[42:43], 0, v[170:171]
	ds_read_b128 v[162:165], v209 offset:32768
	ds_read_b128 v[166:169], v209 offset:33792
	ds_read_b128 v[186:189], v209 offset:34816
	ds_read_b128 v[190:193], v209 offset:35840
	ds_read_b128 v[194:197], v209 offset:36864
	ds_read_b128 v[198:201], v209 offset:37888
	ds_read_b128 v[202:205], v209 offset:38912
	ds_read_b128 v[214:217], v209 offset:39936
	global_load_lds_dwordx4 v[226:227], off
	v_lshl_add_u64 v[226:227], s[42:43], 0, v[174:175]
	s_mov_b32 m0, s55
	s_nop 0
	global_load_lds_dwordx4 v[226:227], off
	s_waitcnt vmcnt(8)
	s_waitcnt lgkmcnt(0)
	s_waitcnt lgkmcnt(0)
	s_barrier
	v_mfma_f32_16x16x32_bf16 v[158:161], v[50:53], v[162:165], v[158:161]
	v_mfma_f32_16x16x32_bf16 v[154:157], v[66:69], v[162:165], v[154:157]
	v_mfma_f32_16x16x32_bf16 v[134:137], v[50:53], v[186:189], v[134:137]
	v_mfma_f32_16x16x32_bf16 v[130:133], v[66:69], v[186:189], v[130:133]
	v_mfma_f32_16x16x32_bf16 v[110:113], v[50:53], v[194:197], v[110:113]
	v_mfma_f32_16x16x32_bf16 v[106:109], v[66:69], v[194:197], v[106:109]
	v_mfma_f32_16x16x32_bf16 v[94:97], v[50:53], v[202:205], v[94:97]
	v_mfma_f32_16x16x32_bf16 v[90:93], v[66:69], v[202:205], v[90:93]
	v_mfma_f32_16x16x32_bf16 v[158:161], v[54:57], v[166:169], v[158:161]
	v_mfma_f32_16x16x32_bf16 v[154:157], v[70:73], v[166:169], v[154:157]
	v_mfma_f32_16x16x32_bf16 v[134:137], v[54:57], v[190:193], v[134:137]
	v_mfma_f32_16x16x32_bf16 v[130:133], v[70:73], v[190:193], v[130:133]
	v_mfma_f32_16x16x32_bf16 v[110:113], v[54:57], v[198:201], v[110:113]
	v_mfma_f32_16x16x32_bf16 v[106:109], v[70:73], v[198:201], v[106:109]
	v_mfma_f32_16x16x32_bf16 v[94:97], v[54:57], v[214:217], v[94:97]
	v_mfma_f32_16x16x32_bf16 v[90:93], v[70:73], v[214:217], v[90:93]
	v_mfma_f32_16x16x32_bf16 v[146:149], v[114:117], v[162:165], v[146:149]
	v_mfma_f32_16x16x32_bf16 v[142:145], v[138:141], v[162:165], v[142:145]
	v_mfma_f32_16x16x32_bf16 v[122:125], v[114:117], v[186:189], v[122:125]
	v_mfma_f32_16x16x32_bf16 v[118:121], v[138:141], v[186:189], v[118:121]
	v_mfma_f32_16x16x32_bf16 v[102:105], v[114:117], v[194:197], v[102:105]
	v_mfma_f32_16x16x32_bf16 v[98:101], v[138:141], v[194:197], v[98:101]
	v_mfma_f32_16x16x32_bf16 v[86:89], v[114:117], v[202:205], v[86:89]
	v_mfma_f32_16x16x32_bf16 v[82:85], v[138:141], v[202:205], v[82:85]
	v_mfma_f32_16x16x32_bf16 v[146:149], v[126:129], v[166:169], v[146:149]
	v_mfma_f32_16x16x32_bf16 v[142:145], v[150:153], v[166:169], v[142:145]
	v_mfma_f32_16x16x32_bf16 v[122:125], v[126:129], v[190:193], v[122:125]
	v_mfma_f32_16x16x32_bf16 v[118:121], v[150:153], v[190:193], v[118:121]
	v_mfma_f32_16x16x32_bf16 v[102:105], v[126:129], v[198:201], v[102:105]
	v_mfma_f32_16x16x32_bf16 v[98:101], v[150:153], v[198:201], v[98:101]
	v_mfma_f32_16x16x32_bf16 v[86:89], v[126:129], v[214:217], v[86:89]
	v_mfma_f32_16x16x32_bf16 v[82:85], v[150:153], v[214:217], v[82:85]
	s_barrier
; #define PG8_STAGE(bufoff, gbase, voff) do { _Pragma("unroll") for (int _i = 0; _i < 2; ++_i) \
;         __builtin_amdgcn_global_load_lds((const unsigned*)((const char*)(gbase) + (voff)[_i]), (PG8_LAS unsigned*)(lds + (bufoff) + ldsw + _i * 8192), 16, 0, 0); } while (0)
; #define PG8_LDA(dst, b, h) do { _Pragma("unroll") for (int m = 0; m < 4; ++m) _Pragma("unroll") for (int k = 0; k < 2; ++k) dst[m][k] = *(const PG8_LAS bf16x8*)(lds + PG8_SA(b, h) + aoff + m * 2048 + k * 1024); } while (0)
; #define PG8_MMA(ai, bj, At, Bt) do { __builtin_amdgcn_s_setprio(1); _Pragma("unroll") for (int m = 0; m < 4; ++m) _Pragma("unroll") for (int n = 0; n < 2; ++n) _Pragma("unroll") for (int k = 0; k < 2; ++k) \
;         acc[ai][bj][m][n] = __builtin_amdgcn_mfma_f32_16x16x32_bf16(Bt[n][k], At[m][k], acc[ai][bj][m][n], 0, 0, 0); __builtin_amdgcn_s_setprio(0); } while (0)
; #define PG8_WAIT_V(n) asm volatile("s_waitcnt vmcnt(" #n ")" ::: "memory")
; #define PG8_WAIT_L(n) do { asm volatile("s_waitcnt lgkmcnt(" #n ")" ::: "memory"); __builtin_amdgcn_s_waitcnt(0xC07F); } while (0)
; #define PG8_BAR __builtin_amdgcn_s_barrier()
; #define PG8_SCHED __builtin_amdgcn_sched_barrier(0)
; template <class Epi, class Sched, bool SEG3 = false>
; __device__ __forceinline__ void gemm_phase(PG8_LAS unsigned char* lds, const Gemm g, const Sched& S, const Epi& E) {
;     ...
;             PG8_LDA(At, 1, 1); PG8_STAGE(PG8_SB(1, 0), b3, voffB); PG8_STAGE(PG8_SB(1, 1), b3 + hsB, voffB); PG8_STAGE(PG8_SA(1, 0), a3, voffA);
;             PG8_WAIT_V(8); PG8_WAIT_L(0); PG8_BAR; if (cur.half != 0) { PG8_MMA(1, 0, At, B0); PG8_MMA(1, 1, At, B1); } PG8_BAR; PG8_SCHED;
	s_mov_b32 m0, s58
	v_lshl_add_u64 v[218:219], v[218:219], 0, s[18:19]
	s_add_u32 s40, s40, 0x40080
	ds_read_b128 v[162:165], v209 offset:49152
	ds_read_b128 v[166:169], v209 offset:50176
	ds_read_b128 v[186:189], v209 offset:51200
	ds_read_b128 v[190:193], v209 offset:52224
	ds_read_b128 v[194:197], v209 offset:53248
	ds_read_b128 v[198:201], v209 offset:54272
	ds_read_b128 v[202:205], v209 offset:55296
	ds_read_b128 v[214:217], v209 offset:56320
	global_load_lds_dwordx4 v[218:219], off
	v_lshl_add_u64 v[218:219], v[220:221], 0, s[18:19]
	s_mov_b32 m0, s59
	s_addc_u32 s41, s41, 0
	global_load_lds_dwordx4 v[218:219], off
	v_lshl_add_u64 v[218:219], s[40:41], 0, v[172:173]
	s_mov_b32 m0, s62
	s_nop 0
	global_load_lds_dwordx4 v[218:219], off
	v_lshl_add_u64 v[218:219], s[40:41], 0, v[176:177]
	s_mov_b32 m0, s63
	s_nop 0
	global_load_lds_dwordx4 v[218:219], off
	v_lshl_add_u64 v[218:219], v[222:223], 0, s[18:19]
	s_mov_b32 m0, s60
	s_nop 0
	global_load_lds_dwordx4 v[218:219], off
	v_lshl_add_u64 v[218:219], v[224:225], 0, s[18:19]
	s_mov_b32 m0, s61
	s_nop 0
	global_load_lds_dwordx4 v[218:219], off
	s_waitcnt vmcnt(8)
	s_waitcnt lgkmcnt(0)
	s_waitcnt lgkmcnt(0)
	s_barrier
	v_mfma_f32_16x16x32_bf16 v[78:81], v[50:53], v[162:165], v[78:81]
	v_mfma_f32_16x16x32_bf16 v[74:77], v[66:69], v[162:165], v[74:77]
	v_mfma_f32_16x16x32_bf16 v[62:65], v[50:53], v[186:189], v[62:65]
	v_mfma_f32_16x16x32_bf16 v[58:61], v[66:69], v[186:189], v[58:61]
	v_mfma_f32_16x16x32_bf16 v[30:33], v[50:53], v[194:197], v[30:33]
	v_mfma_f32_16x16x32_bf16 v[26:29], v[66:69], v[194:197], v[26:29]
	v_mfma_f32_16x16x32_bf16 v[14:17], v[50:53], v[202:205], v[14:17]
	v_mfma_f32_16x16x32_bf16 v[10:13], v[66:69], v[202:205], v[10:13]
	v_mfma_f32_16x16x32_bf16 v[78:81], v[54:57], v[166:169], v[78:81]
	v_mfma_f32_16x16x32_bf16 v[74:77], v[70:73], v[166:169], v[74:77]
	v_mfma_f32_16x16x32_bf16 v[62:65], v[54:57], v[190:193], v[62:65]
	v_mfma_f32_16x16x32_bf16 v[58:61], v[70:73], v[190:193], v[58:61]
	v_mfma_f32_16x16x32_bf16 v[30:33], v[54:57], v[198:201], v[30:33]
	v_mfma_f32_16x16x32_bf16 v[26:29], v[70:73], v[198:201], v[26:29]
	v_mfma_f32_16x16x32_bf16 v[14:17], v[54:57], v[214:217], v[14:17]
	v_mfma_f32_16x16x32_bf16 v[10:13], v[70:73], v[214:217], v[10:13]
	v_mfma_f32_16x16x32_bf16 v[34:37], v[114:117], v[162:165], v[34:37]
	v_mfma_f32_16x16x32_bf16 v[70:73], v[126:129], v[166:169], v[34:37]
	v_mfma_f32_16x16x32_bf16 v[34:37], v[138:141], v[162:165], v[38:41]
	v_mfma_f32_16x16x32_bf16 v[66:69], v[150:153], v[166:169], v[34:37]
	v_mfma_f32_16x16x32_bf16 v[34:37], v[114:117], v[186:189], v[42:45]
	v_mfma_f32_16x16x32_bf16 v[54:57], v[126:129], v[190:193], v[34:37]
	v_mfma_f32_16x16x32_bf16 v[34:37], v[138:141], v[186:189], v[46:49]
	v_mfma_f32_16x16x32_bf16 v[22:25], v[114:117], v[194:197], v[22:25]
	v_mfma_f32_16x16x32_bf16 v[18:21], v[138:141], v[194:197], v[18:21]
	v_mfma_f32_16x16x32_bf16 v[6:9], v[114:117], v[202:205], v[6:9]
	v_mfma_f32_16x16x32_bf16 v[2:5], v[138:141], v[202:205], v[2:5]
	v_mfma_f32_16x16x32_bf16 v[50:53], v[150:153], v[190:193], v[34:37]
	v_mfma_f32_16x16x32_bf16 v[22:25], v[126:129], v[198:201], v[22:25]
	v_mfma_f32_16x16x32_bf16 v[18:21], v[150:153], v[198:201], v[18:21]
	v_mfma_f32_16x16x32_bf16 v[6:9], v[126:129], v[214:217], v[6:9]
	v_mfma_f32_16x16x32_bf16 v[2:5], v[150:153], v[214:217], v[2:5]
	s_barrier
	s_add_u32 s38, s38, 0x100
	s_addc_u32 s39, s39, 0
	s_add_u32 s68, s68, 0x100
	s_addc_u32 s69, s69, 0
	s_cmp_lt_i32 s70, s57
	s_mov_b32 s40, s70
	s_cbranch_scc1 .LBB0_4157
	s_andn2_b64 vcc, exec, s[22:23]
	s_cbranch_vccnz .LBB0_4160
